# phase 13 (conv+GLU) rewritten: next four rows' loads in flight while four rows are computed, counted waits; same per-element arithmetic
# speedup vs baseline: 1.1118x; 1.0043x over previous
.LBB0_2490:
	s_cmp_lt_i32 s68, 14
	s_cselect_b64 s[0:1], -1, 0
	s_cmp_gt_i32 s69, 13
	s_cselect_b64 s[2:3], -1, 0
	s_and_b64 s[0:1], s[0:1], s[2:3]
	s_andn2_b64 vcc, exec, s[0:1]
	s_cbranch_vccnz .LBB0_2582
	s_add_u32 s8, s34, 0xd322200
	s_mov_b32 s29, 0
	v_mov_b32_e32 v87, 0
	s_addc_u32 s9, s35, 0
	s_lshl_b64 s[0:1], s[28:29], 9
	v_mov_b32_e32 v35, v87
	v_lshl_add_u64 v[84:85], s[0:1], 0, v[34:35]
	s_mov_b32 s0, s88
	s_mov_b32 s1, s29
	s_lshl_b64 s[6:7], s[0:1], 9
	s_mov_b64 s[0:1], 0x58000
	v_cmp_gt_u64_e32 vcc, s[0:1], v[84:85]
	s_and_saveexec_b64 s[10:11], vcc
	s_cbranch_execz .LBB0_2504
	s_cmpk_lg_i32 s88, 0x100
	s_cbranch_scc1 .Lconv_orig
	v_readlane_b32 s12, v254, 62
	v_readlane_b32 s13, v254, 63
	v_readlane_b32 s24, v255, 0
	v_readlane_b32 s25, v255, 1
	s_add_u32 s36, s34, 0xd322200
	s_addc_u32 s37, s35, 0
	s_add_u32 s38, s34, 0x190e2200
	s_addc_u32 s39, s35, 0
	s_nop 0
	s_add_u32 s14, s12, 0x5800
	s_addc_u32 s15, s13, 0
	s_add_u32 s16, s12, 0xb000
	s_addc_u32 s17, s13, 0
	s_add_u32 s18, s12, 0x10800
	s_addc_u32 s19, s13, 0
	s_add_u32 s20, s12, 0x16000
	s_addc_u32 s21, s13, 0
	s_add_u32 s22, s12, 0x1b800
	s_addc_u32 s23, s13, 0
	s_add_u32 s26, s24, 0x5800
	s_addc_u32 s27, s25, 0
	v_mov_b32_e32 v164, 0x5800
	v_mov_b32_e32 v165, 0
	v_mov_b32_e32 v30, 0x2c00
	v_mov_b32_e32 v31, 0
	v_mov_b32_e32 v152, 0x5d1746
	v_mul_hi_u32 v157, v84, v152
	v_mul_u32_u24_e32 v152, 0x2c0, v157
	v_sub_u32_e32 v32, v84, v152
	v_mul_u32_u24_e32 v152, 0x58000, v157
	v_lshl_add_u32 v152, v32, 4, v152
	v_mov_b32_e32 v153, 0
	v_lshl_add_u64 v[158:159], s[36:37], 0, v[152:153]
	v_mul_u32_u24_e32 v152, 0x2c000, v157
	v_lshl_add_u32 v152, v32, 4, v152
	v_lshl_add_u64 v[162:163], s[38:39], 0, v[152:153]
	v_lshlrev_b32_e32 v33, 5, v32
	v_and_b32_e32 v152, 0x7f, v157
	v_cmp_eq_u32_e64 s[40:41], 0, v152
	v_mov_b32_e32 v152, 0x2c00
	v_lshl_add_u64 v[160:161], v[158:159], 0, v[152:153]
	global_load_dwordx4 v[104:107], v33, s[12:13]
	global_load_dwordx4 v[108:111], v33, s[12:13] offset:16
	global_load_dwordx4 v[112:115], v33, s[14:15]
	global_load_dwordx4 v[116:119], v33, s[14:15] offset:16
	global_load_dwordx4 v[120:123], v33, s[16:17]
	global_load_dwordx4 v[124:127], v33, s[16:17] offset:16
	global_load_dwordx4 v[128:131], v33, s[18:19]
	global_load_dwordx4 v[132:135], v33, s[18:19] offset:16
	global_load_dwordx4 v[136:139], v33, s[20:21]
	global_load_dwordx4 v[140:143], v33, s[20:21] offset:16
	global_load_dwordx4 v[144:147], v33, s[22:23]
	global_load_dwordx4 v[148:151], v33, s[22:23] offset:16
	global_load_dwordx4 v[174:177], v33, s[24:25]
	global_load_dwordx4 v[178:181], v33, s[24:25] offset:16
	global_load_dwordx4 v[182:185], v33, s[26:27]
	global_load_dwordx4 v[186:189], v33, s[26:27] offset:16
	v_mov_b32_e32 v152, 0xffffa800
	v_mov_b32_e32 v153, -1
	v_lshl_add_u64 v[154:155], v[158:159], 0, v[152:153]
	global_load_dwordx4 v[238:241], v[154:155], off
	v_lshl_add_u64 v[154:155], v[154:155], 0, v[152:153]
	global_load_dwordx4 v[246:249], v[154:155], off
	v_lshl_add_u64 v[154:155], v[160:161], 0, v[152:153]
	global_load_dwordx4 v[242:245], v[154:155], off
	v_lshl_add_u64 v[154:155], v[154:155], 0, v[152:153]
	global_load_dwordx4 v[250:253], v[154:155], off
	global_load_dwordx4 v[36:39], v[158:159], off nt
	global_load_dwordx4 v[40:43], v[160:161], off nt
	v_lshl_add_u64 v[158:159], v[158:159], 0, v[164:165]
	v_lshl_add_u64 v[160:161], v[160:161], 0, v[164:165]
	global_load_dwordx4 v[44:47], v[158:159], off nt
	global_load_dwordx4 v[48:51], v[160:161], off nt
	v_lshl_add_u64 v[158:159], v[158:159], 0, v[164:165]
	v_lshl_add_u64 v[160:161], v[160:161], 0, v[164:165]
	global_load_dwordx4 v[52:55], v[158:159], off nt
	global_load_dwordx4 v[56:59], v[160:161], off nt
	v_lshl_add_u64 v[158:159], v[158:159], 0, v[164:165]
	v_lshl_add_u64 v[160:161], v[160:161], 0, v[164:165]
	global_load_dwordx4 v[60:63], v[158:159], off nt
	global_load_dwordx4 v[64:67], v[160:161], off nt
	v_lshl_add_u64 v[158:159], v[158:159], 0, v[164:165]
	v_lshl_add_u64 v[160:161], v[160:161], 0, v[164:165]
	global_load_dwordx4 v[68:71], v[158:159], off nt
	global_load_dwordx4 v[72:75], v[160:161], off nt
	v_lshl_add_u64 v[158:159], v[158:159], 0, v[164:165]
	v_lshl_add_u64 v[160:161], v[160:161], 0, v[164:165]
	global_load_dwordx4 v[76:79], v[158:159], off nt
	global_load_dwordx4 v[80:83], v[160:161], off nt
	v_lshl_add_u64 v[158:159], v[158:159], 0, v[164:165]
	v_lshl_add_u64 v[160:161], v[160:161], 0, v[164:165]
	global_load_dwordx4 v[88:91], v[158:159], off nt
	global_load_dwordx4 v[92:95], v[160:161], off nt
	v_lshl_add_u64 v[158:159], v[158:159], 0, v[164:165]
	v_lshl_add_u64 v[160:161], v[160:161], 0, v[164:165]
	global_load_dwordx4 v[96:99], v[158:159], off nt
	global_load_dwordx4 v[100:103], v[160:161], off nt
	v_lshl_add_u64 v[158:159], v[158:159], 0, v[164:165]
	v_lshl_add_u64 v[160:161], v[160:161], 0, v[164:165]
	s_waitcnt vmcnt(8)
	v_lshlrev_b32_e32 v222, 16, v238
	v_and_b32_e32 v223, 0xffff0000, v238
	v_lshlrev_b32_e32 v224, 16, v239
	v_and_b32_e32 v225, 0xffff0000, v239
	v_lshlrev_b32_e32 v226, 16, v240
	v_and_b32_e32 v227, 0xffff0000, v240
	v_lshlrev_b32_e32 v228, 16, v241
	v_and_b32_e32 v229, 0xffff0000, v241
	v_lshlrev_b32_e32 v206, 16, v246
	v_and_b32_e32 v207, 0xffff0000, v246
	v_lshlrev_b32_e32 v208, 16, v247
	v_and_b32_e32 v209, 0xffff0000, v247
	v_lshlrev_b32_e32 v210, 16, v248
	v_and_b32_e32 v211, 0xffff0000, v248
	v_lshlrev_b32_e32 v212, 16, v249
	v_and_b32_e32 v213, 0xffff0000, v249
	v_lshlrev_b32_e32 v230, 16, v242
	v_and_b32_e32 v231, 0xffff0000, v242
	v_lshlrev_b32_e32 v232, 16, v243
	v_and_b32_e32 v233, 0xffff0000, v243
	v_lshlrev_b32_e32 v234, 16, v244
	v_and_b32_e32 v235, 0xffff0000, v244
	v_lshlrev_b32_e32 v236, 16, v245
	v_and_b32_e32 v237, 0xffff0000, v245
	v_lshlrev_b32_e32 v214, 16, v250
	v_and_b32_e32 v215, 0xffff0000, v250
	v_lshlrev_b32_e32 v216, 16, v251
	v_and_b32_e32 v217, 0xffff0000, v251
	v_lshlrev_b32_e32 v218, 16, v252
	v_and_b32_e32 v219, 0xffff0000, v252
	v_lshlrev_b32_e32 v220, 16, v253
	v_and_b32_e32 v221, 0xffff0000, v253
	v_cndmask_b32_e64 v206, v206, 0, s[40:41]
	v_cndmask_b32_e64 v207, v207, 0, s[40:41]
	v_cndmask_b32_e64 v208, v208, 0, s[40:41]
	v_cndmask_b32_e64 v209, v209, 0, s[40:41]
	v_cndmask_b32_e64 v210, v210, 0, s[40:41]
	v_cndmask_b32_e64 v211, v211, 0, s[40:41]
	v_cndmask_b32_e64 v212, v212, 0, s[40:41]
	v_cndmask_b32_e64 v213, v213, 0, s[40:41]
	v_cndmask_b32_e64 v214, v214, 0, s[40:41]
	v_cndmask_b32_e64 v215, v215, 0, s[40:41]
	v_cndmask_b32_e64 v216, v216, 0, s[40:41]
	v_cndmask_b32_e64 v217, v217, 0, s[40:41]
	v_cndmask_b32_e64 v218, v218, 0, s[40:41]
	v_cndmask_b32_e64 v219, v219, 0, s[40:41]
	v_cndmask_b32_e64 v220, v220, 0, s[40:41]
	v_cndmask_b32_e64 v221, v221, 0, s[40:41]
	v_cndmask_b32_e64 v222, v222, 0, s[40:41]
	v_cndmask_b32_e64 v223, v223, 0, s[40:41]
	v_cndmask_b32_e64 v224, v224, 0, s[40:41]
	v_cndmask_b32_e64 v225, v225, 0, s[40:41]
	v_cndmask_b32_e64 v226, v226, 0, s[40:41]
	v_cndmask_b32_e64 v227, v227, 0, s[40:41]
	v_cndmask_b32_e64 v228, v228, 0, s[40:41]
	v_cndmask_b32_e64 v229, v229, 0, s[40:41]
	v_cndmask_b32_e64 v230, v230, 0, s[40:41]
	v_cndmask_b32_e64 v231, v231, 0, s[40:41]
	v_cndmask_b32_e64 v232, v232, 0, s[40:41]
	v_cndmask_b32_e64 v233, v233, 0, s[40:41]
	v_cndmask_b32_e64 v234, v234, 0, s[40:41]
	v_cndmask_b32_e64 v235, v235, 0, s[40:41]
	v_cndmask_b32_e64 v236, v236, 0, s[40:41]
	v_cndmask_b32_e64 v237, v237, 0, s[40:41]
	v_lshlrev_b32_e32 v190, 16, v36
	v_and_b32_e32 v191, 0xffff0000, v36
	v_lshlrev_b32_e32 v192, 16, v37
	v_and_b32_e32 v193, 0xffff0000, v37
	v_lshlrev_b32_e32 v194, 16, v38
	v_and_b32_e32 v195, 0xffff0000, v38
	v_lshlrev_b32_e32 v196, 16, v39
	v_and_b32_e32 v197, 0xffff0000, v39
	v_lshlrev_b32_e32 v198, 16, v40
	v_and_b32_e32 v199, 0xffff0000, v40
	v_lshlrev_b32_e32 v200, 16, v41
	v_and_b32_e32 v201, 0xffff0000, v41
	v_lshlrev_b32_e32 v202, 16, v42
	v_and_b32_e32 v203, 0xffff0000, v42
	v_lshlrev_b32_e32 v204, 16, v43
	v_and_b32_e32 v205, 0xffff0000, v43
	v_pk_fma_f32 v[2:3], v[104:105], v[206:207], v[174:175]
	v_pk_fma_f32 v[4:5], v[106:107], v[208:209], v[176:177]
	v_pk_fma_f32 v[6:7], v[108:109], v[210:211], v[178:179]
	v_pk_fma_f32 v[8:9], v[110:111], v[212:213], v[180:181]
	v_pk_fma_f32 v[10:11], v[112:113], v[214:215], v[182:183]
	v_pk_fma_f32 v[12:13], v[114:115], v[216:217], v[184:185]
	v_pk_fma_f32 v[14:15], v[116:117], v[218:219], v[186:187]
	v_pk_fma_f32 v[16:17], v[118:119], v[220:221], v[188:189]
	v_pk_fma_f32 v[2:3], v[120:121], v[222:223], v[2:3]
	v_pk_fma_f32 v[4:5], v[122:123], v[224:225], v[4:5]
	v_pk_fma_f32 v[6:7], v[124:125], v[226:227], v[6:7]
	v_pk_fma_f32 v[8:9], v[126:127], v[228:229], v[8:9]
	v_pk_fma_f32 v[10:11], v[128:129], v[230:231], v[10:11]
	v_pk_fma_f32 v[12:13], v[130:131], v[232:233], v[12:13]
	v_pk_fma_f32 v[14:15], v[132:133], v[234:235], v[14:15]
	v_pk_fma_f32 v[16:17], v[134:135], v[236:237], v[16:17]
	v_pk_fma_f32 v[2:3], v[136:137], v[190:191], v[2:3]
	v_pk_fma_f32 v[4:5], v[138:139], v[192:193], v[4:5]
	v_pk_fma_f32 v[6:7], v[140:141], v[194:195], v[6:7]
	v_pk_fma_f32 v[8:9], v[142:143], v[196:197], v[8:9]
	v_pk_fma_f32 v[10:11], v[144:145], v[198:199], v[10:11]
	v_pk_fma_f32 v[12:13], v[146:147], v[200:201], v[12:13]
	v_pk_fma_f32 v[14:15], v[148:149], v[202:203], v[14:15]
	v_pk_fma_f32 v[16:17], v[150:151], v[204:205], v[16:17]
	v_mul_f32_e32 v18, 0xbfb8aa3b, v2
	v_mul_f32_e32 v19, 0xbfb8aa3b, v3
	v_mul_f32_e32 v20, 0xbfb8aa3b, v4
	v_mul_f32_e32 v21, 0xbfb8aa3b, v5
	v_mul_f32_e32 v22, 0xbfb8aa3b, v6
	v_mul_f32_e32 v23, 0xbfb8aa3b, v7
	v_mul_f32_e32 v24, 0xbfb8aa3b, v8
	v_mul_f32_e32 v25, 0xbfb8aa3b, v9
	v_exp_f32_e32 v18, v18
	v_exp_f32_e32 v19, v19
	v_exp_f32_e32 v20, v20
	v_exp_f32_e32 v21, v21
	v_exp_f32_e32 v22, v22
	v_exp_f32_e32 v23, v23
	v_exp_f32_e32 v24, v24
	v_exp_f32_e32 v25, v25
	v_add_f32_e32 v18, 1.0, v18
	v_add_f32_e32 v19, 1.0, v19
	v_add_f32_e32 v20, 1.0, v20
	v_add_f32_e32 v21, 1.0, v21
	v_add_f32_e32 v22, 1.0, v22
	v_add_f32_e32 v23, 1.0, v23
	v_add_f32_e32 v24, 1.0, v24
	v_add_f32_e32 v25, 1.0, v25
	v_rcp_f32_e32 v18, v18
	v_rcp_f32_e32 v19, v19
	v_rcp_f32_e32 v20, v20
	v_rcp_f32_e32 v21, v21
	v_rcp_f32_e32 v22, v22
	v_rcp_f32_e32 v23, v23
	v_rcp_f32_e32 v24, v24
	v_rcp_f32_e32 v25, v25
	v_mul_f32_e32 v18, v2, v18
	v_mul_f32_e32 v19, v3, v19
	v_mul_f32_e32 v20, v4, v20
	v_mul_f32_e32 v21, v5, v21
	v_mul_f32_e32 v22, v6, v22
	v_mul_f32_e32 v23, v7, v23
	v_mul_f32_e32 v24, v8, v24
	v_mul_f32_e32 v25, v9, v25
	v_mul_f32_e32 v18, v10, v18
	v_mul_f32_e32 v19, v11, v19
	v_mul_f32_e32 v20, v12, v20
	v_mul_f32_e32 v21, v13, v21
	v_mul_f32_e32 v22, v14, v22
	v_mul_f32_e32 v23, v15, v23
	v_mul_f32_e32 v24, v16, v24
	v_mul_f32_e32 v25, v17, v25
	v_cvt_pk_bf16_f32 v26, v18, v19
	v_cvt_pk_bf16_f32 v27, v20, v21
	v_cvt_pk_bf16_f32 v28, v22, v23
	v_cvt_pk_bf16_f32 v29, v24, v25
	global_store_dwordx4 v[162:163], v[26:29], off sc1
	v_lshl_add_u64 v[162:163], v[162:163], 0, v[30:31]
	v_lshlrev_b32_e32 v206, 16, v44
	v_and_b32_e32 v207, 0xffff0000, v44
	v_lshlrev_b32_e32 v208, 16, v45
	v_and_b32_e32 v209, 0xffff0000, v45
	v_lshlrev_b32_e32 v210, 16, v46
	v_and_b32_e32 v211, 0xffff0000, v46
	v_lshlrev_b32_e32 v212, 16, v47
	v_and_b32_e32 v213, 0xffff0000, v47
	v_lshlrev_b32_e32 v214, 16, v48
	v_and_b32_e32 v215, 0xffff0000, v48
	v_lshlrev_b32_e32 v216, 16, v49
	v_and_b32_e32 v217, 0xffff0000, v49
	v_lshlrev_b32_e32 v218, 16, v50
	v_and_b32_e32 v219, 0xffff0000, v50
	v_lshlrev_b32_e32 v220, 16, v51
	v_and_b32_e32 v221, 0xffff0000, v51
	v_pk_fma_f32 v[2:3], v[104:105], v[222:223], v[174:175]
	v_pk_fma_f32 v[4:5], v[106:107], v[224:225], v[176:177]
	v_pk_fma_f32 v[6:7], v[108:109], v[226:227], v[178:179]
	v_pk_fma_f32 v[8:9], v[110:111], v[228:229], v[180:181]
	v_pk_fma_f32 v[10:11], v[112:113], v[230:231], v[182:183]
	v_pk_fma_f32 v[12:13], v[114:115], v[232:233], v[184:185]
	v_pk_fma_f32 v[14:15], v[116:117], v[234:235], v[186:187]
	v_pk_fma_f32 v[16:17], v[118:119], v[236:237], v[188:189]
	v_pk_fma_f32 v[2:3], v[120:121], v[190:191], v[2:3]
	v_pk_fma_f32 v[4:5], v[122:123], v[192:193], v[4:5]
	v_pk_fma_f32 v[6:7], v[124:125], v[194:195], v[6:7]
	v_pk_fma_f32 v[8:9], v[126:127], v[196:197], v[8:9]
	v_pk_fma_f32 v[10:11], v[128:129], v[198:199], v[10:11]
	v_pk_fma_f32 v[12:13], v[130:131], v[200:201], v[12:13]
	v_pk_fma_f32 v[14:15], v[132:133], v[202:203], v[14:15]
	v_pk_fma_f32 v[16:17], v[134:135], v[204:205], v[16:17]
	v_pk_fma_f32 v[2:3], v[136:137], v[206:207], v[2:3]
	v_pk_fma_f32 v[4:5], v[138:139], v[208:209], v[4:5]
	v_pk_fma_f32 v[6:7], v[140:141], v[210:211], v[6:7]
	v_pk_fma_f32 v[8:9], v[142:143], v[212:213], v[8:9]
	v_pk_fma_f32 v[10:11], v[144:145], v[214:215], v[10:11]
	v_pk_fma_f32 v[12:13], v[146:147], v[216:217], v[12:13]
	v_pk_fma_f32 v[14:15], v[148:149], v[218:219], v[14:15]
	v_pk_fma_f32 v[16:17], v[150:151], v[220:221], v[16:17]
	v_mul_f32_e32 v18, 0xbfb8aa3b, v2
	v_mul_f32_e32 v19, 0xbfb8aa3b, v3
	v_mul_f32_e32 v20, 0xbfb8aa3b, v4
	v_mul_f32_e32 v21, 0xbfb8aa3b, v5
	v_mul_f32_e32 v22, 0xbfb8aa3b, v6
	v_mul_f32_e32 v23, 0xbfb8aa3b, v7
	v_mul_f32_e32 v24, 0xbfb8aa3b, v8
	v_mul_f32_e32 v25, 0xbfb8aa3b, v9
	v_exp_f32_e32 v18, v18
	v_exp_f32_e32 v19, v19
	v_exp_f32_e32 v20, v20
	v_exp_f32_e32 v21, v21
	v_exp_f32_e32 v22, v22
	v_exp_f32_e32 v23, v23
	v_exp_f32_e32 v24, v24
	v_exp_f32_e32 v25, v25
	v_add_f32_e32 v18, 1.0, v18
	v_add_f32_e32 v19, 1.0, v19
	v_add_f32_e32 v20, 1.0, v20
	v_add_f32_e32 v21, 1.0, v21
	v_add_f32_e32 v22, 1.0, v22
	v_add_f32_e32 v23, 1.0, v23
	v_add_f32_e32 v24, 1.0, v24
	v_add_f32_e32 v25, 1.0, v25
	v_rcp_f32_e32 v18, v18
	v_rcp_f32_e32 v19, v19
	v_rcp_f32_e32 v20, v20
	v_rcp_f32_e32 v21, v21
	v_rcp_f32_e32 v22, v22
	v_rcp_f32_e32 v23, v23
	v_rcp_f32_e32 v24, v24
	v_rcp_f32_e32 v25, v25
	v_mul_f32_e32 v18, v2, v18
	v_mul_f32_e32 v19, v3, v19
	v_mul_f32_e32 v20, v4, v20
	v_mul_f32_e32 v21, v5, v21
	v_mul_f32_e32 v22, v6, v22
	v_mul_f32_e32 v23, v7, v23
	v_mul_f32_e32 v24, v8, v24
	v_mul_f32_e32 v25, v9, v25
	v_mul_f32_e32 v18, v10, v18
	v_mul_f32_e32 v19, v11, v19
	v_mul_f32_e32 v20, v12, v20
	v_mul_f32_e32 v21, v13, v21
	v_mul_f32_e32 v22, v14, v22
	v_mul_f32_e32 v23, v15, v23
	v_mul_f32_e32 v24, v16, v24
	v_mul_f32_e32 v25, v17, v25
	v_cvt_pk_bf16_f32 v26, v18, v19
	v_cvt_pk_bf16_f32 v27, v20, v21
	v_cvt_pk_bf16_f32 v28, v22, v23
	v_cvt_pk_bf16_f32 v29, v24, v25
	global_store_dwordx4 v[162:163], v[26:29], off sc1
	v_lshl_add_u64 v[162:163], v[162:163], 0, v[30:31]
	v_lshlrev_b32_e32 v222, 16, v52
	v_and_b32_e32 v223, 0xffff0000, v52
	v_lshlrev_b32_e32 v224, 16, v53
	v_and_b32_e32 v225, 0xffff0000, v53
	v_lshlrev_b32_e32 v226, 16, v54
	v_and_b32_e32 v227, 0xffff0000, v54
	v_lshlrev_b32_e32 v228, 16, v55
	v_and_b32_e32 v229, 0xffff0000, v55
	v_lshlrev_b32_e32 v230, 16, v56
	v_and_b32_e32 v231, 0xffff0000, v56
	v_lshlrev_b32_e32 v232, 16, v57
	v_and_b32_e32 v233, 0xffff0000, v57
	v_lshlrev_b32_e32 v234, 16, v58
	v_and_b32_e32 v235, 0xffff0000, v58
	v_lshlrev_b32_e32 v236, 16, v59
	v_and_b32_e32 v237, 0xffff0000, v59
	v_pk_fma_f32 v[2:3], v[104:105], v[190:191], v[174:175]
	v_pk_fma_f32 v[4:5], v[106:107], v[192:193], v[176:177]
	v_pk_fma_f32 v[6:7], v[108:109], v[194:195], v[178:179]
	v_pk_fma_f32 v[8:9], v[110:111], v[196:197], v[180:181]
	v_pk_fma_f32 v[10:11], v[112:113], v[198:199], v[182:183]
	v_pk_fma_f32 v[12:13], v[114:115], v[200:201], v[184:185]
	v_pk_fma_f32 v[14:15], v[116:117], v[202:203], v[186:187]
	v_pk_fma_f32 v[16:17], v[118:119], v[204:205], v[188:189]
	v_pk_fma_f32 v[2:3], v[120:121], v[206:207], v[2:3]
	v_pk_fma_f32 v[4:5], v[122:123], v[208:209], v[4:5]
	v_pk_fma_f32 v[6:7], v[124:125], v[210:211], v[6:7]
	v_pk_fma_f32 v[8:9], v[126:127], v[212:213], v[8:9]
	v_pk_fma_f32 v[10:11], v[128:129], v[214:215], v[10:11]
	v_pk_fma_f32 v[12:13], v[130:131], v[216:217], v[12:13]
	v_pk_fma_f32 v[14:15], v[132:133], v[218:219], v[14:15]
	v_pk_fma_f32 v[16:17], v[134:135], v[220:221], v[16:17]
	v_pk_fma_f32 v[2:3], v[136:137], v[222:223], v[2:3]
	v_pk_fma_f32 v[4:5], v[138:139], v[224:225], v[4:5]
	v_pk_fma_f32 v[6:7], v[140:141], v[226:227], v[6:7]
	v_pk_fma_f32 v[8:9], v[142:143], v[228:229], v[8:9]
	v_pk_fma_f32 v[10:11], v[144:145], v[230:231], v[10:11]
	v_pk_fma_f32 v[12:13], v[146:147], v[232:233], v[12:13]
	v_pk_fma_f32 v[14:15], v[148:149], v[234:235], v[14:15]
	v_pk_fma_f32 v[16:17], v[150:151], v[236:237], v[16:17]
	v_mul_f32_e32 v18, 0xbfb8aa3b, v2
	v_mul_f32_e32 v19, 0xbfb8aa3b, v3
	v_mul_f32_e32 v20, 0xbfb8aa3b, v4
	v_mul_f32_e32 v21, 0xbfb8aa3b, v5
	v_mul_f32_e32 v22, 0xbfb8aa3b, v6
	v_mul_f32_e32 v23, 0xbfb8aa3b, v7
	v_mul_f32_e32 v24, 0xbfb8aa3b, v8
	v_mul_f32_e32 v25, 0xbfb8aa3b, v9
	v_exp_f32_e32 v18, v18
	v_exp_f32_e32 v19, v19
	v_exp_f32_e32 v20, v20
	v_exp_f32_e32 v21, v21
	v_exp_f32_e32 v22, v22
	v_exp_f32_e32 v23, v23
	v_exp_f32_e32 v24, v24
	v_exp_f32_e32 v25, v25
	v_add_f32_e32 v18, 1.0, v18
	v_add_f32_e32 v19, 1.0, v19
	v_add_f32_e32 v20, 1.0, v20
	v_add_f32_e32 v21, 1.0, v21
	v_add_f32_e32 v22, 1.0, v22
	v_add_f32_e32 v23, 1.0, v23
	v_add_f32_e32 v24, 1.0, v24
	v_add_f32_e32 v25, 1.0, v25
	v_rcp_f32_e32 v18, v18
	v_rcp_f32_e32 v19, v19
	v_rcp_f32_e32 v20, v20
	v_rcp_f32_e32 v21, v21
	v_rcp_f32_e32 v22, v22
	v_rcp_f32_e32 v23, v23
	v_rcp_f32_e32 v24, v24
	v_rcp_f32_e32 v25, v25
	v_mul_f32_e32 v18, v2, v18
	v_mul_f32_e32 v19, v3, v19
	v_mul_f32_e32 v20, v4, v20
	v_mul_f32_e32 v21, v5, v21
	v_mul_f32_e32 v22, v6, v22
	v_mul_f32_e32 v23, v7, v23
	v_mul_f32_e32 v24, v8, v24
	v_mul_f32_e32 v25, v9, v25
	v_mul_f32_e32 v18, v10, v18
	v_mul_f32_e32 v19, v11, v19
	v_mul_f32_e32 v20, v12, v20
	v_mul_f32_e32 v21, v13, v21
	v_mul_f32_e32 v22, v14, v22
	v_mul_f32_e32 v23, v15, v23
	v_mul_f32_e32 v24, v16, v24
	v_mul_f32_e32 v25, v17, v25
	v_cvt_pk_bf16_f32 v26, v18, v19
	v_cvt_pk_bf16_f32 v27, v20, v21
	v_cvt_pk_bf16_f32 v28, v22, v23
	v_cvt_pk_bf16_f32 v29, v24, v25
	global_store_dwordx4 v[162:163], v[26:29], off sc1
	v_lshl_add_u64 v[162:163], v[162:163], 0, v[30:31]
	v_lshlrev_b32_e32 v190, 16, v60
	v_and_b32_e32 v191, 0xffff0000, v60
	v_lshlrev_b32_e32 v192, 16, v61
	v_and_b32_e32 v193, 0xffff0000, v61
	v_lshlrev_b32_e32 v194, 16, v62
	v_and_b32_e32 v195, 0xffff0000, v62
	v_lshlrev_b32_e32 v196, 16, v63
	v_and_b32_e32 v197, 0xffff0000, v63
	v_lshlrev_b32_e32 v198, 16, v64
	v_and_b32_e32 v199, 0xffff0000, v64
	v_lshlrev_b32_e32 v200, 16, v65
	v_and_b32_e32 v201, 0xffff0000, v65
	v_lshlrev_b32_e32 v202, 16, v66
	v_and_b32_e32 v203, 0xffff0000, v66
	v_lshlrev_b32_e32 v204, 16, v67
	v_and_b32_e32 v205, 0xffff0000, v67
	v_pk_fma_f32 v[2:3], v[104:105], v[206:207], v[174:175]
	v_pk_fma_f32 v[4:5], v[106:107], v[208:209], v[176:177]
	v_pk_fma_f32 v[6:7], v[108:109], v[210:211], v[178:179]
	v_pk_fma_f32 v[8:9], v[110:111], v[212:213], v[180:181]
	v_pk_fma_f32 v[10:11], v[112:113], v[214:215], v[182:183]
	v_pk_fma_f32 v[12:13], v[114:115], v[216:217], v[184:185]
	v_pk_fma_f32 v[14:15], v[116:117], v[218:219], v[186:187]
	v_pk_fma_f32 v[16:17], v[118:119], v[220:221], v[188:189]
	v_pk_fma_f32 v[2:3], v[120:121], v[222:223], v[2:3]
	v_pk_fma_f32 v[4:5], v[122:123], v[224:225], v[4:5]
	v_pk_fma_f32 v[6:7], v[124:125], v[226:227], v[6:7]
	v_pk_fma_f32 v[8:9], v[126:127], v[228:229], v[8:9]
	v_pk_fma_f32 v[10:11], v[128:129], v[230:231], v[10:11]
	v_pk_fma_f32 v[12:13], v[130:131], v[232:233], v[12:13]
	v_pk_fma_f32 v[14:15], v[132:133], v[234:235], v[14:15]
	v_pk_fma_f32 v[16:17], v[134:135], v[236:237], v[16:17]
	v_pk_fma_f32 v[2:3], v[136:137], v[190:191], v[2:3]
	v_pk_fma_f32 v[4:5], v[138:139], v[192:193], v[4:5]
	v_pk_fma_f32 v[6:7], v[140:141], v[194:195], v[6:7]
	v_pk_fma_f32 v[8:9], v[142:143], v[196:197], v[8:9]
	v_pk_fma_f32 v[10:11], v[144:145], v[198:199], v[10:11]
	v_pk_fma_f32 v[12:13], v[146:147], v[200:201], v[12:13]
	v_pk_fma_f32 v[14:15], v[148:149], v[202:203], v[14:15]
	v_pk_fma_f32 v[16:17], v[150:151], v[204:205], v[16:17]
	v_mul_f32_e32 v18, 0xbfb8aa3b, v2
	v_mul_f32_e32 v19, 0xbfb8aa3b, v3
	v_mul_f32_e32 v20, 0xbfb8aa3b, v4
	v_mul_f32_e32 v21, 0xbfb8aa3b, v5
	v_mul_f32_e32 v22, 0xbfb8aa3b, v6
	v_mul_f32_e32 v23, 0xbfb8aa3b, v7
	v_mul_f32_e32 v24, 0xbfb8aa3b, v8
	v_mul_f32_e32 v25, 0xbfb8aa3b, v9
	v_exp_f32_e32 v18, v18
	v_exp_f32_e32 v19, v19
	v_exp_f32_e32 v20, v20
	v_exp_f32_e32 v21, v21
	v_exp_f32_e32 v22, v22
	v_exp_f32_e32 v23, v23
	v_exp_f32_e32 v24, v24
	v_exp_f32_e32 v25, v25
	v_add_f32_e32 v18, 1.0, v18
	v_add_f32_e32 v19, 1.0, v19
	v_add_f32_e32 v20, 1.0, v20
	v_add_f32_e32 v21, 1.0, v21
	v_add_f32_e32 v22, 1.0, v22
	v_add_f32_e32 v23, 1.0, v23
	v_add_f32_e32 v24, 1.0, v24
	v_add_f32_e32 v25, 1.0, v25
	v_rcp_f32_e32 v18, v18
	v_rcp_f32_e32 v19, v19
	v_rcp_f32_e32 v20, v20
	v_rcp_f32_e32 v21, v21
	v_rcp_f32_e32 v22, v22
	v_rcp_f32_e32 v23, v23
	v_rcp_f32_e32 v24, v24
	v_rcp_f32_e32 v25, v25
	v_mul_f32_e32 v18, v2, v18
	v_mul_f32_e32 v19, v3, v19
	v_mul_f32_e32 v20, v4, v20
	v_mul_f32_e32 v21, v5, v21
	v_mul_f32_e32 v22, v6, v22
	v_mul_f32_e32 v23, v7, v23
	v_mul_f32_e32 v24, v8, v24
	v_mul_f32_e32 v25, v9, v25
	v_mul_f32_e32 v18, v10, v18
	v_mul_f32_e32 v19, v11, v19
	v_mul_f32_e32 v20, v12, v20
	v_mul_f32_e32 v21, v13, v21
	v_mul_f32_e32 v22, v14, v22
	v_mul_f32_e32 v23, v15, v23
	v_mul_f32_e32 v24, v16, v24
	v_mul_f32_e32 v25, v17, v25
	v_cvt_pk_bf16_f32 v26, v18, v19
	v_cvt_pk_bf16_f32 v27, v20, v21
	v_cvt_pk_bf16_f32 v28, v22, v23
	v_cvt_pk_bf16_f32 v29, v24, v25
	global_store_dwordx4 v[162:163], v[26:29], off sc1
	v_lshl_add_u64 v[162:163], v[162:163], 0, v[30:31]
	global_load_dwordx4 v[36:39], v[158:159], off nt
	global_load_dwordx4 v[40:43], v[160:161], off nt
	v_lshl_add_u64 v[158:159], v[158:159], 0, v[164:165]
	v_lshl_add_u64 v[160:161], v[160:161], 0, v[164:165]
	global_load_dwordx4 v[44:47], v[158:159], off nt
	global_load_dwordx4 v[48:51], v[160:161], off nt
	v_lshl_add_u64 v[158:159], v[158:159], 0, v[164:165]
	v_lshl_add_u64 v[160:161], v[160:161], 0, v[164:165]
	global_load_dwordx4 v[52:55], v[158:159], off nt
	global_load_dwordx4 v[56:59], v[160:161], off nt
	v_lshl_add_u64 v[158:159], v[158:159], 0, v[164:165]
	v_lshl_add_u64 v[160:161], v[160:161], 0, v[164:165]
	global_load_dwordx4 v[60:63], v[158:159], off nt
	global_load_dwordx4 v[64:67], v[160:161], off nt
	v_lshl_add_u64 v[158:159], v[158:159], 0, v[164:165]
	v_lshl_add_u64 v[160:161], v[160:161], 0, v[164:165]
	s_waitcnt vmcnt(12)
	v_lshlrev_b32_e32 v206, 16, v68
	v_and_b32_e32 v207, 0xffff0000, v68
	v_lshlrev_b32_e32 v208, 16, v69
	v_and_b32_e32 v209, 0xffff0000, v69
	v_lshlrev_b32_e32 v210, 16, v70
	v_and_b32_e32 v211, 0xffff0000, v70
	v_lshlrev_b32_e32 v212, 16, v71
	v_and_b32_e32 v213, 0xffff0000, v71
	v_lshlrev_b32_e32 v214, 16, v72
	v_and_b32_e32 v215, 0xffff0000, v72
	v_lshlrev_b32_e32 v216, 16, v73
	v_and_b32_e32 v217, 0xffff0000, v73
	v_lshlrev_b32_e32 v218, 16, v74
	v_and_b32_e32 v219, 0xffff0000, v74
	v_lshlrev_b32_e32 v220, 16, v75
	v_and_b32_e32 v221, 0xffff0000, v75
	v_pk_fma_f32 v[2:3], v[104:105], v[222:223], v[174:175]
	v_pk_fma_f32 v[4:5], v[106:107], v[224:225], v[176:177]
	v_pk_fma_f32 v[6:7], v[108:109], v[226:227], v[178:179]
	v_pk_fma_f32 v[8:9], v[110:111], v[228:229], v[180:181]
	v_pk_fma_f32 v[10:11], v[112:113], v[230:231], v[182:183]
	v_pk_fma_f32 v[12:13], v[114:115], v[232:233], v[184:185]
	v_pk_fma_f32 v[14:15], v[116:117], v[234:235], v[186:187]
	v_pk_fma_f32 v[16:17], v[118:119], v[236:237], v[188:189]
	v_pk_fma_f32 v[2:3], v[120:121], v[190:191], v[2:3]
	v_pk_fma_f32 v[4:5], v[122:123], v[192:193], v[4:5]
	v_pk_fma_f32 v[6:7], v[124:125], v[194:195], v[6:7]
	v_pk_fma_f32 v[8:9], v[126:127], v[196:197], v[8:9]
	v_pk_fma_f32 v[10:11], v[128:129], v[198:199], v[10:11]
	v_pk_fma_f32 v[12:13], v[130:131], v[200:201], v[12:13]
	v_pk_fma_f32 v[14:15], v[132:133], v[202:203], v[14:15]
	v_pk_fma_f32 v[16:17], v[134:135], v[204:205], v[16:17]
	v_pk_fma_f32 v[2:3], v[136:137], v[206:207], v[2:3]
	v_pk_fma_f32 v[4:5], v[138:139], v[208:209], v[4:5]
	v_pk_fma_f32 v[6:7], v[140:141], v[210:211], v[6:7]
	v_pk_fma_f32 v[8:9], v[142:143], v[212:213], v[8:9]
	v_pk_fma_f32 v[10:11], v[144:145], v[214:215], v[10:11]
	v_pk_fma_f32 v[12:13], v[146:147], v[216:217], v[12:13]
	v_pk_fma_f32 v[14:15], v[148:149], v[218:219], v[14:15]
	v_pk_fma_f32 v[16:17], v[150:151], v[220:221], v[16:17]
	v_mul_f32_e32 v18, 0xbfb8aa3b, v2
	v_mul_f32_e32 v19, 0xbfb8aa3b, v3
	v_mul_f32_e32 v20, 0xbfb8aa3b, v4
	v_mul_f32_e32 v21, 0xbfb8aa3b, v5
	v_mul_f32_e32 v22, 0xbfb8aa3b, v6
	v_mul_f32_e32 v23, 0xbfb8aa3b, v7
	v_mul_f32_e32 v24, 0xbfb8aa3b, v8
	v_mul_f32_e32 v25, 0xbfb8aa3b, v9
	v_exp_f32_e32 v18, v18
	v_exp_f32_e32 v19, v19
	v_exp_f32_e32 v20, v20
	v_exp_f32_e32 v21, v21
	v_exp_f32_e32 v22, v22
	v_exp_f32_e32 v23, v23
	v_exp_f32_e32 v24, v24
	v_exp_f32_e32 v25, v25
	v_add_f32_e32 v18, 1.0, v18
	v_add_f32_e32 v19, 1.0, v19
	v_add_f32_e32 v20, 1.0, v20
	v_add_f32_e32 v21, 1.0, v21
	v_add_f32_e32 v22, 1.0, v22
	v_add_f32_e32 v23, 1.0, v23
	v_add_f32_e32 v24, 1.0, v24
	v_add_f32_e32 v25, 1.0, v25
	v_rcp_f32_e32 v18, v18
	v_rcp_f32_e32 v19, v19
	v_rcp_f32_e32 v20, v20
	v_rcp_f32_e32 v21, v21
	v_rcp_f32_e32 v22, v22
	v_rcp_f32_e32 v23, v23
	v_rcp_f32_e32 v24, v24
	v_rcp_f32_e32 v25, v25
	v_mul_f32_e32 v18, v2, v18
	v_mul_f32_e32 v19, v3, v19
	v_mul_f32_e32 v20, v4, v20
	v_mul_f32_e32 v21, v5, v21
	v_mul_f32_e32 v22, v6, v22
	v_mul_f32_e32 v23, v7, v23
	v_mul_f32_e32 v24, v8, v24
	v_mul_f32_e32 v25, v9, v25
	v_mul_f32_e32 v18, v10, v18
	v_mul_f32_e32 v19, v11, v19
	v_mul_f32_e32 v20, v12, v20
	v_mul_f32_e32 v21, v13, v21
	v_mul_f32_e32 v22, v14, v22
	v_mul_f32_e32 v23, v15, v23
	v_mul_f32_e32 v24, v16, v24
	v_mul_f32_e32 v25, v17, v25
	v_cvt_pk_bf16_f32 v26, v18, v19
	v_cvt_pk_bf16_f32 v27, v20, v21
	v_cvt_pk_bf16_f32 v28, v22, v23
	v_cvt_pk_bf16_f32 v29, v24, v25
	global_store_dwordx4 v[162:163], v[26:29], off sc1
	v_lshl_add_u64 v[162:163], v[162:163], 0, v[30:31]
	v_lshlrev_b32_e32 v222, 16, v76
	v_and_b32_e32 v223, 0xffff0000, v76
	v_lshlrev_b32_e32 v224, 16, v77
	v_and_b32_e32 v225, 0xffff0000, v77
	v_lshlrev_b32_e32 v226, 16, v78
	v_and_b32_e32 v227, 0xffff0000, v78
	v_lshlrev_b32_e32 v228, 16, v79
	v_and_b32_e32 v229, 0xffff0000, v79
	v_lshlrev_b32_e32 v230, 16, v80
	v_and_b32_e32 v231, 0xffff0000, v80
	v_lshlrev_b32_e32 v232, 16, v81
	v_and_b32_e32 v233, 0xffff0000, v81
	v_lshlrev_b32_e32 v234, 16, v82
	v_and_b32_e32 v235, 0xffff0000, v82
	v_lshlrev_b32_e32 v236, 16, v83
	v_and_b32_e32 v237, 0xffff0000, v83
	v_pk_fma_f32 v[2:3], v[104:105], v[190:191], v[174:175]
	v_pk_fma_f32 v[4:5], v[106:107], v[192:193], v[176:177]
	v_pk_fma_f32 v[6:7], v[108:109], v[194:195], v[178:179]
	v_pk_fma_f32 v[8:9], v[110:111], v[196:197], v[180:181]
	v_pk_fma_f32 v[10:11], v[112:113], v[198:199], v[182:183]
	v_pk_fma_f32 v[12:13], v[114:115], v[200:201], v[184:185]
	v_pk_fma_f32 v[14:15], v[116:117], v[202:203], v[186:187]
	v_pk_fma_f32 v[16:17], v[118:119], v[204:205], v[188:189]
	v_pk_fma_f32 v[2:3], v[120:121], v[206:207], v[2:3]
	v_pk_fma_f32 v[4:5], v[122:123], v[208:209], v[4:5]
	v_pk_fma_f32 v[6:7], v[124:125], v[210:211], v[6:7]
	v_pk_fma_f32 v[8:9], v[126:127], v[212:213], v[8:9]
	v_pk_fma_f32 v[10:11], v[128:129], v[214:215], v[10:11]
	v_pk_fma_f32 v[12:13], v[130:131], v[216:217], v[12:13]
	v_pk_fma_f32 v[14:15], v[132:133], v[218:219], v[14:15]
	v_pk_fma_f32 v[16:17], v[134:135], v[220:221], v[16:17]
	v_pk_fma_f32 v[2:3], v[136:137], v[222:223], v[2:3]
	v_pk_fma_f32 v[4:5], v[138:139], v[224:225], v[4:5]
	v_pk_fma_f32 v[6:7], v[140:141], v[226:227], v[6:7]
	v_pk_fma_f32 v[8:9], v[142:143], v[228:229], v[8:9]
	v_pk_fma_f32 v[10:11], v[144:145], v[230:231], v[10:11]
	v_pk_fma_f32 v[12:13], v[146:147], v[232:233], v[12:13]
	v_pk_fma_f32 v[14:15], v[148:149], v[234:235], v[14:15]
	v_pk_fma_f32 v[16:17], v[150:151], v[236:237], v[16:17]
	v_mul_f32_e32 v18, 0xbfb8aa3b, v2
	v_mul_f32_e32 v19, 0xbfb8aa3b, v3
	v_mul_f32_e32 v20, 0xbfb8aa3b, v4
	v_mul_f32_e32 v21, 0xbfb8aa3b, v5
	v_mul_f32_e32 v22, 0xbfb8aa3b, v6
	v_mul_f32_e32 v23, 0xbfb8aa3b, v7
	v_mul_f32_e32 v24, 0xbfb8aa3b, v8
	v_mul_f32_e32 v25, 0xbfb8aa3b, v9
	v_exp_f32_e32 v18, v18
	v_exp_f32_e32 v19, v19
	v_exp_f32_e32 v20, v20
	v_exp_f32_e32 v21, v21
	v_exp_f32_e32 v22, v22
	v_exp_f32_e32 v23, v23
	v_exp_f32_e32 v24, v24
	v_exp_f32_e32 v25, v25
	v_add_f32_e32 v18, 1.0, v18
	v_add_f32_e32 v19, 1.0, v19
	v_add_f32_e32 v20, 1.0, v20
	v_add_f32_e32 v21, 1.0, v21
	v_add_f32_e32 v22, 1.0, v22
	v_add_f32_e32 v23, 1.0, v23
	v_add_f32_e32 v24, 1.0, v24
	v_add_f32_e32 v25, 1.0, v25
	v_rcp_f32_e32 v18, v18
	v_rcp_f32_e32 v19, v19
	v_rcp_f32_e32 v20, v20
	v_rcp_f32_e32 v21, v21
	v_rcp_f32_e32 v22, v22
	v_rcp_f32_e32 v23, v23
	v_rcp_f32_e32 v24, v24
	v_rcp_f32_e32 v25, v25
	v_mul_f32_e32 v18, v2, v18
	v_mul_f32_e32 v19, v3, v19
	v_mul_f32_e32 v20, v4, v20
	v_mul_f32_e32 v21, v5, v21
	v_mul_f32_e32 v22, v6, v22
	v_mul_f32_e32 v23, v7, v23
	v_mul_f32_e32 v24, v8, v24
	v_mul_f32_e32 v25, v9, v25
	v_mul_f32_e32 v18, v10, v18
	v_mul_f32_e32 v19, v11, v19
	v_mul_f32_e32 v20, v12, v20
	v_mul_f32_e32 v21, v13, v21
	v_mul_f32_e32 v22, v14, v22
	v_mul_f32_e32 v23, v15, v23
	v_mul_f32_e32 v24, v16, v24
	v_mul_f32_e32 v25, v17, v25
	v_cvt_pk_bf16_f32 v26, v18, v19
	v_cvt_pk_bf16_f32 v27, v20, v21
	v_cvt_pk_bf16_f32 v28, v22, v23
	v_cvt_pk_bf16_f32 v29, v24, v25
	global_store_dwordx4 v[162:163], v[26:29], off sc1
	v_lshl_add_u64 v[162:163], v[162:163], 0, v[30:31]
	v_lshlrev_b32_e32 v190, 16, v88
	v_and_b32_e32 v191, 0xffff0000, v88
	v_lshlrev_b32_e32 v192, 16, v89
	v_and_b32_e32 v193, 0xffff0000, v89
	v_lshlrev_b32_e32 v194, 16, v90
	v_and_b32_e32 v195, 0xffff0000, v90
	v_lshlrev_b32_e32 v196, 16, v91
	v_and_b32_e32 v197, 0xffff0000, v91
	v_lshlrev_b32_e32 v198, 16, v92
	v_and_b32_e32 v199, 0xffff0000, v92
	v_lshlrev_b32_e32 v200, 16, v93
	v_and_b32_e32 v201, 0xffff0000, v93
	v_lshlrev_b32_e32 v202, 16, v94
	v_and_b32_e32 v203, 0xffff0000, v94
	v_lshlrev_b32_e32 v204, 16, v95
	v_and_b32_e32 v205, 0xffff0000, v95
	v_pk_fma_f32 v[2:3], v[104:105], v[206:207], v[174:175]
	v_pk_fma_f32 v[4:5], v[106:107], v[208:209], v[176:177]
	v_pk_fma_f32 v[6:7], v[108:109], v[210:211], v[178:179]
	v_pk_fma_f32 v[8:9], v[110:111], v[212:213], v[180:181]
	v_pk_fma_f32 v[10:11], v[112:113], v[214:215], v[182:183]
	v_pk_fma_f32 v[12:13], v[114:115], v[216:217], v[184:185]
	v_pk_fma_f32 v[14:15], v[116:117], v[218:219], v[186:187]
	v_pk_fma_f32 v[16:17], v[118:119], v[220:221], v[188:189]
	v_pk_fma_f32 v[2:3], v[120:121], v[222:223], v[2:3]
	v_pk_fma_f32 v[4:5], v[122:123], v[224:225], v[4:5]
	v_pk_fma_f32 v[6:7], v[124:125], v[226:227], v[6:7]
	v_pk_fma_f32 v[8:9], v[126:127], v[228:229], v[8:9]
	v_pk_fma_f32 v[10:11], v[128:129], v[230:231], v[10:11]
	v_pk_fma_f32 v[12:13], v[130:131], v[232:233], v[12:13]
	v_pk_fma_f32 v[14:15], v[132:133], v[234:235], v[14:15]
	v_pk_fma_f32 v[16:17], v[134:135], v[236:237], v[16:17]
	v_pk_fma_f32 v[2:3], v[136:137], v[190:191], v[2:3]
	v_pk_fma_f32 v[4:5], v[138:139], v[192:193], v[4:5]
	v_pk_fma_f32 v[6:7], v[140:141], v[194:195], v[6:7]
	v_pk_fma_f32 v[8:9], v[142:143], v[196:197], v[8:9]
	v_pk_fma_f32 v[10:11], v[144:145], v[198:199], v[10:11]
	v_pk_fma_f32 v[12:13], v[146:147], v[200:201], v[12:13]
	v_pk_fma_f32 v[14:15], v[148:149], v[202:203], v[14:15]
	v_pk_fma_f32 v[16:17], v[150:151], v[204:205], v[16:17]
	v_mul_f32_e32 v18, 0xbfb8aa3b, v2
	v_mul_f32_e32 v19, 0xbfb8aa3b, v3
	v_mul_f32_e32 v20, 0xbfb8aa3b, v4
	v_mul_f32_e32 v21, 0xbfb8aa3b, v5
	v_mul_f32_e32 v22, 0xbfb8aa3b, v6
	v_mul_f32_e32 v23, 0xbfb8aa3b, v7
	v_mul_f32_e32 v24, 0xbfb8aa3b, v8
	v_mul_f32_e32 v25, 0xbfb8aa3b, v9
	v_exp_f32_e32 v18, v18
	v_exp_f32_e32 v19, v19
	v_exp_f32_e32 v20, v20
	v_exp_f32_e32 v21, v21
	v_exp_f32_e32 v22, v22
	v_exp_f32_e32 v23, v23
	v_exp_f32_e32 v24, v24
	v_exp_f32_e32 v25, v25
	v_add_f32_e32 v18, 1.0, v18
	v_add_f32_e32 v19, 1.0, v19
	v_add_f32_e32 v20, 1.0, v20
	v_add_f32_e32 v21, 1.0, v21
	v_add_f32_e32 v22, 1.0, v22
	v_add_f32_e32 v23, 1.0, v23
	v_add_f32_e32 v24, 1.0, v24
	v_add_f32_e32 v25, 1.0, v25
	v_rcp_f32_e32 v18, v18
	v_rcp_f32_e32 v19, v19
	v_rcp_f32_e32 v20, v20
	v_rcp_f32_e32 v21, v21
	v_rcp_f32_e32 v22, v22
	v_rcp_f32_e32 v23, v23
	v_rcp_f32_e32 v24, v24
	v_rcp_f32_e32 v25, v25
	v_mul_f32_e32 v18, v2, v18
	v_mul_f32_e32 v19, v3, v19
	v_mul_f32_e32 v20, v4, v20
	v_mul_f32_e32 v21, v5, v21
	v_mul_f32_e32 v22, v6, v22
	v_mul_f32_e32 v23, v7, v23
	v_mul_f32_e32 v24, v8, v24
	v_mul_f32_e32 v25, v9, v25
	v_mul_f32_e32 v18, v10, v18
	v_mul_f32_e32 v19, v11, v19
	v_mul_f32_e32 v20, v12, v20
	v_mul_f32_e32 v21, v13, v21
	v_mul_f32_e32 v22, v14, v22
	v_mul_f32_e32 v23, v15, v23
	v_mul_f32_e32 v24, v16, v24
	v_mul_f32_e32 v25, v17, v25
	v_cvt_pk_bf16_f32 v26, v18, v19
	v_cvt_pk_bf16_f32 v27, v20, v21
	v_cvt_pk_bf16_f32 v28, v22, v23
	v_cvt_pk_bf16_f32 v29, v24, v25
	global_store_dwordx4 v[162:163], v[26:29], off sc1
	v_lshl_add_u64 v[162:163], v[162:163], 0, v[30:31]
	v_lshlrev_b32_e32 v206, 16, v96
	v_and_b32_e32 v207, 0xffff0000, v96
	v_lshlrev_b32_e32 v208, 16, v97
	v_and_b32_e32 v209, 0xffff0000, v97
	v_lshlrev_b32_e32 v210, 16, v98
	v_and_b32_e32 v211, 0xffff0000, v98
	v_lshlrev_b32_e32 v212, 16, v99
	v_and_b32_e32 v213, 0xffff0000, v99
	v_lshlrev_b32_e32 v214, 16, v100
	v_and_b32_e32 v215, 0xffff0000, v100
	v_lshlrev_b32_e32 v216, 16, v101
	v_and_b32_e32 v217, 0xffff0000, v101
	v_lshlrev_b32_e32 v218, 16, v102
	v_and_b32_e32 v219, 0xffff0000, v102
	v_lshlrev_b32_e32 v220, 16, v103
	v_and_b32_e32 v221, 0xffff0000, v103
	v_pk_fma_f32 v[2:3], v[104:105], v[222:223], v[174:175]
	v_pk_fma_f32 v[4:5], v[106:107], v[224:225], v[176:177]
	v_pk_fma_f32 v[6:7], v[108:109], v[226:227], v[178:179]
	v_pk_fma_f32 v[8:9], v[110:111], v[228:229], v[180:181]
	v_pk_fma_f32 v[10:11], v[112:113], v[230:231], v[182:183]
	v_pk_fma_f32 v[12:13], v[114:115], v[232:233], v[184:185]
	v_pk_fma_f32 v[14:15], v[116:117], v[234:235], v[186:187]
	v_pk_fma_f32 v[16:17], v[118:119], v[236:237], v[188:189]
	v_pk_fma_f32 v[2:3], v[120:121], v[190:191], v[2:3]
	v_pk_fma_f32 v[4:5], v[122:123], v[192:193], v[4:5]
	v_pk_fma_f32 v[6:7], v[124:125], v[194:195], v[6:7]
	v_pk_fma_f32 v[8:9], v[126:127], v[196:197], v[8:9]
	v_pk_fma_f32 v[10:11], v[128:129], v[198:199], v[10:11]
	v_pk_fma_f32 v[12:13], v[130:131], v[200:201], v[12:13]
	v_pk_fma_f32 v[14:15], v[132:133], v[202:203], v[14:15]
	v_pk_fma_f32 v[16:17], v[134:135], v[204:205], v[16:17]
	v_pk_fma_f32 v[2:3], v[136:137], v[206:207], v[2:3]
	v_pk_fma_f32 v[4:5], v[138:139], v[208:209], v[4:5]
	v_pk_fma_f32 v[6:7], v[140:141], v[210:211], v[6:7]
	v_pk_fma_f32 v[8:9], v[142:143], v[212:213], v[8:9]
	v_pk_fma_f32 v[10:11], v[144:145], v[214:215], v[10:11]
	v_pk_fma_f32 v[12:13], v[146:147], v[216:217], v[12:13]
	v_pk_fma_f32 v[14:15], v[148:149], v[218:219], v[14:15]
	v_pk_fma_f32 v[16:17], v[150:151], v[220:221], v[16:17]
	v_mul_f32_e32 v18, 0xbfb8aa3b, v2
	v_mul_f32_e32 v19, 0xbfb8aa3b, v3
	v_mul_f32_e32 v20, 0xbfb8aa3b, v4
	v_mul_f32_e32 v21, 0xbfb8aa3b, v5
	v_mul_f32_e32 v22, 0xbfb8aa3b, v6
	v_mul_f32_e32 v23, 0xbfb8aa3b, v7
	v_mul_f32_e32 v24, 0xbfb8aa3b, v8
	v_mul_f32_e32 v25, 0xbfb8aa3b, v9
	v_exp_f32_e32 v18, v18
	v_exp_f32_e32 v19, v19
	v_exp_f32_e32 v20, v20
	v_exp_f32_e32 v21, v21
	v_exp_f32_e32 v22, v22
	v_exp_f32_e32 v23, v23
	v_exp_f32_e32 v24, v24
	v_exp_f32_e32 v25, v25
	v_add_f32_e32 v18, 1.0, v18
	v_add_f32_e32 v19, 1.0, v19
	v_add_f32_e32 v20, 1.0, v20
	v_add_f32_e32 v21, 1.0, v21
	v_add_f32_e32 v22, 1.0, v22
	v_add_f32_e32 v23, 1.0, v23
	v_add_f32_e32 v24, 1.0, v24
	v_add_f32_e32 v25, 1.0, v25
	v_rcp_f32_e32 v18, v18
	v_rcp_f32_e32 v19, v19
	v_rcp_f32_e32 v20, v20
	v_rcp_f32_e32 v21, v21
	v_rcp_f32_e32 v22, v22
	v_rcp_f32_e32 v23, v23
	v_rcp_f32_e32 v24, v24
	v_rcp_f32_e32 v25, v25
	v_mul_f32_e32 v18, v2, v18
	v_mul_f32_e32 v19, v3, v19
	v_mul_f32_e32 v20, v4, v20
	v_mul_f32_e32 v21, v5, v21
	v_mul_f32_e32 v22, v6, v22
	v_mul_f32_e32 v23, v7, v23
	v_mul_f32_e32 v24, v8, v24
	v_mul_f32_e32 v25, v9, v25
	v_mul_f32_e32 v18, v10, v18
	v_mul_f32_e32 v19, v11, v19
	v_mul_f32_e32 v20, v12, v20
	v_mul_f32_e32 v21, v13, v21
	v_mul_f32_e32 v22, v14, v22
	v_mul_f32_e32 v23, v15, v23
	v_mul_f32_e32 v24, v16, v24
	v_mul_f32_e32 v25, v17, v25
	v_cvt_pk_bf16_f32 v26, v18, v19
	v_cvt_pk_bf16_f32 v27, v20, v21
	v_cvt_pk_bf16_f32 v28, v22, v23
	v_cvt_pk_bf16_f32 v29, v24, v25
	global_store_dwordx4 v[162:163], v[26:29], off sc1
	v_lshl_add_u64 v[162:163], v[162:163], 0, v[30:31]
	global_load_dwordx4 v[68:71], v[158:159], off nt
	global_load_dwordx4 v[72:75], v[160:161], off nt
	v_lshl_add_u64 v[158:159], v[158:159], 0, v[164:165]
	v_lshl_add_u64 v[160:161], v[160:161], 0, v[164:165]
	global_load_dwordx4 v[76:79], v[158:159], off nt
	global_load_dwordx4 v[80:83], v[160:161], off nt
	v_lshl_add_u64 v[158:159], v[158:159], 0, v[164:165]
	v_lshl_add_u64 v[160:161], v[160:161], 0, v[164:165]
	global_load_dwordx4 v[88:91], v[158:159], off nt
	global_load_dwordx4 v[92:95], v[160:161], off nt
	v_lshl_add_u64 v[158:159], v[158:159], 0, v[164:165]
	v_lshl_add_u64 v[160:161], v[160:161], 0, v[164:165]
	global_load_dwordx4 v[96:99], v[158:159], off nt
	global_load_dwordx4 v[100:103], v[160:161], off nt
	v_lshl_add_u64 v[158:159], v[158:159], 0, v[164:165]
	v_lshl_add_u64 v[160:161], v[160:161], 0, v[164:165]
	s_waitcnt vmcnt(12)
	v_lshlrev_b32_e32 v222, 16, v36
	v_and_b32_e32 v223, 0xffff0000, v36
	v_lshlrev_b32_e32 v224, 16, v37
	v_and_b32_e32 v225, 0xffff0000, v37
	v_lshlrev_b32_e32 v226, 16, v38
	v_and_b32_e32 v227, 0xffff0000, v38
	v_lshlrev_b32_e32 v228, 16, v39
	v_and_b32_e32 v229, 0xffff0000, v39
	v_lshlrev_b32_e32 v230, 16, v40
	v_and_b32_e32 v231, 0xffff0000, v40
	v_lshlrev_b32_e32 v232, 16, v41
	v_and_b32_e32 v233, 0xffff0000, v41
	v_lshlrev_b32_e32 v234, 16, v42
	v_and_b32_e32 v235, 0xffff0000, v42
	v_lshlrev_b32_e32 v236, 16, v43
	v_and_b32_e32 v237, 0xffff0000, v43
	v_pk_fma_f32 v[2:3], v[104:105], v[190:191], v[174:175]
	v_pk_fma_f32 v[4:5], v[106:107], v[192:193], v[176:177]
	v_pk_fma_f32 v[6:7], v[108:109], v[194:195], v[178:179]
	v_pk_fma_f32 v[8:9], v[110:111], v[196:197], v[180:181]
	v_pk_fma_f32 v[10:11], v[112:113], v[198:199], v[182:183]
	v_pk_fma_f32 v[12:13], v[114:115], v[200:201], v[184:185]
	v_pk_fma_f32 v[14:15], v[116:117], v[202:203], v[186:187]
	v_pk_fma_f32 v[16:17], v[118:119], v[204:205], v[188:189]
	v_pk_fma_f32 v[2:3], v[120:121], v[206:207], v[2:3]
	v_pk_fma_f32 v[4:5], v[122:123], v[208:209], v[4:5]
	v_pk_fma_f32 v[6:7], v[124:125], v[210:211], v[6:7]
	v_pk_fma_f32 v[8:9], v[126:127], v[212:213], v[8:9]
	v_pk_fma_f32 v[10:11], v[128:129], v[214:215], v[10:11]
	v_pk_fma_f32 v[12:13], v[130:131], v[216:217], v[12:13]
	v_pk_fma_f32 v[14:15], v[132:133], v[218:219], v[14:15]
	v_pk_fma_f32 v[16:17], v[134:135], v[220:221], v[16:17]
	v_pk_fma_f32 v[2:3], v[136:137], v[222:223], v[2:3]
	v_pk_fma_f32 v[4:5], v[138:139], v[224:225], v[4:5]
	v_pk_fma_f32 v[6:7], v[140:141], v[226:227], v[6:7]
	v_pk_fma_f32 v[8:9], v[142:143], v[228:229], v[8:9]
	v_pk_fma_f32 v[10:11], v[144:145], v[230:231], v[10:11]
	v_pk_fma_f32 v[12:13], v[146:147], v[232:233], v[12:13]
	v_pk_fma_f32 v[14:15], v[148:149], v[234:235], v[14:15]
	v_pk_fma_f32 v[16:17], v[150:151], v[236:237], v[16:17]
	v_mul_f32_e32 v18, 0xbfb8aa3b, v2
	v_mul_f32_e32 v19, 0xbfb8aa3b, v3
	v_mul_f32_e32 v20, 0xbfb8aa3b, v4
	v_mul_f32_e32 v21, 0xbfb8aa3b, v5
	v_mul_f32_e32 v22, 0xbfb8aa3b, v6
	v_mul_f32_e32 v23, 0xbfb8aa3b, v7
	v_mul_f32_e32 v24, 0xbfb8aa3b, v8
	v_mul_f32_e32 v25, 0xbfb8aa3b, v9
	v_exp_f32_e32 v18, v18
	v_exp_f32_e32 v19, v19
	v_exp_f32_e32 v20, v20
	v_exp_f32_e32 v21, v21
	v_exp_f32_e32 v22, v22
	v_exp_f32_e32 v23, v23
	v_exp_f32_e32 v24, v24
	v_exp_f32_e32 v25, v25
	v_add_f32_e32 v18, 1.0, v18
	v_add_f32_e32 v19, 1.0, v19
	v_add_f32_e32 v20, 1.0, v20
	v_add_f32_e32 v21, 1.0, v21
	v_add_f32_e32 v22, 1.0, v22
	v_add_f32_e32 v23, 1.0, v23
	v_add_f32_e32 v24, 1.0, v24
	v_add_f32_e32 v25, 1.0, v25
	v_rcp_f32_e32 v18, v18
	v_rcp_f32_e32 v19, v19
	v_rcp_f32_e32 v20, v20
	v_rcp_f32_e32 v21, v21
	v_rcp_f32_e32 v22, v22
	v_rcp_f32_e32 v23, v23
	v_rcp_f32_e32 v24, v24
	v_rcp_f32_e32 v25, v25
	v_mul_f32_e32 v18, v2, v18
	v_mul_f32_e32 v19, v3, v19
	v_mul_f32_e32 v20, v4, v20
	v_mul_f32_e32 v21, v5, v21
	v_mul_f32_e32 v22, v6, v22
	v_mul_f32_e32 v23, v7, v23
	v_mul_f32_e32 v24, v8, v24
	v_mul_f32_e32 v25, v9, v25
	v_mul_f32_e32 v18, v10, v18
	v_mul_f32_e32 v19, v11, v19
	v_mul_f32_e32 v20, v12, v20
	v_mul_f32_e32 v21, v13, v21
	v_mul_f32_e32 v22, v14, v22
	v_mul_f32_e32 v23, v15, v23
	v_mul_f32_e32 v24, v16, v24
	v_mul_f32_e32 v25, v17, v25
	v_cvt_pk_bf16_f32 v26, v18, v19
	v_cvt_pk_bf16_f32 v27, v20, v21
	v_cvt_pk_bf16_f32 v28, v22, v23
	v_cvt_pk_bf16_f32 v29, v24, v25
	global_store_dwordx4 v[162:163], v[26:29], off sc1
	v_lshl_add_u64 v[162:163], v[162:163], 0, v[30:31]
	v_lshlrev_b32_e32 v190, 16, v44
	v_and_b32_e32 v191, 0xffff0000, v44
	v_lshlrev_b32_e32 v192, 16, v45
	v_and_b32_e32 v193, 0xffff0000, v45
	v_lshlrev_b32_e32 v194, 16, v46
	v_and_b32_e32 v195, 0xffff0000, v46
	v_lshlrev_b32_e32 v196, 16, v47
	v_and_b32_e32 v197, 0xffff0000, v47
	v_lshlrev_b32_e32 v198, 16, v48
	v_and_b32_e32 v199, 0xffff0000, v48
	v_lshlrev_b32_e32 v200, 16, v49
	v_and_b32_e32 v201, 0xffff0000, v49
	v_lshlrev_b32_e32 v202, 16, v50
	v_and_b32_e32 v203, 0xffff0000, v50
	v_lshlrev_b32_e32 v204, 16, v51
	v_and_b32_e32 v205, 0xffff0000, v51
	v_pk_fma_f32 v[2:3], v[104:105], v[206:207], v[174:175]
	v_pk_fma_f32 v[4:5], v[106:107], v[208:209], v[176:177]
	v_pk_fma_f32 v[6:7], v[108:109], v[210:211], v[178:179]
	v_pk_fma_f32 v[8:9], v[110:111], v[212:213], v[180:181]
	v_pk_fma_f32 v[10:11], v[112:113], v[214:215], v[182:183]
	v_pk_fma_f32 v[12:13], v[114:115], v[216:217], v[184:185]
	v_pk_fma_f32 v[14:15], v[116:117], v[218:219], v[186:187]
	v_pk_fma_f32 v[16:17], v[118:119], v[220:221], v[188:189]
	v_pk_fma_f32 v[2:3], v[120:121], v[222:223], v[2:3]
	v_pk_fma_f32 v[4:5], v[122:123], v[224:225], v[4:5]
	v_pk_fma_f32 v[6:7], v[124:125], v[226:227], v[6:7]
	v_pk_fma_f32 v[8:9], v[126:127], v[228:229], v[8:9]
	v_pk_fma_f32 v[10:11], v[128:129], v[230:231], v[10:11]
	v_pk_fma_f32 v[12:13], v[130:131], v[232:233], v[12:13]
	v_pk_fma_f32 v[14:15], v[132:133], v[234:235], v[14:15]
	v_pk_fma_f32 v[16:17], v[134:135], v[236:237], v[16:17]
	v_pk_fma_f32 v[2:3], v[136:137], v[190:191], v[2:3]
	v_pk_fma_f32 v[4:5], v[138:139], v[192:193], v[4:5]
	v_pk_fma_f32 v[6:7], v[140:141], v[194:195], v[6:7]
	v_pk_fma_f32 v[8:9], v[142:143], v[196:197], v[8:9]
	v_pk_fma_f32 v[10:11], v[144:145], v[198:199], v[10:11]
	v_pk_fma_f32 v[12:13], v[146:147], v[200:201], v[12:13]
	v_pk_fma_f32 v[14:15], v[148:149], v[202:203], v[14:15]
	v_pk_fma_f32 v[16:17], v[150:151], v[204:205], v[16:17]
	v_mul_f32_e32 v18, 0xbfb8aa3b, v2
	v_mul_f32_e32 v19, 0xbfb8aa3b, v3
	v_mul_f32_e32 v20, 0xbfb8aa3b, v4
	v_mul_f32_e32 v21, 0xbfb8aa3b, v5
	v_mul_f32_e32 v22, 0xbfb8aa3b, v6
	v_mul_f32_e32 v23, 0xbfb8aa3b, v7
	v_mul_f32_e32 v24, 0xbfb8aa3b, v8
	v_mul_f32_e32 v25, 0xbfb8aa3b, v9
	v_exp_f32_e32 v18, v18
	v_exp_f32_e32 v19, v19
	v_exp_f32_e32 v20, v20
	v_exp_f32_e32 v21, v21
	v_exp_f32_e32 v22, v22
	v_exp_f32_e32 v23, v23
	v_exp_f32_e32 v24, v24
	v_exp_f32_e32 v25, v25
	v_add_f32_e32 v18, 1.0, v18
	v_add_f32_e32 v19, 1.0, v19
	v_add_f32_e32 v20, 1.0, v20
	v_add_f32_e32 v21, 1.0, v21
	v_add_f32_e32 v22, 1.0, v22
	v_add_f32_e32 v23, 1.0, v23
	v_add_f32_e32 v24, 1.0, v24
	v_add_f32_e32 v25, 1.0, v25
	v_rcp_f32_e32 v18, v18
	v_rcp_f32_e32 v19, v19
	v_rcp_f32_e32 v20, v20
	v_rcp_f32_e32 v21, v21
	v_rcp_f32_e32 v22, v22
	v_rcp_f32_e32 v23, v23
	v_rcp_f32_e32 v24, v24
	v_rcp_f32_e32 v25, v25
	v_mul_f32_e32 v18, v2, v18
	v_mul_f32_e32 v19, v3, v19
	v_mul_f32_e32 v20, v4, v20
	v_mul_f32_e32 v21, v5, v21
	v_mul_f32_e32 v22, v6, v22
	v_mul_f32_e32 v23, v7, v23
	v_mul_f32_e32 v24, v8, v24
	v_mul_f32_e32 v25, v9, v25
	v_mul_f32_e32 v18, v10, v18
	v_mul_f32_e32 v19, v11, v19
	v_mul_f32_e32 v20, v12, v20
	v_mul_f32_e32 v21, v13, v21
	v_mul_f32_e32 v22, v14, v22
	v_mul_f32_e32 v23, v15, v23
	v_mul_f32_e32 v24, v16, v24
	v_mul_f32_e32 v25, v17, v25
	v_cvt_pk_bf16_f32 v26, v18, v19
	v_cvt_pk_bf16_f32 v27, v20, v21
	v_cvt_pk_bf16_f32 v28, v22, v23
	v_cvt_pk_bf16_f32 v29, v24, v25
	global_store_dwordx4 v[162:163], v[26:29], off sc1
	v_lshl_add_u64 v[162:163], v[162:163], 0, v[30:31]
	v_lshlrev_b32_e32 v206, 16, v52
	v_and_b32_e32 v207, 0xffff0000, v52
	v_lshlrev_b32_e32 v208, 16, v53
	v_and_b32_e32 v209, 0xffff0000, v53
	v_lshlrev_b32_e32 v210, 16, v54
	v_and_b32_e32 v211, 0xffff0000, v54
	v_lshlrev_b32_e32 v212, 16, v55
	v_and_b32_e32 v213, 0xffff0000, v55
	v_lshlrev_b32_e32 v214, 16, v56
	v_and_b32_e32 v215, 0xffff0000, v56
	v_lshlrev_b32_e32 v216, 16, v57
	v_and_b32_e32 v217, 0xffff0000, v57
	v_lshlrev_b32_e32 v218, 16, v58
	v_and_b32_e32 v219, 0xffff0000, v58
	v_lshlrev_b32_e32 v220, 16, v59
	v_and_b32_e32 v221, 0xffff0000, v59
	v_pk_fma_f32 v[2:3], v[104:105], v[222:223], v[174:175]
	v_pk_fma_f32 v[4:5], v[106:107], v[224:225], v[176:177]
	v_pk_fma_f32 v[6:7], v[108:109], v[226:227], v[178:179]
	v_pk_fma_f32 v[8:9], v[110:111], v[228:229], v[180:181]
	v_pk_fma_f32 v[10:11], v[112:113], v[230:231], v[182:183]
	v_pk_fma_f32 v[12:13], v[114:115], v[232:233], v[184:185]
	v_pk_fma_f32 v[14:15], v[116:117], v[234:235], v[186:187]
	v_pk_fma_f32 v[16:17], v[118:119], v[236:237], v[188:189]
	v_pk_fma_f32 v[2:3], v[120:121], v[190:191], v[2:3]
	v_pk_fma_f32 v[4:5], v[122:123], v[192:193], v[4:5]
	v_pk_fma_f32 v[6:7], v[124:125], v[194:195], v[6:7]
	v_pk_fma_f32 v[8:9], v[126:127], v[196:197], v[8:9]
	v_pk_fma_f32 v[10:11], v[128:129], v[198:199], v[10:11]
	v_pk_fma_f32 v[12:13], v[130:131], v[200:201], v[12:13]
	v_pk_fma_f32 v[14:15], v[132:133], v[202:203], v[14:15]
	v_pk_fma_f32 v[16:17], v[134:135], v[204:205], v[16:17]
	v_pk_fma_f32 v[2:3], v[136:137], v[206:207], v[2:3]
	v_pk_fma_f32 v[4:5], v[138:139], v[208:209], v[4:5]
	v_pk_fma_f32 v[6:7], v[140:141], v[210:211], v[6:7]
	v_pk_fma_f32 v[8:9], v[142:143], v[212:213], v[8:9]
	v_pk_fma_f32 v[10:11], v[144:145], v[214:215], v[10:11]
	v_pk_fma_f32 v[12:13], v[146:147], v[216:217], v[12:13]
	v_pk_fma_f32 v[14:15], v[148:149], v[218:219], v[14:15]
	v_pk_fma_f32 v[16:17], v[150:151], v[220:221], v[16:17]
	v_mul_f32_e32 v18, 0xbfb8aa3b, v2
	v_mul_f32_e32 v19, 0xbfb8aa3b, v3
	v_mul_f32_e32 v20, 0xbfb8aa3b, v4
	v_mul_f32_e32 v21, 0xbfb8aa3b, v5
	v_mul_f32_e32 v22, 0xbfb8aa3b, v6
	v_mul_f32_e32 v23, 0xbfb8aa3b, v7
	v_mul_f32_e32 v24, 0xbfb8aa3b, v8
	v_mul_f32_e32 v25, 0xbfb8aa3b, v9
	v_exp_f32_e32 v18, v18
	v_exp_f32_e32 v19, v19
	v_exp_f32_e32 v20, v20
	v_exp_f32_e32 v21, v21
	v_exp_f32_e32 v22, v22
	v_exp_f32_e32 v23, v23
	v_exp_f32_e32 v24, v24
	v_exp_f32_e32 v25, v25
	v_add_f32_e32 v18, 1.0, v18
	v_add_f32_e32 v19, 1.0, v19
	v_add_f32_e32 v20, 1.0, v20
	v_add_f32_e32 v21, 1.0, v21
	v_add_f32_e32 v22, 1.0, v22
	v_add_f32_e32 v23, 1.0, v23
	v_add_f32_e32 v24, 1.0, v24
	v_add_f32_e32 v25, 1.0, v25
	v_rcp_f32_e32 v18, v18
	v_rcp_f32_e32 v19, v19
	v_rcp_f32_e32 v20, v20
	v_rcp_f32_e32 v21, v21
	v_rcp_f32_e32 v22, v22
	v_rcp_f32_e32 v23, v23
	v_rcp_f32_e32 v24, v24
	v_rcp_f32_e32 v25, v25
	v_mul_f32_e32 v18, v2, v18
	v_mul_f32_e32 v19, v3, v19
	v_mul_f32_e32 v20, v4, v20
	v_mul_f32_e32 v21, v5, v21
	v_mul_f32_e32 v22, v6, v22
	v_mul_f32_e32 v23, v7, v23
	v_mul_f32_e32 v24, v8, v24
	v_mul_f32_e32 v25, v9, v25
	v_mul_f32_e32 v18, v10, v18
	v_mul_f32_e32 v19, v11, v19
	v_mul_f32_e32 v20, v12, v20
	v_mul_f32_e32 v21, v13, v21
	v_mul_f32_e32 v22, v14, v22
	v_mul_f32_e32 v23, v15, v23
	v_mul_f32_e32 v24, v16, v24
	v_mul_f32_e32 v25, v17, v25
	v_cvt_pk_bf16_f32 v26, v18, v19
	v_cvt_pk_bf16_f32 v27, v20, v21
	v_cvt_pk_bf16_f32 v28, v22, v23
	v_cvt_pk_bf16_f32 v29, v24, v25
	global_store_dwordx4 v[162:163], v[26:29], off sc1
	v_lshl_add_u64 v[162:163], v[162:163], 0, v[30:31]
	v_lshlrev_b32_e32 v222, 16, v60
	v_and_b32_e32 v223, 0xffff0000, v60
	v_lshlrev_b32_e32 v224, 16, v61
	v_and_b32_e32 v225, 0xffff0000, v61
	v_lshlrev_b32_e32 v226, 16, v62
	v_and_b32_e32 v227, 0xffff0000, v62
	v_lshlrev_b32_e32 v228, 16, v63
	v_and_b32_e32 v229, 0xffff0000, v63
	v_lshlrev_b32_e32 v230, 16, v64
	v_and_b32_e32 v231, 0xffff0000, v64
	v_lshlrev_b32_e32 v232, 16, v65
	v_and_b32_e32 v233, 0xffff0000, v65
	v_lshlrev_b32_e32 v234, 16, v66
	v_and_b32_e32 v235, 0xffff0000, v66
	v_lshlrev_b32_e32 v236, 16, v67
	v_and_b32_e32 v237, 0xffff0000, v67
	v_pk_fma_f32 v[2:3], v[104:105], v[190:191], v[174:175]
	v_pk_fma_f32 v[4:5], v[106:107], v[192:193], v[176:177]
	v_pk_fma_f32 v[6:7], v[108:109], v[194:195], v[178:179]
	v_pk_fma_f32 v[8:9], v[110:111], v[196:197], v[180:181]
	v_pk_fma_f32 v[10:11], v[112:113], v[198:199], v[182:183]
	v_pk_fma_f32 v[12:13], v[114:115], v[200:201], v[184:185]
	v_pk_fma_f32 v[14:15], v[116:117], v[202:203], v[186:187]
	v_pk_fma_f32 v[16:17], v[118:119], v[204:205], v[188:189]
	v_pk_fma_f32 v[2:3], v[120:121], v[206:207], v[2:3]
	v_pk_fma_f32 v[4:5], v[122:123], v[208:209], v[4:5]
	v_pk_fma_f32 v[6:7], v[124:125], v[210:211], v[6:7]
	v_pk_fma_f32 v[8:9], v[126:127], v[212:213], v[8:9]
	v_pk_fma_f32 v[10:11], v[128:129], v[214:215], v[10:11]
	v_pk_fma_f32 v[12:13], v[130:131], v[216:217], v[12:13]
	v_pk_fma_f32 v[14:15], v[132:133], v[218:219], v[14:15]
	v_pk_fma_f32 v[16:17], v[134:135], v[220:221], v[16:17]
	v_pk_fma_f32 v[2:3], v[136:137], v[222:223], v[2:3]
	v_pk_fma_f32 v[4:5], v[138:139], v[224:225], v[4:5]
	v_pk_fma_f32 v[6:7], v[140:141], v[226:227], v[6:7]
	v_pk_fma_f32 v[8:9], v[142:143], v[228:229], v[8:9]
	v_pk_fma_f32 v[10:11], v[144:145], v[230:231], v[10:11]
	v_pk_fma_f32 v[12:13], v[146:147], v[232:233], v[12:13]
	v_pk_fma_f32 v[14:15], v[148:149], v[234:235], v[14:15]
	v_pk_fma_f32 v[16:17], v[150:151], v[236:237], v[16:17]
	v_mul_f32_e32 v18, 0xbfb8aa3b, v2
	v_mul_f32_e32 v19, 0xbfb8aa3b, v3
	v_mul_f32_e32 v20, 0xbfb8aa3b, v4
	v_mul_f32_e32 v21, 0xbfb8aa3b, v5
	v_mul_f32_e32 v22, 0xbfb8aa3b, v6
	v_mul_f32_e32 v23, 0xbfb8aa3b, v7
	v_mul_f32_e32 v24, 0xbfb8aa3b, v8
	v_mul_f32_e32 v25, 0xbfb8aa3b, v9
	v_exp_f32_e32 v18, v18
	v_exp_f32_e32 v19, v19
	v_exp_f32_e32 v20, v20
	v_exp_f32_e32 v21, v21
	v_exp_f32_e32 v22, v22
	v_exp_f32_e32 v23, v23
	v_exp_f32_e32 v24, v24
	v_exp_f32_e32 v25, v25
	v_add_f32_e32 v18, 1.0, v18
	v_add_f32_e32 v19, 1.0, v19
	v_add_f32_e32 v20, 1.0, v20
	v_add_f32_e32 v21, 1.0, v21
	v_add_f32_e32 v22, 1.0, v22
	v_add_f32_e32 v23, 1.0, v23
	v_add_f32_e32 v24, 1.0, v24
	v_add_f32_e32 v25, 1.0, v25
	v_rcp_f32_e32 v18, v18
	v_rcp_f32_e32 v19, v19
	v_rcp_f32_e32 v20, v20
	v_rcp_f32_e32 v21, v21
	v_rcp_f32_e32 v22, v22
	v_rcp_f32_e32 v23, v23
	v_rcp_f32_e32 v24, v24
	v_rcp_f32_e32 v25, v25
	v_mul_f32_e32 v18, v2, v18
	v_mul_f32_e32 v19, v3, v19
	v_mul_f32_e32 v20, v4, v20
	v_mul_f32_e32 v21, v5, v21
	v_mul_f32_e32 v22, v6, v22
	v_mul_f32_e32 v23, v7, v23
	v_mul_f32_e32 v24, v8, v24
	v_mul_f32_e32 v25, v9, v25
	v_mul_f32_e32 v18, v10, v18
	v_mul_f32_e32 v19, v11, v19
	v_mul_f32_e32 v20, v12, v20
	v_mul_f32_e32 v21, v13, v21
	v_mul_f32_e32 v22, v14, v22
	v_mul_f32_e32 v23, v15, v23
	v_mul_f32_e32 v24, v16, v24
	v_mul_f32_e32 v25, v17, v25
	v_cvt_pk_bf16_f32 v26, v18, v19
	v_cvt_pk_bf16_f32 v27, v20, v21
	v_cvt_pk_bf16_f32 v28, v22, v23
	v_cvt_pk_bf16_f32 v29, v24, v25
	global_store_dwordx4 v[162:163], v[26:29], off sc1
	v_lshl_add_u64 v[162:163], v[162:163], 0, v[30:31]
	s_waitcnt vmcnt(4)
	v_lshlrev_b32_e32 v190, 16, v68
	v_and_b32_e32 v191, 0xffff0000, v68
	v_lshlrev_b32_e32 v192, 16, v69
	v_and_b32_e32 v193, 0xffff0000, v69
	v_lshlrev_b32_e32 v194, 16, v70
	v_and_b32_e32 v195, 0xffff0000, v70
	v_lshlrev_b32_e32 v196, 16, v71
	v_and_b32_e32 v197, 0xffff0000, v71
	v_lshlrev_b32_e32 v198, 16, v72
	v_and_b32_e32 v199, 0xffff0000, v72
	v_lshlrev_b32_e32 v200, 16, v73
	v_and_b32_e32 v201, 0xffff0000, v73
	v_lshlrev_b32_e32 v202, 16, v74
	v_and_b32_e32 v203, 0xffff0000, v74
	v_lshlrev_b32_e32 v204, 16, v75
	v_and_b32_e32 v205, 0xffff0000, v75
	v_pk_fma_f32 v[2:3], v[104:105], v[206:207], v[174:175]
	v_pk_fma_f32 v[4:5], v[106:107], v[208:209], v[176:177]
	v_pk_fma_f32 v[6:7], v[108:109], v[210:211], v[178:179]
	v_pk_fma_f32 v[8:9], v[110:111], v[212:213], v[180:181]
	v_pk_fma_f32 v[10:11], v[112:113], v[214:215], v[182:183]
	v_pk_fma_f32 v[12:13], v[114:115], v[216:217], v[184:185]
	v_pk_fma_f32 v[14:15], v[116:117], v[218:219], v[186:187]
	v_pk_fma_f32 v[16:17], v[118:119], v[220:221], v[188:189]
	v_pk_fma_f32 v[2:3], v[120:121], v[222:223], v[2:3]
	v_pk_fma_f32 v[4:5], v[122:123], v[224:225], v[4:5]
	v_pk_fma_f32 v[6:7], v[124:125], v[226:227], v[6:7]
	v_pk_fma_f32 v[8:9], v[126:127], v[228:229], v[8:9]
	v_pk_fma_f32 v[10:11], v[128:129], v[230:231], v[10:11]
	v_pk_fma_f32 v[12:13], v[130:131], v[232:233], v[12:13]
	v_pk_fma_f32 v[14:15], v[132:133], v[234:235], v[14:15]
	v_pk_fma_f32 v[16:17], v[134:135], v[236:237], v[16:17]
	v_pk_fma_f32 v[2:3], v[136:137], v[190:191], v[2:3]
	v_pk_fma_f32 v[4:5], v[138:139], v[192:193], v[4:5]
	v_pk_fma_f32 v[6:7], v[140:141], v[194:195], v[6:7]
	v_pk_fma_f32 v[8:9], v[142:143], v[196:197], v[8:9]
	v_pk_fma_f32 v[10:11], v[144:145], v[198:199], v[10:11]
	v_pk_fma_f32 v[12:13], v[146:147], v[200:201], v[12:13]
	v_pk_fma_f32 v[14:15], v[148:149], v[202:203], v[14:15]
	v_pk_fma_f32 v[16:17], v[150:151], v[204:205], v[16:17]
	v_mul_f32_e32 v18, 0xbfb8aa3b, v2
	v_mul_f32_e32 v19, 0xbfb8aa3b, v3
	v_mul_f32_e32 v20, 0xbfb8aa3b, v4
	v_mul_f32_e32 v21, 0xbfb8aa3b, v5
	v_mul_f32_e32 v22, 0xbfb8aa3b, v6
	v_mul_f32_e32 v23, 0xbfb8aa3b, v7
	v_mul_f32_e32 v24, 0xbfb8aa3b, v8
	v_mul_f32_e32 v25, 0xbfb8aa3b, v9
	v_exp_f32_e32 v18, v18
	v_exp_f32_e32 v19, v19
	v_exp_f32_e32 v20, v20
	v_exp_f32_e32 v21, v21
	v_exp_f32_e32 v22, v22
	v_exp_f32_e32 v23, v23
	v_exp_f32_e32 v24, v24
	v_exp_f32_e32 v25, v25
	v_add_f32_e32 v18, 1.0, v18
	v_add_f32_e32 v19, 1.0, v19
	v_add_f32_e32 v20, 1.0, v20
	v_add_f32_e32 v21, 1.0, v21
	v_add_f32_e32 v22, 1.0, v22
	v_add_f32_e32 v23, 1.0, v23
	v_add_f32_e32 v24, 1.0, v24
	v_add_f32_e32 v25, 1.0, v25
	v_rcp_f32_e32 v18, v18
	v_rcp_f32_e32 v19, v19
	v_rcp_f32_e32 v20, v20
	v_rcp_f32_e32 v21, v21
	v_rcp_f32_e32 v22, v22
	v_rcp_f32_e32 v23, v23
	v_rcp_f32_e32 v24, v24
	v_rcp_f32_e32 v25, v25
	v_mul_f32_e32 v18, v2, v18
	v_mul_f32_e32 v19, v3, v19
	v_mul_f32_e32 v20, v4, v20
	v_mul_f32_e32 v21, v5, v21
	v_mul_f32_e32 v22, v6, v22
	v_mul_f32_e32 v23, v7, v23
	v_mul_f32_e32 v24, v8, v24
	v_mul_f32_e32 v25, v9, v25
	v_mul_f32_e32 v18, v10, v18
	v_mul_f32_e32 v19, v11, v19
	v_mul_f32_e32 v20, v12, v20
	v_mul_f32_e32 v21, v13, v21
	v_mul_f32_e32 v22, v14, v22
	v_mul_f32_e32 v23, v15, v23
	v_mul_f32_e32 v24, v16, v24
	v_mul_f32_e32 v25, v17, v25
	v_cvt_pk_bf16_f32 v26, v18, v19
	v_cvt_pk_bf16_f32 v27, v20, v21
	v_cvt_pk_bf16_f32 v28, v22, v23
	v_cvt_pk_bf16_f32 v29, v24, v25
	global_store_dwordx4 v[162:163], v[26:29], off sc1
	v_lshl_add_u64 v[162:163], v[162:163], 0, v[30:31]
	v_lshlrev_b32_e32 v206, 16, v76
	v_and_b32_e32 v207, 0xffff0000, v76
	v_lshlrev_b32_e32 v208, 16, v77
	v_and_b32_e32 v209, 0xffff0000, v77
	v_lshlrev_b32_e32 v210, 16, v78
	v_and_b32_e32 v211, 0xffff0000, v78
	v_lshlrev_b32_e32 v212, 16, v79
	v_and_b32_e32 v213, 0xffff0000, v79
	v_lshlrev_b32_e32 v214, 16, v80
	v_and_b32_e32 v215, 0xffff0000, v80
	v_lshlrev_b32_e32 v216, 16, v81
	v_and_b32_e32 v217, 0xffff0000, v81
	v_lshlrev_b32_e32 v218, 16, v82
	v_and_b32_e32 v219, 0xffff0000, v82
	v_lshlrev_b32_e32 v220, 16, v83
	v_and_b32_e32 v221, 0xffff0000, v83
	v_pk_fma_f32 v[2:3], v[104:105], v[222:223], v[174:175]
	v_pk_fma_f32 v[4:5], v[106:107], v[224:225], v[176:177]
	v_pk_fma_f32 v[6:7], v[108:109], v[226:227], v[178:179]
	v_pk_fma_f32 v[8:9], v[110:111], v[228:229], v[180:181]
	v_pk_fma_f32 v[10:11], v[112:113], v[230:231], v[182:183]
	v_pk_fma_f32 v[12:13], v[114:115], v[232:233], v[184:185]
	v_pk_fma_f32 v[14:15], v[116:117], v[234:235], v[186:187]
	v_pk_fma_f32 v[16:17], v[118:119], v[236:237], v[188:189]
	v_pk_fma_f32 v[2:3], v[120:121], v[190:191], v[2:3]
	v_pk_fma_f32 v[4:5], v[122:123], v[192:193], v[4:5]
	v_pk_fma_f32 v[6:7], v[124:125], v[194:195], v[6:7]
	v_pk_fma_f32 v[8:9], v[126:127], v[196:197], v[8:9]
	v_pk_fma_f32 v[10:11], v[128:129], v[198:199], v[10:11]
	v_pk_fma_f32 v[12:13], v[130:131], v[200:201], v[12:13]
	v_pk_fma_f32 v[14:15], v[132:133], v[202:203], v[14:15]
	v_pk_fma_f32 v[16:17], v[134:135], v[204:205], v[16:17]
	v_pk_fma_f32 v[2:3], v[136:137], v[206:207], v[2:3]
	v_pk_fma_f32 v[4:5], v[138:139], v[208:209], v[4:5]
	v_pk_fma_f32 v[6:7], v[140:141], v[210:211], v[6:7]
	v_pk_fma_f32 v[8:9], v[142:143], v[212:213], v[8:9]
	v_pk_fma_f32 v[10:11], v[144:145], v[214:215], v[10:11]
	v_pk_fma_f32 v[12:13], v[146:147], v[216:217], v[12:13]
	v_pk_fma_f32 v[14:15], v[148:149], v[218:219], v[14:15]
	v_pk_fma_f32 v[16:17], v[150:151], v[220:221], v[16:17]
	v_mul_f32_e32 v18, 0xbfb8aa3b, v2
	v_mul_f32_e32 v19, 0xbfb8aa3b, v3
	v_mul_f32_e32 v20, 0xbfb8aa3b, v4
	v_mul_f32_e32 v21, 0xbfb8aa3b, v5
	v_mul_f32_e32 v22, 0xbfb8aa3b, v6
	v_mul_f32_e32 v23, 0xbfb8aa3b, v7
	v_mul_f32_e32 v24, 0xbfb8aa3b, v8
	v_mul_f32_e32 v25, 0xbfb8aa3b, v9
	v_exp_f32_e32 v18, v18
	v_exp_f32_e32 v19, v19
	v_exp_f32_e32 v20, v20
	v_exp_f32_e32 v21, v21
	v_exp_f32_e32 v22, v22
	v_exp_f32_e32 v23, v23
	v_exp_f32_e32 v24, v24
	v_exp_f32_e32 v25, v25
	v_add_f32_e32 v18, 1.0, v18
	v_add_f32_e32 v19, 1.0, v19
	v_add_f32_e32 v20, 1.0, v20
	v_add_f32_e32 v21, 1.0, v21
	v_add_f32_e32 v22, 1.0, v22
	v_add_f32_e32 v23, 1.0, v23
	v_add_f32_e32 v24, 1.0, v24
	v_add_f32_e32 v25, 1.0, v25
	v_rcp_f32_e32 v18, v18
	v_rcp_f32_e32 v19, v19
	v_rcp_f32_e32 v20, v20
	v_rcp_f32_e32 v21, v21
	v_rcp_f32_e32 v22, v22
	v_rcp_f32_e32 v23, v23
	v_rcp_f32_e32 v24, v24
	v_rcp_f32_e32 v25, v25
	v_mul_f32_e32 v18, v2, v18
	v_mul_f32_e32 v19, v3, v19
	v_mul_f32_e32 v20, v4, v20
	v_mul_f32_e32 v21, v5, v21
	v_mul_f32_e32 v22, v6, v22
	v_mul_f32_e32 v23, v7, v23
	v_mul_f32_e32 v24, v8, v24
	v_mul_f32_e32 v25, v9, v25
	v_mul_f32_e32 v18, v10, v18
	v_mul_f32_e32 v19, v11, v19
	v_mul_f32_e32 v20, v12, v20
	v_mul_f32_e32 v21, v13, v21
	v_mul_f32_e32 v22, v14, v22
	v_mul_f32_e32 v23, v15, v23
	v_mul_f32_e32 v24, v16, v24
	v_mul_f32_e32 v25, v17, v25
	v_cvt_pk_bf16_f32 v26, v18, v19
	v_cvt_pk_bf16_f32 v27, v20, v21
	v_cvt_pk_bf16_f32 v28, v22, v23
	v_cvt_pk_bf16_f32 v29, v24, v25
	global_store_dwordx4 v[162:163], v[26:29], off sc1
	v_lshl_add_u64 v[162:163], v[162:163], 0, v[30:31]
	v_lshlrev_b32_e32 v222, 16, v88
	v_and_b32_e32 v223, 0xffff0000, v88
	v_lshlrev_b32_e32 v224, 16, v89
	v_and_b32_e32 v225, 0xffff0000, v89
	v_lshlrev_b32_e32 v226, 16, v90
	v_and_b32_e32 v227, 0xffff0000, v90
	v_lshlrev_b32_e32 v228, 16, v91
	v_and_b32_e32 v229, 0xffff0000, v91
	v_lshlrev_b32_e32 v230, 16, v92
	v_and_b32_e32 v231, 0xffff0000, v92
	v_lshlrev_b32_e32 v232, 16, v93
	v_and_b32_e32 v233, 0xffff0000, v93
	v_lshlrev_b32_e32 v234, 16, v94
	v_and_b32_e32 v235, 0xffff0000, v94
	v_lshlrev_b32_e32 v236, 16, v95
	v_and_b32_e32 v237, 0xffff0000, v95
	v_pk_fma_f32 v[2:3], v[104:105], v[190:191], v[174:175]
	v_pk_fma_f32 v[4:5], v[106:107], v[192:193], v[176:177]
	v_pk_fma_f32 v[6:7], v[108:109], v[194:195], v[178:179]
	v_pk_fma_f32 v[8:9], v[110:111], v[196:197], v[180:181]
	v_pk_fma_f32 v[10:11], v[112:113], v[198:199], v[182:183]
	v_pk_fma_f32 v[12:13], v[114:115], v[200:201], v[184:185]
	v_pk_fma_f32 v[14:15], v[116:117], v[202:203], v[186:187]
	v_pk_fma_f32 v[16:17], v[118:119], v[204:205], v[188:189]
	v_pk_fma_f32 v[2:3], v[120:121], v[206:207], v[2:3]
	v_pk_fma_f32 v[4:5], v[122:123], v[208:209], v[4:5]
	v_pk_fma_f32 v[6:7], v[124:125], v[210:211], v[6:7]
	v_pk_fma_f32 v[8:9], v[126:127], v[212:213], v[8:9]
	v_pk_fma_f32 v[10:11], v[128:129], v[214:215], v[10:11]
	v_pk_fma_f32 v[12:13], v[130:131], v[216:217], v[12:13]
	v_pk_fma_f32 v[14:15], v[132:133], v[218:219], v[14:15]
	v_pk_fma_f32 v[16:17], v[134:135], v[220:221], v[16:17]
	v_pk_fma_f32 v[2:3], v[136:137], v[222:223], v[2:3]
	v_pk_fma_f32 v[4:5], v[138:139], v[224:225], v[4:5]
	v_pk_fma_f32 v[6:7], v[140:141], v[226:227], v[6:7]
	v_pk_fma_f32 v[8:9], v[142:143], v[228:229], v[8:9]
	v_pk_fma_f32 v[10:11], v[144:145], v[230:231], v[10:11]
	v_pk_fma_f32 v[12:13], v[146:147], v[232:233], v[12:13]
	v_pk_fma_f32 v[14:15], v[148:149], v[234:235], v[14:15]
	v_pk_fma_f32 v[16:17], v[150:151], v[236:237], v[16:17]
	v_mul_f32_e32 v18, 0xbfb8aa3b, v2
	v_mul_f32_e32 v19, 0xbfb8aa3b, v3
	v_mul_f32_e32 v20, 0xbfb8aa3b, v4
	v_mul_f32_e32 v21, 0xbfb8aa3b, v5
	v_mul_f32_e32 v22, 0xbfb8aa3b, v6
	v_mul_f32_e32 v23, 0xbfb8aa3b, v7
	v_mul_f32_e32 v24, 0xbfb8aa3b, v8
	v_mul_f32_e32 v25, 0xbfb8aa3b, v9
	v_exp_f32_e32 v18, v18
	v_exp_f32_e32 v19, v19
	v_exp_f32_e32 v20, v20
	v_exp_f32_e32 v21, v21
	v_exp_f32_e32 v22, v22
	v_exp_f32_e32 v23, v23
	v_exp_f32_e32 v24, v24
	v_exp_f32_e32 v25, v25
	v_add_f32_e32 v18, 1.0, v18
	v_add_f32_e32 v19, 1.0, v19
	v_add_f32_e32 v20, 1.0, v20
	v_add_f32_e32 v21, 1.0, v21
	v_add_f32_e32 v22, 1.0, v22
	v_add_f32_e32 v23, 1.0, v23
	v_add_f32_e32 v24, 1.0, v24
	v_add_f32_e32 v25, 1.0, v25
	v_rcp_f32_e32 v18, v18
	v_rcp_f32_e32 v19, v19
	v_rcp_f32_e32 v20, v20
	v_rcp_f32_e32 v21, v21
	v_rcp_f32_e32 v22, v22
	v_rcp_f32_e32 v23, v23
	v_rcp_f32_e32 v24, v24
	v_rcp_f32_e32 v25, v25
	v_mul_f32_e32 v18, v2, v18
	v_mul_f32_e32 v19, v3, v19
	v_mul_f32_e32 v20, v4, v20
	v_mul_f32_e32 v21, v5, v21
	v_mul_f32_e32 v22, v6, v22
	v_mul_f32_e32 v23, v7, v23
	v_mul_f32_e32 v24, v8, v24
	v_mul_f32_e32 v25, v9, v25
	v_mul_f32_e32 v18, v10, v18
	v_mul_f32_e32 v19, v11, v19
	v_mul_f32_e32 v20, v12, v20
	v_mul_f32_e32 v21, v13, v21
	v_mul_f32_e32 v22, v14, v22
	v_mul_f32_e32 v23, v15, v23
	v_mul_f32_e32 v24, v16, v24
	v_mul_f32_e32 v25, v17, v25
	v_cvt_pk_bf16_f32 v26, v18, v19
	v_cvt_pk_bf16_f32 v27, v20, v21
	v_cvt_pk_bf16_f32 v28, v22, v23
	v_cvt_pk_bf16_f32 v29, v24, v25
	global_store_dwordx4 v[162:163], v[26:29], off sc1
	v_lshl_add_u64 v[162:163], v[162:163], 0, v[30:31]
	v_lshlrev_b32_e32 v190, 16, v96
	v_and_b32_e32 v191, 0xffff0000, v96
	v_lshlrev_b32_e32 v192, 16, v97
	v_and_b32_e32 v193, 0xffff0000, v97
	v_lshlrev_b32_e32 v194, 16, v98
	v_and_b32_e32 v195, 0xffff0000, v98
	v_lshlrev_b32_e32 v196, 16, v99
	v_and_b32_e32 v197, 0xffff0000, v99
	v_lshlrev_b32_e32 v198, 16, v100
	v_and_b32_e32 v199, 0xffff0000, v100
	v_lshlrev_b32_e32 v200, 16, v101
	v_and_b32_e32 v201, 0xffff0000, v101
	v_lshlrev_b32_e32 v202, 16, v102
	v_and_b32_e32 v203, 0xffff0000, v102
	v_lshlrev_b32_e32 v204, 16, v103
	v_and_b32_e32 v205, 0xffff0000, v103
	v_pk_fma_f32 v[2:3], v[104:105], v[206:207], v[174:175]
	v_pk_fma_f32 v[4:5], v[106:107], v[208:209], v[176:177]
	v_pk_fma_f32 v[6:7], v[108:109], v[210:211], v[178:179]
	v_pk_fma_f32 v[8:9], v[110:111], v[212:213], v[180:181]
	v_pk_fma_f32 v[10:11], v[112:113], v[214:215], v[182:183]
	v_pk_fma_f32 v[12:13], v[114:115], v[216:217], v[184:185]
	v_pk_fma_f32 v[14:15], v[116:117], v[218:219], v[186:187]
	v_pk_fma_f32 v[16:17], v[118:119], v[220:221], v[188:189]
	v_pk_fma_f32 v[2:3], v[120:121], v[222:223], v[2:3]
	v_pk_fma_f32 v[4:5], v[122:123], v[224:225], v[4:5]
	v_pk_fma_f32 v[6:7], v[124:125], v[226:227], v[6:7]
	v_pk_fma_f32 v[8:9], v[126:127], v[228:229], v[8:9]
	v_pk_fma_f32 v[10:11], v[128:129], v[230:231], v[10:11]
	v_pk_fma_f32 v[12:13], v[130:131], v[232:233], v[12:13]
	v_pk_fma_f32 v[14:15], v[132:133], v[234:235], v[14:15]
	v_pk_fma_f32 v[16:17], v[134:135], v[236:237], v[16:17]
	v_pk_fma_f32 v[2:3], v[136:137], v[190:191], v[2:3]
	v_pk_fma_f32 v[4:5], v[138:139], v[192:193], v[4:5]
	v_pk_fma_f32 v[6:7], v[140:141], v[194:195], v[6:7]
	v_pk_fma_f32 v[8:9], v[142:143], v[196:197], v[8:9]
	v_pk_fma_f32 v[10:11], v[144:145], v[198:199], v[10:11]
	v_pk_fma_f32 v[12:13], v[146:147], v[200:201], v[12:13]
	v_pk_fma_f32 v[14:15], v[148:149], v[202:203], v[14:15]
	v_pk_fma_f32 v[16:17], v[150:151], v[204:205], v[16:17]
	v_mul_f32_e32 v18, 0xbfb8aa3b, v2
	v_mul_f32_e32 v19, 0xbfb8aa3b, v3
	v_mul_f32_e32 v20, 0xbfb8aa3b, v4
	v_mul_f32_e32 v21, 0xbfb8aa3b, v5
	v_mul_f32_e32 v22, 0xbfb8aa3b, v6
	v_mul_f32_e32 v23, 0xbfb8aa3b, v7
	v_mul_f32_e32 v24, 0xbfb8aa3b, v8
	v_mul_f32_e32 v25, 0xbfb8aa3b, v9
	v_exp_f32_e32 v18, v18
	v_exp_f32_e32 v19, v19
	v_exp_f32_e32 v20, v20
	v_exp_f32_e32 v21, v21
	v_exp_f32_e32 v22, v22
	v_exp_f32_e32 v23, v23
	v_exp_f32_e32 v24, v24
	v_exp_f32_e32 v25, v25
	v_add_f32_e32 v18, 1.0, v18
	v_add_f32_e32 v19, 1.0, v19
	v_add_f32_e32 v20, 1.0, v20
	v_add_f32_e32 v21, 1.0, v21
	v_add_f32_e32 v22, 1.0, v22
	v_add_f32_e32 v23, 1.0, v23
	v_add_f32_e32 v24, 1.0, v24
	v_add_f32_e32 v25, 1.0, v25
	v_rcp_f32_e32 v18, v18
	v_rcp_f32_e32 v19, v19
	v_rcp_f32_e32 v20, v20
	v_rcp_f32_e32 v21, v21
	v_rcp_f32_e32 v22, v22
	v_rcp_f32_e32 v23, v23
	v_rcp_f32_e32 v24, v24
	v_rcp_f32_e32 v25, v25
	v_mul_f32_e32 v18, v2, v18
	v_mul_f32_e32 v19, v3, v19
	v_mul_f32_e32 v20, v4, v20
	v_mul_f32_e32 v21, v5, v21
	v_mul_f32_e32 v22, v6, v22
	v_mul_f32_e32 v23, v7, v23
	v_mul_f32_e32 v24, v8, v24
	v_mul_f32_e32 v25, v9, v25
	v_mul_f32_e32 v18, v10, v18
	v_mul_f32_e32 v19, v11, v19
	v_mul_f32_e32 v20, v12, v20
	v_mul_f32_e32 v21, v13, v21
	v_mul_f32_e32 v22, v14, v22
	v_mul_f32_e32 v23, v15, v23
	v_mul_f32_e32 v24, v16, v24
	v_mul_f32_e32 v25, v17, v25
	v_cvt_pk_bf16_f32 v26, v18, v19
	v_cvt_pk_bf16_f32 v27, v20, v21
	v_cvt_pk_bf16_f32 v28, v22, v23
	v_cvt_pk_bf16_f32 v29, v24, v25
	global_store_dwordx4 v[162:163], v[26:29], off sc1
	v_lshl_add_u64 v[162:163], v[162:163], 0, v[30:31]
	v_add_u32_e32 v32, 0x80, v32
	v_add_u32_e32 v157, 0xba, v157
	v_cmp_lt_u32_e32 vcc, 0x2bf, v32
	v_subrev_u32_e32 v152, 0x2c0, v32
	s_nop 1
	v_cndmask_b32_e32 v32, v32, v152, vcc
	v_addc_co_u32_e32 v157, vcc, 0, v157, vcc
	v_mul_u32_u24_e32 v152, 0x58000, v157
	v_lshl_add_u32 v152, v32, 4, v152
	v_mov_b32_e32 v153, 0
	v_lshl_add_u64 v[158:159], s[36:37], 0, v[152:153]
	v_mul_u32_u24_e32 v152, 0x2c000, v157
	v_lshl_add_u32 v152, v32, 4, v152
	v_lshl_add_u64 v[162:163], s[38:39], 0, v[152:153]
	v_lshlrev_b32_e32 v33, 5, v32
	v_and_b32_e32 v152, 0x7f, v157
	v_cmp_eq_u32_e64 s[40:41], 0, v152
	v_mov_b32_e32 v152, 0x2c00
	v_lshl_add_u64 v[160:161], v[158:159], 0, v[152:153]
	global_load_dwordx4 v[104:107], v33, s[12:13]
	global_load_dwordx4 v[108:111], v33, s[12:13] offset:16
	global_load_dwordx4 v[112:115], v33, s[14:15]
	global_load_dwordx4 v[116:119], v33, s[14:15] offset:16
	global_load_dwordx4 v[120:123], v33, s[16:17]
	global_load_dwordx4 v[124:127], v33, s[16:17] offset:16
	global_load_dwordx4 v[128:131], v33, s[18:19]
	global_load_dwordx4 v[132:135], v33, s[18:19] offset:16
	global_load_dwordx4 v[136:139], v33, s[20:21]
	global_load_dwordx4 v[140:143], v33, s[20:21] offset:16
	global_load_dwordx4 v[144:147], v33, s[22:23]
	global_load_dwordx4 v[148:151], v33, s[22:23] offset:16
	global_load_dwordx4 v[174:177], v33, s[24:25]
	global_load_dwordx4 v[178:181], v33, s[24:25] offset:16
	global_load_dwordx4 v[182:185], v33, s[26:27]
	global_load_dwordx4 v[186:189], v33, s[26:27] offset:16
	v_mov_b32_e32 v152, 0xffffa800
	v_mov_b32_e32 v153, -1
	v_lshl_add_u64 v[154:155], v[158:159], 0, v[152:153]
	global_load_dwordx4 v[238:241], v[154:155], off
	v_lshl_add_u64 v[154:155], v[154:155], 0, v[152:153]
	global_load_dwordx4 v[246:249], v[154:155], off
	v_lshl_add_u64 v[154:155], v[160:161], 0, v[152:153]
	global_load_dwordx4 v[242:245], v[154:155], off
	v_lshl_add_u64 v[154:155], v[154:155], 0, v[152:153]
	global_load_dwordx4 v[250:253], v[154:155], off
	global_load_dwordx4 v[36:39], v[158:159], off nt
	global_load_dwordx4 v[40:43], v[160:161], off nt
	v_lshl_add_u64 v[158:159], v[158:159], 0, v[164:165]
	v_lshl_add_u64 v[160:161], v[160:161], 0, v[164:165]
	global_load_dwordx4 v[44:47], v[158:159], off nt
	global_load_dwordx4 v[48:51], v[160:161], off nt
	v_lshl_add_u64 v[158:159], v[158:159], 0, v[164:165]
	v_lshl_add_u64 v[160:161], v[160:161], 0, v[164:165]
	global_load_dwordx4 v[52:55], v[158:159], off nt
	global_load_dwordx4 v[56:59], v[160:161], off nt
	v_lshl_add_u64 v[158:159], v[158:159], 0, v[164:165]
	v_lshl_add_u64 v[160:161], v[160:161], 0, v[164:165]
	global_load_dwordx4 v[60:63], v[158:159], off nt
	global_load_dwordx4 v[64:67], v[160:161], off nt
	v_lshl_add_u64 v[158:159], v[158:159], 0, v[164:165]
	v_lshl_add_u64 v[160:161], v[160:161], 0, v[164:165]
	global_load_dwordx4 v[68:71], v[158:159], off nt
	global_load_dwordx4 v[72:75], v[160:161], off nt
	v_lshl_add_u64 v[158:159], v[158:159], 0, v[164:165]
	v_lshl_add_u64 v[160:161], v[160:161], 0, v[164:165]
	global_load_dwordx4 v[76:79], v[158:159], off nt
	global_load_dwordx4 v[80:83], v[160:161], off nt
	v_lshl_add_u64 v[158:159], v[158:159], 0, v[164:165]
	v_lshl_add_u64 v[160:161], v[160:161], 0, v[164:165]
	global_load_dwordx4 v[88:91], v[158:159], off nt
	global_load_dwordx4 v[92:95], v[160:161], off nt
	v_lshl_add_u64 v[158:159], v[158:159], 0, v[164:165]
	v_lshl_add_u64 v[160:161], v[160:161], 0, v[164:165]
	global_load_dwordx4 v[96:99], v[158:159], off nt
	global_load_dwordx4 v[100:103], v[160:161], off nt
	v_lshl_add_u64 v[158:159], v[158:159], 0, v[164:165]
	v_lshl_add_u64 v[160:161], v[160:161], 0, v[164:165]
	s_waitcnt vmcnt(8)
	v_lshlrev_b32_e32 v222, 16, v238
	v_and_b32_e32 v223, 0xffff0000, v238
	v_lshlrev_b32_e32 v224, 16, v239
	v_and_b32_e32 v225, 0xffff0000, v239
	v_lshlrev_b32_e32 v226, 16, v240
	v_and_b32_e32 v227, 0xffff0000, v240
	v_lshlrev_b32_e32 v228, 16, v241
	v_and_b32_e32 v229, 0xffff0000, v241
	v_lshlrev_b32_e32 v206, 16, v246
	v_and_b32_e32 v207, 0xffff0000, v246
	v_lshlrev_b32_e32 v208, 16, v247
	v_and_b32_e32 v209, 0xffff0000, v247
	v_lshlrev_b32_e32 v210, 16, v248
	v_and_b32_e32 v211, 0xffff0000, v248
	v_lshlrev_b32_e32 v212, 16, v249
	v_and_b32_e32 v213, 0xffff0000, v249
	v_lshlrev_b32_e32 v230, 16, v242
	v_and_b32_e32 v231, 0xffff0000, v242
	v_lshlrev_b32_e32 v232, 16, v243
	v_and_b32_e32 v233, 0xffff0000, v243
	v_lshlrev_b32_e32 v234, 16, v244
	v_and_b32_e32 v235, 0xffff0000, v244
	v_lshlrev_b32_e32 v236, 16, v245
	v_and_b32_e32 v237, 0xffff0000, v245
	v_lshlrev_b32_e32 v214, 16, v250
	v_and_b32_e32 v215, 0xffff0000, v250
	v_lshlrev_b32_e32 v216, 16, v251
	v_and_b32_e32 v217, 0xffff0000, v251
	v_lshlrev_b32_e32 v218, 16, v252
	v_and_b32_e32 v219, 0xffff0000, v252
	v_lshlrev_b32_e32 v220, 16, v253
	v_and_b32_e32 v221, 0xffff0000, v253
	v_cndmask_b32_e64 v206, v206, 0, s[40:41]
	v_cndmask_b32_e64 v207, v207, 0, s[40:41]
	v_cndmask_b32_e64 v208, v208, 0, s[40:41]
	v_cndmask_b32_e64 v209, v209, 0, s[40:41]
	v_cndmask_b32_e64 v210, v210, 0, s[40:41]
	v_cndmask_b32_e64 v211, v211, 0, s[40:41]
	v_cndmask_b32_e64 v212, v212, 0, s[40:41]
	v_cndmask_b32_e64 v213, v213, 0, s[40:41]
	v_cndmask_b32_e64 v214, v214, 0, s[40:41]
	v_cndmask_b32_e64 v215, v215, 0, s[40:41]
	v_cndmask_b32_e64 v216, v216, 0, s[40:41]
	v_cndmask_b32_e64 v217, v217, 0, s[40:41]
	v_cndmask_b32_e64 v218, v218, 0, s[40:41]
	v_cndmask_b32_e64 v219, v219, 0, s[40:41]
	v_cndmask_b32_e64 v220, v220, 0, s[40:41]
	v_cndmask_b32_e64 v221, v221, 0, s[40:41]
	v_cndmask_b32_e64 v222, v222, 0, s[40:41]
	v_cndmask_b32_e64 v223, v223, 0, s[40:41]
	v_cndmask_b32_e64 v224, v224, 0, s[40:41]
	v_cndmask_b32_e64 v225, v225, 0, s[40:41]
	v_cndmask_b32_e64 v226, v226, 0, s[40:41]
	v_cndmask_b32_e64 v227, v227, 0, s[40:41]
	v_cndmask_b32_e64 v228, v228, 0, s[40:41]
	v_cndmask_b32_e64 v229, v229, 0, s[40:41]
	v_cndmask_b32_e64 v230, v230, 0, s[40:41]
	v_cndmask_b32_e64 v231, v231, 0, s[40:41]
	v_cndmask_b32_e64 v232, v232, 0, s[40:41]
	v_cndmask_b32_e64 v233, v233, 0, s[40:41]
	v_cndmask_b32_e64 v234, v234, 0, s[40:41]
	v_cndmask_b32_e64 v235, v235, 0, s[40:41]
	v_cndmask_b32_e64 v236, v236, 0, s[40:41]
	v_cndmask_b32_e64 v237, v237, 0, s[40:41]
	v_lshlrev_b32_e32 v190, 16, v36
	v_and_b32_e32 v191, 0xffff0000, v36
	v_lshlrev_b32_e32 v192, 16, v37
	v_and_b32_e32 v193, 0xffff0000, v37
	v_lshlrev_b32_e32 v194, 16, v38
	v_and_b32_e32 v195, 0xffff0000, v38
	v_lshlrev_b32_e32 v196, 16, v39
	v_and_b32_e32 v197, 0xffff0000, v39
	v_lshlrev_b32_e32 v198, 16, v40
	v_and_b32_e32 v199, 0xffff0000, v40
	v_lshlrev_b32_e32 v200, 16, v41
	v_and_b32_e32 v201, 0xffff0000, v41
	v_lshlrev_b32_e32 v202, 16, v42
	v_and_b32_e32 v203, 0xffff0000, v42
	v_lshlrev_b32_e32 v204, 16, v43
	v_and_b32_e32 v205, 0xffff0000, v43
	v_pk_fma_f32 v[2:3], v[104:105], v[206:207], v[174:175]
	v_pk_fma_f32 v[4:5], v[106:107], v[208:209], v[176:177]
	v_pk_fma_f32 v[6:7], v[108:109], v[210:211], v[178:179]
	v_pk_fma_f32 v[8:9], v[110:111], v[212:213], v[180:181]
	v_pk_fma_f32 v[10:11], v[112:113], v[214:215], v[182:183]
	v_pk_fma_f32 v[12:13], v[114:115], v[216:217], v[184:185]
	v_pk_fma_f32 v[14:15], v[116:117], v[218:219], v[186:187]
	v_pk_fma_f32 v[16:17], v[118:119], v[220:221], v[188:189]
	v_pk_fma_f32 v[2:3], v[120:121], v[222:223], v[2:3]
	v_pk_fma_f32 v[4:5], v[122:123], v[224:225], v[4:5]
	v_pk_fma_f32 v[6:7], v[124:125], v[226:227], v[6:7]
	v_pk_fma_f32 v[8:9], v[126:127], v[228:229], v[8:9]
	v_pk_fma_f32 v[10:11], v[128:129], v[230:231], v[10:11]
	v_pk_fma_f32 v[12:13], v[130:131], v[232:233], v[12:13]
	v_pk_fma_f32 v[14:15], v[132:133], v[234:235], v[14:15]
	v_pk_fma_f32 v[16:17], v[134:135], v[236:237], v[16:17]
	v_pk_fma_f32 v[2:3], v[136:137], v[190:191], v[2:3]
	v_pk_fma_f32 v[4:5], v[138:139], v[192:193], v[4:5]
	v_pk_fma_f32 v[6:7], v[140:141], v[194:195], v[6:7]
	v_pk_fma_f32 v[8:9], v[142:143], v[196:197], v[8:9]
	v_pk_fma_f32 v[10:11], v[144:145], v[198:199], v[10:11]
	v_pk_fma_f32 v[12:13], v[146:147], v[200:201], v[12:13]
	v_pk_fma_f32 v[14:15], v[148:149], v[202:203], v[14:15]
	v_pk_fma_f32 v[16:17], v[150:151], v[204:205], v[16:17]
	v_mul_f32_e32 v18, 0xbfb8aa3b, v2
	v_mul_f32_e32 v19, 0xbfb8aa3b, v3
	v_mul_f32_e32 v20, 0xbfb8aa3b, v4
	v_mul_f32_e32 v21, 0xbfb8aa3b, v5
	v_mul_f32_e32 v22, 0xbfb8aa3b, v6
	v_mul_f32_e32 v23, 0xbfb8aa3b, v7
	v_mul_f32_e32 v24, 0xbfb8aa3b, v8
	v_mul_f32_e32 v25, 0xbfb8aa3b, v9
	v_exp_f32_e32 v18, v18
	v_exp_f32_e32 v19, v19
	v_exp_f32_e32 v20, v20
	v_exp_f32_e32 v21, v21
	v_exp_f32_e32 v22, v22
	v_exp_f32_e32 v23, v23
	v_exp_f32_e32 v24, v24
	v_exp_f32_e32 v25, v25
	v_add_f32_e32 v18, 1.0, v18
	v_add_f32_e32 v19, 1.0, v19
	v_add_f32_e32 v20, 1.0, v20
	v_add_f32_e32 v21, 1.0, v21
	v_add_f32_e32 v22, 1.0, v22
	v_add_f32_e32 v23, 1.0, v23
	v_add_f32_e32 v24, 1.0, v24
	v_add_f32_e32 v25, 1.0, v25
	v_rcp_f32_e32 v18, v18
	v_rcp_f32_e32 v19, v19
	v_rcp_f32_e32 v20, v20
	v_rcp_f32_e32 v21, v21
	v_rcp_f32_e32 v22, v22
	v_rcp_f32_e32 v23, v23
	v_rcp_f32_e32 v24, v24
	v_rcp_f32_e32 v25, v25
	v_mul_f32_e32 v18, v2, v18
	v_mul_f32_e32 v19, v3, v19
	v_mul_f32_e32 v20, v4, v20
	v_mul_f32_e32 v21, v5, v21
	v_mul_f32_e32 v22, v6, v22
	v_mul_f32_e32 v23, v7, v23
	v_mul_f32_e32 v24, v8, v24
	v_mul_f32_e32 v25, v9, v25
	v_mul_f32_e32 v18, v10, v18
	v_mul_f32_e32 v19, v11, v19
	v_mul_f32_e32 v20, v12, v20
	v_mul_f32_e32 v21, v13, v21
	v_mul_f32_e32 v22, v14, v22
	v_mul_f32_e32 v23, v15, v23
	v_mul_f32_e32 v24, v16, v24
	v_mul_f32_e32 v25, v17, v25
	v_cvt_pk_bf16_f32 v26, v18, v19
	v_cvt_pk_bf16_f32 v27, v20, v21
	v_cvt_pk_bf16_f32 v28, v22, v23
	v_cvt_pk_bf16_f32 v29, v24, v25
	global_store_dwordx4 v[162:163], v[26:29], off sc1
	v_lshl_add_u64 v[162:163], v[162:163], 0, v[30:31]
	v_lshlrev_b32_e32 v206, 16, v44
	v_and_b32_e32 v207, 0xffff0000, v44
	v_lshlrev_b32_e32 v208, 16, v45
	v_and_b32_e32 v209, 0xffff0000, v45
	v_lshlrev_b32_e32 v210, 16, v46
	v_and_b32_e32 v211, 0xffff0000, v46
	v_lshlrev_b32_e32 v212, 16, v47
	v_and_b32_e32 v213, 0xffff0000, v47
	v_lshlrev_b32_e32 v214, 16, v48
	v_and_b32_e32 v215, 0xffff0000, v48
	v_lshlrev_b32_e32 v216, 16, v49
	v_and_b32_e32 v217, 0xffff0000, v49
	v_lshlrev_b32_e32 v218, 16, v50
	v_and_b32_e32 v219, 0xffff0000, v50
	v_lshlrev_b32_e32 v220, 16, v51
	v_and_b32_e32 v221, 0xffff0000, v51
	v_pk_fma_f32 v[2:3], v[104:105], v[222:223], v[174:175]
	v_pk_fma_f32 v[4:5], v[106:107], v[224:225], v[176:177]
	v_pk_fma_f32 v[6:7], v[108:109], v[226:227], v[178:179]
	v_pk_fma_f32 v[8:9], v[110:111], v[228:229], v[180:181]
	v_pk_fma_f32 v[10:11], v[112:113], v[230:231], v[182:183]
	v_pk_fma_f32 v[12:13], v[114:115], v[232:233], v[184:185]
	v_pk_fma_f32 v[14:15], v[116:117], v[234:235], v[186:187]
	v_pk_fma_f32 v[16:17], v[118:119], v[236:237], v[188:189]
	v_pk_fma_f32 v[2:3], v[120:121], v[190:191], v[2:3]
	v_pk_fma_f32 v[4:5], v[122:123], v[192:193], v[4:5]
	v_pk_fma_f32 v[6:7], v[124:125], v[194:195], v[6:7]
	v_pk_fma_f32 v[8:9], v[126:127], v[196:197], v[8:9]
	v_pk_fma_f32 v[10:11], v[128:129], v[198:199], v[10:11]
	v_pk_fma_f32 v[12:13], v[130:131], v[200:201], v[12:13]
	v_pk_fma_f32 v[14:15], v[132:133], v[202:203], v[14:15]
	v_pk_fma_f32 v[16:17], v[134:135], v[204:205], v[16:17]
	v_pk_fma_f32 v[2:3], v[136:137], v[206:207], v[2:3]
	v_pk_fma_f32 v[4:5], v[138:139], v[208:209], v[4:5]
	v_pk_fma_f32 v[6:7], v[140:141], v[210:211], v[6:7]
	v_pk_fma_f32 v[8:9], v[142:143], v[212:213], v[8:9]
	v_pk_fma_f32 v[10:11], v[144:145], v[214:215], v[10:11]
	v_pk_fma_f32 v[12:13], v[146:147], v[216:217], v[12:13]
	v_pk_fma_f32 v[14:15], v[148:149], v[218:219], v[14:15]
	v_pk_fma_f32 v[16:17], v[150:151], v[220:221], v[16:17]
	v_mul_f32_e32 v18, 0xbfb8aa3b, v2
	v_mul_f32_e32 v19, 0xbfb8aa3b, v3
	v_mul_f32_e32 v20, 0xbfb8aa3b, v4
	v_mul_f32_e32 v21, 0xbfb8aa3b, v5
	v_mul_f32_e32 v22, 0xbfb8aa3b, v6
	v_mul_f32_e32 v23, 0xbfb8aa3b, v7
	v_mul_f32_e32 v24, 0xbfb8aa3b, v8
	v_mul_f32_e32 v25, 0xbfb8aa3b, v9
	v_exp_f32_e32 v18, v18
	v_exp_f32_e32 v19, v19
	v_exp_f32_e32 v20, v20
	v_exp_f32_e32 v21, v21
	v_exp_f32_e32 v22, v22
	v_exp_f32_e32 v23, v23
	v_exp_f32_e32 v24, v24
	v_exp_f32_e32 v25, v25
	v_add_f32_e32 v18, 1.0, v18
	v_add_f32_e32 v19, 1.0, v19
	v_add_f32_e32 v20, 1.0, v20
	v_add_f32_e32 v21, 1.0, v21
	v_add_f32_e32 v22, 1.0, v22
	v_add_f32_e32 v23, 1.0, v23
	v_add_f32_e32 v24, 1.0, v24
	v_add_f32_e32 v25, 1.0, v25
	v_rcp_f32_e32 v18, v18
	v_rcp_f32_e32 v19, v19
	v_rcp_f32_e32 v20, v20
	v_rcp_f32_e32 v21, v21
	v_rcp_f32_e32 v22, v22
	v_rcp_f32_e32 v23, v23
	v_rcp_f32_e32 v24, v24
	v_rcp_f32_e32 v25, v25
	v_mul_f32_e32 v18, v2, v18
	v_mul_f32_e32 v19, v3, v19
	v_mul_f32_e32 v20, v4, v20
	v_mul_f32_e32 v21, v5, v21
	v_mul_f32_e32 v22, v6, v22
	v_mul_f32_e32 v23, v7, v23
	v_mul_f32_e32 v24, v8, v24
	v_mul_f32_e32 v25, v9, v25
	v_mul_f32_e32 v18, v10, v18
	v_mul_f32_e32 v19, v11, v19
	v_mul_f32_e32 v20, v12, v20
	v_mul_f32_e32 v21, v13, v21
	v_mul_f32_e32 v22, v14, v22
	v_mul_f32_e32 v23, v15, v23
	v_mul_f32_e32 v24, v16, v24
	v_mul_f32_e32 v25, v17, v25
	v_cvt_pk_bf16_f32 v26, v18, v19
	v_cvt_pk_bf16_f32 v27, v20, v21
	v_cvt_pk_bf16_f32 v28, v22, v23
	v_cvt_pk_bf16_f32 v29, v24, v25
	global_store_dwordx4 v[162:163], v[26:29], off sc1
	v_lshl_add_u64 v[162:163], v[162:163], 0, v[30:31]
	v_lshlrev_b32_e32 v222, 16, v52
	v_and_b32_e32 v223, 0xffff0000, v52
	v_lshlrev_b32_e32 v224, 16, v53
	v_and_b32_e32 v225, 0xffff0000, v53
	v_lshlrev_b32_e32 v226, 16, v54
	v_and_b32_e32 v227, 0xffff0000, v54
	v_lshlrev_b32_e32 v228, 16, v55
	v_and_b32_e32 v229, 0xffff0000, v55
	v_lshlrev_b32_e32 v230, 16, v56
	v_and_b32_e32 v231, 0xffff0000, v56
	v_lshlrev_b32_e32 v232, 16, v57
	v_and_b32_e32 v233, 0xffff0000, v57
	v_lshlrev_b32_e32 v234, 16, v58
	v_and_b32_e32 v235, 0xffff0000, v58
	v_lshlrev_b32_e32 v236, 16, v59
	v_and_b32_e32 v237, 0xffff0000, v59
	v_pk_fma_f32 v[2:3], v[104:105], v[190:191], v[174:175]
	v_pk_fma_f32 v[4:5], v[106:107], v[192:193], v[176:177]
	v_pk_fma_f32 v[6:7], v[108:109], v[194:195], v[178:179]
	v_pk_fma_f32 v[8:9], v[110:111], v[196:197], v[180:181]
	v_pk_fma_f32 v[10:11], v[112:113], v[198:199], v[182:183]
	v_pk_fma_f32 v[12:13], v[114:115], v[200:201], v[184:185]
	v_pk_fma_f32 v[14:15], v[116:117], v[202:203], v[186:187]
	v_pk_fma_f32 v[16:17], v[118:119], v[204:205], v[188:189]
	v_pk_fma_f32 v[2:3], v[120:121], v[206:207], v[2:3]
	v_pk_fma_f32 v[4:5], v[122:123], v[208:209], v[4:5]
	v_pk_fma_f32 v[6:7], v[124:125], v[210:211], v[6:7]
	v_pk_fma_f32 v[8:9], v[126:127], v[212:213], v[8:9]
	v_pk_fma_f32 v[10:11], v[128:129], v[214:215], v[10:11]
	v_pk_fma_f32 v[12:13], v[130:131], v[216:217], v[12:13]
	v_pk_fma_f32 v[14:15], v[132:133], v[218:219], v[14:15]
	v_pk_fma_f32 v[16:17], v[134:135], v[220:221], v[16:17]
	v_pk_fma_f32 v[2:3], v[136:137], v[222:223], v[2:3]
	v_pk_fma_f32 v[4:5], v[138:139], v[224:225], v[4:5]
	v_pk_fma_f32 v[6:7], v[140:141], v[226:227], v[6:7]
	v_pk_fma_f32 v[8:9], v[142:143], v[228:229], v[8:9]
	v_pk_fma_f32 v[10:11], v[144:145], v[230:231], v[10:11]
	v_pk_fma_f32 v[12:13], v[146:147], v[232:233], v[12:13]
	v_pk_fma_f32 v[14:15], v[148:149], v[234:235], v[14:15]
	v_pk_fma_f32 v[16:17], v[150:151], v[236:237], v[16:17]
	v_mul_f32_e32 v18, 0xbfb8aa3b, v2
	v_mul_f32_e32 v19, 0xbfb8aa3b, v3
	v_mul_f32_e32 v20, 0xbfb8aa3b, v4
	v_mul_f32_e32 v21, 0xbfb8aa3b, v5
	v_mul_f32_e32 v22, 0xbfb8aa3b, v6
	v_mul_f32_e32 v23, 0xbfb8aa3b, v7
	v_mul_f32_e32 v24, 0xbfb8aa3b, v8
	v_mul_f32_e32 v25, 0xbfb8aa3b, v9
	v_exp_f32_e32 v18, v18
	v_exp_f32_e32 v19, v19
	v_exp_f32_e32 v20, v20
	v_exp_f32_e32 v21, v21
	v_exp_f32_e32 v22, v22
	v_exp_f32_e32 v23, v23
	v_exp_f32_e32 v24, v24
	v_exp_f32_e32 v25, v25
	v_add_f32_e32 v18, 1.0, v18
	v_add_f32_e32 v19, 1.0, v19
	v_add_f32_e32 v20, 1.0, v20
	v_add_f32_e32 v21, 1.0, v21
	v_add_f32_e32 v22, 1.0, v22
	v_add_f32_e32 v23, 1.0, v23
	v_add_f32_e32 v24, 1.0, v24
	v_add_f32_e32 v25, 1.0, v25
	v_rcp_f32_e32 v18, v18
	v_rcp_f32_e32 v19, v19
	v_rcp_f32_e32 v20, v20
	v_rcp_f32_e32 v21, v21
	v_rcp_f32_e32 v22, v22
	v_rcp_f32_e32 v23, v23
	v_rcp_f32_e32 v24, v24
	v_rcp_f32_e32 v25, v25
	v_mul_f32_e32 v18, v2, v18
	v_mul_f32_e32 v19, v3, v19
	v_mul_f32_e32 v20, v4, v20
	v_mul_f32_e32 v21, v5, v21
	v_mul_f32_e32 v22, v6, v22
	v_mul_f32_e32 v23, v7, v23
	v_mul_f32_e32 v24, v8, v24
	v_mul_f32_e32 v25, v9, v25
	v_mul_f32_e32 v18, v10, v18
	v_mul_f32_e32 v19, v11, v19
	v_mul_f32_e32 v20, v12, v20
	v_mul_f32_e32 v21, v13, v21
	v_mul_f32_e32 v22, v14, v22
	v_mul_f32_e32 v23, v15, v23
	v_mul_f32_e32 v24, v16, v24
	v_mul_f32_e32 v25, v17, v25
	v_cvt_pk_bf16_f32 v26, v18, v19
	v_cvt_pk_bf16_f32 v27, v20, v21
	v_cvt_pk_bf16_f32 v28, v22, v23
	v_cvt_pk_bf16_f32 v29, v24, v25
	global_store_dwordx4 v[162:163], v[26:29], off sc1
	v_lshl_add_u64 v[162:163], v[162:163], 0, v[30:31]
	v_lshlrev_b32_e32 v190, 16, v60
	v_and_b32_e32 v191, 0xffff0000, v60
	v_lshlrev_b32_e32 v192, 16, v61
	v_and_b32_e32 v193, 0xffff0000, v61
	v_lshlrev_b32_e32 v194, 16, v62
	v_and_b32_e32 v195, 0xffff0000, v62
	v_lshlrev_b32_e32 v196, 16, v63
	v_and_b32_e32 v197, 0xffff0000, v63
	v_lshlrev_b32_e32 v198, 16, v64
	v_and_b32_e32 v199, 0xffff0000, v64
	v_lshlrev_b32_e32 v200, 16, v65
	v_and_b32_e32 v201, 0xffff0000, v65
	v_lshlrev_b32_e32 v202, 16, v66
	v_and_b32_e32 v203, 0xffff0000, v66
	v_lshlrev_b32_e32 v204, 16, v67
	v_and_b32_e32 v205, 0xffff0000, v67
	v_pk_fma_f32 v[2:3], v[104:105], v[206:207], v[174:175]
	v_pk_fma_f32 v[4:5], v[106:107], v[208:209], v[176:177]
	v_pk_fma_f32 v[6:7], v[108:109], v[210:211], v[178:179]
	v_pk_fma_f32 v[8:9], v[110:111], v[212:213], v[180:181]
	v_pk_fma_f32 v[10:11], v[112:113], v[214:215], v[182:183]
	v_pk_fma_f32 v[12:13], v[114:115], v[216:217], v[184:185]
	v_pk_fma_f32 v[14:15], v[116:117], v[218:219], v[186:187]
	v_pk_fma_f32 v[16:17], v[118:119], v[220:221], v[188:189]
	v_pk_fma_f32 v[2:3], v[120:121], v[222:223], v[2:3]
	v_pk_fma_f32 v[4:5], v[122:123], v[224:225], v[4:5]
	v_pk_fma_f32 v[6:7], v[124:125], v[226:227], v[6:7]
	v_pk_fma_f32 v[8:9], v[126:127], v[228:229], v[8:9]
	v_pk_fma_f32 v[10:11], v[128:129], v[230:231], v[10:11]
	v_pk_fma_f32 v[12:13], v[130:131], v[232:233], v[12:13]
	v_pk_fma_f32 v[14:15], v[132:133], v[234:235], v[14:15]
	v_pk_fma_f32 v[16:17], v[134:135], v[236:237], v[16:17]
	v_pk_fma_f32 v[2:3], v[136:137], v[190:191], v[2:3]
	v_pk_fma_f32 v[4:5], v[138:139], v[192:193], v[4:5]
	v_pk_fma_f32 v[6:7], v[140:141], v[194:195], v[6:7]
	v_pk_fma_f32 v[8:9], v[142:143], v[196:197], v[8:9]
	v_pk_fma_f32 v[10:11], v[144:145], v[198:199], v[10:11]
	v_pk_fma_f32 v[12:13], v[146:147], v[200:201], v[12:13]
	v_pk_fma_f32 v[14:15], v[148:149], v[202:203], v[14:15]
	v_pk_fma_f32 v[16:17], v[150:151], v[204:205], v[16:17]
	v_mul_f32_e32 v18, 0xbfb8aa3b, v2
	v_mul_f32_e32 v19, 0xbfb8aa3b, v3
	v_mul_f32_e32 v20, 0xbfb8aa3b, v4
	v_mul_f32_e32 v21, 0xbfb8aa3b, v5
	v_mul_f32_e32 v22, 0xbfb8aa3b, v6
	v_mul_f32_e32 v23, 0xbfb8aa3b, v7
	v_mul_f32_e32 v24, 0xbfb8aa3b, v8
	v_mul_f32_e32 v25, 0xbfb8aa3b, v9
	v_exp_f32_e32 v18, v18
	v_exp_f32_e32 v19, v19
	v_exp_f32_e32 v20, v20
	v_exp_f32_e32 v21, v21
	v_exp_f32_e32 v22, v22
	v_exp_f32_e32 v23, v23
	v_exp_f32_e32 v24, v24
	v_exp_f32_e32 v25, v25
	v_add_f32_e32 v18, 1.0, v18
	v_add_f32_e32 v19, 1.0, v19
	v_add_f32_e32 v20, 1.0, v20
	v_add_f32_e32 v21, 1.0, v21
	v_add_f32_e32 v22, 1.0, v22
	v_add_f32_e32 v23, 1.0, v23
	v_add_f32_e32 v24, 1.0, v24
	v_add_f32_e32 v25, 1.0, v25
	v_rcp_f32_e32 v18, v18
	v_rcp_f32_e32 v19, v19
	v_rcp_f32_e32 v20, v20
	v_rcp_f32_e32 v21, v21
	v_rcp_f32_e32 v22, v22
	v_rcp_f32_e32 v23, v23
	v_rcp_f32_e32 v24, v24
	v_rcp_f32_e32 v25, v25
	v_mul_f32_e32 v18, v2, v18
	v_mul_f32_e32 v19, v3, v19
	v_mul_f32_e32 v20, v4, v20
	v_mul_f32_e32 v21, v5, v21
	v_mul_f32_e32 v22, v6, v22
	v_mul_f32_e32 v23, v7, v23
	v_mul_f32_e32 v24, v8, v24
	v_mul_f32_e32 v25, v9, v25
	v_mul_f32_e32 v18, v10, v18
	v_mul_f32_e32 v19, v11, v19
	v_mul_f32_e32 v20, v12, v20
	v_mul_f32_e32 v21, v13, v21
	v_mul_f32_e32 v22, v14, v22
	v_mul_f32_e32 v23, v15, v23
	v_mul_f32_e32 v24, v16, v24
	v_mul_f32_e32 v25, v17, v25
	v_cvt_pk_bf16_f32 v26, v18, v19
	v_cvt_pk_bf16_f32 v27, v20, v21
	v_cvt_pk_bf16_f32 v28, v22, v23
	v_cvt_pk_bf16_f32 v29, v24, v25
	global_store_dwordx4 v[162:163], v[26:29], off sc1
	v_lshl_add_u64 v[162:163], v[162:163], 0, v[30:31]
	global_load_dwordx4 v[36:39], v[158:159], off nt
	global_load_dwordx4 v[40:43], v[160:161], off nt
	v_lshl_add_u64 v[158:159], v[158:159], 0, v[164:165]
	v_lshl_add_u64 v[160:161], v[160:161], 0, v[164:165]
	global_load_dwordx4 v[44:47], v[158:159], off nt
	global_load_dwordx4 v[48:51], v[160:161], off nt
	v_lshl_add_u64 v[158:159], v[158:159], 0, v[164:165]
	v_lshl_add_u64 v[160:161], v[160:161], 0, v[164:165]
	global_load_dwordx4 v[52:55], v[158:159], off nt
	global_load_dwordx4 v[56:59], v[160:161], off nt
	v_lshl_add_u64 v[158:159], v[158:159], 0, v[164:165]
	v_lshl_add_u64 v[160:161], v[160:161], 0, v[164:165]
	global_load_dwordx4 v[60:63], v[158:159], off nt
	global_load_dwordx4 v[64:67], v[160:161], off nt
	v_lshl_add_u64 v[158:159], v[158:159], 0, v[164:165]
	v_lshl_add_u64 v[160:161], v[160:161], 0, v[164:165]
	s_waitcnt vmcnt(12)
	v_lshlrev_b32_e32 v206, 16, v68
	v_and_b32_e32 v207, 0xffff0000, v68
	v_lshlrev_b32_e32 v208, 16, v69
	v_and_b32_e32 v209, 0xffff0000, v69
	v_lshlrev_b32_e32 v210, 16, v70
	v_and_b32_e32 v211, 0xffff0000, v70
	v_lshlrev_b32_e32 v212, 16, v71
	v_and_b32_e32 v213, 0xffff0000, v71
	v_lshlrev_b32_e32 v214, 16, v72
	v_and_b32_e32 v215, 0xffff0000, v72
	v_lshlrev_b32_e32 v216, 16, v73
	v_and_b32_e32 v217, 0xffff0000, v73
	v_lshlrev_b32_e32 v218, 16, v74
	v_and_b32_e32 v219, 0xffff0000, v74
	v_lshlrev_b32_e32 v220, 16, v75
	v_and_b32_e32 v221, 0xffff0000, v75
	v_pk_fma_f32 v[2:3], v[104:105], v[222:223], v[174:175]
	v_pk_fma_f32 v[4:5], v[106:107], v[224:225], v[176:177]
	v_pk_fma_f32 v[6:7], v[108:109], v[226:227], v[178:179]
	v_pk_fma_f32 v[8:9], v[110:111], v[228:229], v[180:181]
	v_pk_fma_f32 v[10:11], v[112:113], v[230:231], v[182:183]
	v_pk_fma_f32 v[12:13], v[114:115], v[232:233], v[184:185]
	v_pk_fma_f32 v[14:15], v[116:117], v[234:235], v[186:187]
	v_pk_fma_f32 v[16:17], v[118:119], v[236:237], v[188:189]
	v_pk_fma_f32 v[2:3], v[120:121], v[190:191], v[2:3]
	v_pk_fma_f32 v[4:5], v[122:123], v[192:193], v[4:5]
	v_pk_fma_f32 v[6:7], v[124:125], v[194:195], v[6:7]
	v_pk_fma_f32 v[8:9], v[126:127], v[196:197], v[8:9]
	v_pk_fma_f32 v[10:11], v[128:129], v[198:199], v[10:11]
	v_pk_fma_f32 v[12:13], v[130:131], v[200:201], v[12:13]
	v_pk_fma_f32 v[14:15], v[132:133], v[202:203], v[14:15]
	v_pk_fma_f32 v[16:17], v[134:135], v[204:205], v[16:17]
	v_pk_fma_f32 v[2:3], v[136:137], v[206:207], v[2:3]
	v_pk_fma_f32 v[4:5], v[138:139], v[208:209], v[4:5]
	v_pk_fma_f32 v[6:7], v[140:141], v[210:211], v[6:7]
	v_pk_fma_f32 v[8:9], v[142:143], v[212:213], v[8:9]
	v_pk_fma_f32 v[10:11], v[144:145], v[214:215], v[10:11]
	v_pk_fma_f32 v[12:13], v[146:147], v[216:217], v[12:13]
	v_pk_fma_f32 v[14:15], v[148:149], v[218:219], v[14:15]
	v_pk_fma_f32 v[16:17], v[150:151], v[220:221], v[16:17]
	v_mul_f32_e32 v18, 0xbfb8aa3b, v2
	v_mul_f32_e32 v19, 0xbfb8aa3b, v3
	v_mul_f32_e32 v20, 0xbfb8aa3b, v4
	v_mul_f32_e32 v21, 0xbfb8aa3b, v5
	v_mul_f32_e32 v22, 0xbfb8aa3b, v6
	v_mul_f32_e32 v23, 0xbfb8aa3b, v7
	v_mul_f32_e32 v24, 0xbfb8aa3b, v8
	v_mul_f32_e32 v25, 0xbfb8aa3b, v9
	v_exp_f32_e32 v18, v18
	v_exp_f32_e32 v19, v19
	v_exp_f32_e32 v20, v20
	v_exp_f32_e32 v21, v21
	v_exp_f32_e32 v22, v22
	v_exp_f32_e32 v23, v23
	v_exp_f32_e32 v24, v24
	v_exp_f32_e32 v25, v25
	v_add_f32_e32 v18, 1.0, v18
	v_add_f32_e32 v19, 1.0, v19
	v_add_f32_e32 v20, 1.0, v20
	v_add_f32_e32 v21, 1.0, v21
	v_add_f32_e32 v22, 1.0, v22
	v_add_f32_e32 v23, 1.0, v23
	v_add_f32_e32 v24, 1.0, v24
	v_add_f32_e32 v25, 1.0, v25
	v_rcp_f32_e32 v18, v18
	v_rcp_f32_e32 v19, v19
	v_rcp_f32_e32 v20, v20
	v_rcp_f32_e32 v21, v21
	v_rcp_f32_e32 v22, v22
	v_rcp_f32_e32 v23, v23
	v_rcp_f32_e32 v24, v24
	v_rcp_f32_e32 v25, v25
	v_mul_f32_e32 v18, v2, v18
	v_mul_f32_e32 v19, v3, v19
	v_mul_f32_e32 v20, v4, v20
	v_mul_f32_e32 v21, v5, v21
	v_mul_f32_e32 v22, v6, v22
	v_mul_f32_e32 v23, v7, v23
	v_mul_f32_e32 v24, v8, v24
	v_mul_f32_e32 v25, v9, v25
	v_mul_f32_e32 v18, v10, v18
	v_mul_f32_e32 v19, v11, v19
	v_mul_f32_e32 v20, v12, v20
	v_mul_f32_e32 v21, v13, v21
	v_mul_f32_e32 v22, v14, v22
	v_mul_f32_e32 v23, v15, v23
	v_mul_f32_e32 v24, v16, v24
	v_mul_f32_e32 v25, v17, v25
	v_cvt_pk_bf16_f32 v26, v18, v19
	v_cvt_pk_bf16_f32 v27, v20, v21
	v_cvt_pk_bf16_f32 v28, v22, v23
	v_cvt_pk_bf16_f32 v29, v24, v25
	global_store_dwordx4 v[162:163], v[26:29], off sc1
	v_lshl_add_u64 v[162:163], v[162:163], 0, v[30:31]
	v_lshlrev_b32_e32 v222, 16, v76
	v_and_b32_e32 v223, 0xffff0000, v76
	v_lshlrev_b32_e32 v224, 16, v77
	v_and_b32_e32 v225, 0xffff0000, v77
	v_lshlrev_b32_e32 v226, 16, v78
	v_and_b32_e32 v227, 0xffff0000, v78
	v_lshlrev_b32_e32 v228, 16, v79
	v_and_b32_e32 v229, 0xffff0000, v79
	v_lshlrev_b32_e32 v230, 16, v80
	v_and_b32_e32 v231, 0xffff0000, v80
	v_lshlrev_b32_e32 v232, 16, v81
	v_and_b32_e32 v233, 0xffff0000, v81
	v_lshlrev_b32_e32 v234, 16, v82
	v_and_b32_e32 v235, 0xffff0000, v82
	v_lshlrev_b32_e32 v236, 16, v83
	v_and_b32_e32 v237, 0xffff0000, v83
	v_pk_fma_f32 v[2:3], v[104:105], v[190:191], v[174:175]
	v_pk_fma_f32 v[4:5], v[106:107], v[192:193], v[176:177]
	v_pk_fma_f32 v[6:7], v[108:109], v[194:195], v[178:179]
	v_pk_fma_f32 v[8:9], v[110:111], v[196:197], v[180:181]
	v_pk_fma_f32 v[10:11], v[112:113], v[198:199], v[182:183]
	v_pk_fma_f32 v[12:13], v[114:115], v[200:201], v[184:185]
	v_pk_fma_f32 v[14:15], v[116:117], v[202:203], v[186:187]
	v_pk_fma_f32 v[16:17], v[118:119], v[204:205], v[188:189]
	v_pk_fma_f32 v[2:3], v[120:121], v[206:207], v[2:3]
	v_pk_fma_f32 v[4:5], v[122:123], v[208:209], v[4:5]
	v_pk_fma_f32 v[6:7], v[124:125], v[210:211], v[6:7]
	v_pk_fma_f32 v[8:9], v[126:127], v[212:213], v[8:9]
	v_pk_fma_f32 v[10:11], v[128:129], v[214:215], v[10:11]
	v_pk_fma_f32 v[12:13], v[130:131], v[216:217], v[12:13]
	v_pk_fma_f32 v[14:15], v[132:133], v[218:219], v[14:15]
	v_pk_fma_f32 v[16:17], v[134:135], v[220:221], v[16:17]
	v_pk_fma_f32 v[2:3], v[136:137], v[222:223], v[2:3]
	v_pk_fma_f32 v[4:5], v[138:139], v[224:225], v[4:5]
	v_pk_fma_f32 v[6:7], v[140:141], v[226:227], v[6:7]
	v_pk_fma_f32 v[8:9], v[142:143], v[228:229], v[8:9]
	v_pk_fma_f32 v[10:11], v[144:145], v[230:231], v[10:11]
	v_pk_fma_f32 v[12:13], v[146:147], v[232:233], v[12:13]
	v_pk_fma_f32 v[14:15], v[148:149], v[234:235], v[14:15]
	v_pk_fma_f32 v[16:17], v[150:151], v[236:237], v[16:17]
	v_mul_f32_e32 v18, 0xbfb8aa3b, v2
	v_mul_f32_e32 v19, 0xbfb8aa3b, v3
	v_mul_f32_e32 v20, 0xbfb8aa3b, v4
	v_mul_f32_e32 v21, 0xbfb8aa3b, v5
	v_mul_f32_e32 v22, 0xbfb8aa3b, v6
	v_mul_f32_e32 v23, 0xbfb8aa3b, v7
	v_mul_f32_e32 v24, 0xbfb8aa3b, v8
	v_mul_f32_e32 v25, 0xbfb8aa3b, v9
	v_exp_f32_e32 v18, v18
	v_exp_f32_e32 v19, v19
	v_exp_f32_e32 v20, v20
	v_exp_f32_e32 v21, v21
	v_exp_f32_e32 v22, v22
	v_exp_f32_e32 v23, v23
	v_exp_f32_e32 v24, v24
	v_exp_f32_e32 v25, v25
	v_add_f32_e32 v18, 1.0, v18
	v_add_f32_e32 v19, 1.0, v19
	v_add_f32_e32 v20, 1.0, v20
	v_add_f32_e32 v21, 1.0, v21
	v_add_f32_e32 v22, 1.0, v22
	v_add_f32_e32 v23, 1.0, v23
	v_add_f32_e32 v24, 1.0, v24
	v_add_f32_e32 v25, 1.0, v25
	v_rcp_f32_e32 v18, v18
	v_rcp_f32_e32 v19, v19
	v_rcp_f32_e32 v20, v20
	v_rcp_f32_e32 v21, v21
	v_rcp_f32_e32 v22, v22
	v_rcp_f32_e32 v23, v23
	v_rcp_f32_e32 v24, v24
	v_rcp_f32_e32 v25, v25
	v_mul_f32_e32 v18, v2, v18
	v_mul_f32_e32 v19, v3, v19
	v_mul_f32_e32 v20, v4, v20
	v_mul_f32_e32 v21, v5, v21
	v_mul_f32_e32 v22, v6, v22
	v_mul_f32_e32 v23, v7, v23
	v_mul_f32_e32 v24, v8, v24
	v_mul_f32_e32 v25, v9, v25
	v_mul_f32_e32 v18, v10, v18
	v_mul_f32_e32 v19, v11, v19
	v_mul_f32_e32 v20, v12, v20
	v_mul_f32_e32 v21, v13, v21
	v_mul_f32_e32 v22, v14, v22
	v_mul_f32_e32 v23, v15, v23
	v_mul_f32_e32 v24, v16, v24
	v_mul_f32_e32 v25, v17, v25
	v_cvt_pk_bf16_f32 v26, v18, v19
	v_cvt_pk_bf16_f32 v27, v20, v21
	v_cvt_pk_bf16_f32 v28, v22, v23
	v_cvt_pk_bf16_f32 v29, v24, v25
	global_store_dwordx4 v[162:163], v[26:29], off sc1
	v_lshl_add_u64 v[162:163], v[162:163], 0, v[30:31]
	v_lshlrev_b32_e32 v190, 16, v88
	v_and_b32_e32 v191, 0xffff0000, v88
	v_lshlrev_b32_e32 v192, 16, v89
	v_and_b32_e32 v193, 0xffff0000, v89
	v_lshlrev_b32_e32 v194, 16, v90
	v_and_b32_e32 v195, 0xffff0000, v90
	v_lshlrev_b32_e32 v196, 16, v91
	v_and_b32_e32 v197, 0xffff0000, v91
	v_lshlrev_b32_e32 v198, 16, v92
	v_and_b32_e32 v199, 0xffff0000, v92
	v_lshlrev_b32_e32 v200, 16, v93
	v_and_b32_e32 v201, 0xffff0000, v93
	v_lshlrev_b32_e32 v202, 16, v94
	v_and_b32_e32 v203, 0xffff0000, v94
	v_lshlrev_b32_e32 v204, 16, v95
	v_and_b32_e32 v205, 0xffff0000, v95
	v_pk_fma_f32 v[2:3], v[104:105], v[206:207], v[174:175]
	v_pk_fma_f32 v[4:5], v[106:107], v[208:209], v[176:177]
	v_pk_fma_f32 v[6:7], v[108:109], v[210:211], v[178:179]
	v_pk_fma_f32 v[8:9], v[110:111], v[212:213], v[180:181]
	v_pk_fma_f32 v[10:11], v[112:113], v[214:215], v[182:183]
	v_pk_fma_f32 v[12:13], v[114:115], v[216:217], v[184:185]
	v_pk_fma_f32 v[14:15], v[116:117], v[218:219], v[186:187]
	v_pk_fma_f32 v[16:17], v[118:119], v[220:221], v[188:189]
	v_pk_fma_f32 v[2:3], v[120:121], v[222:223], v[2:3]
	v_pk_fma_f32 v[4:5], v[122:123], v[224:225], v[4:5]
	v_pk_fma_f32 v[6:7], v[124:125], v[226:227], v[6:7]
	v_pk_fma_f32 v[8:9], v[126:127], v[228:229], v[8:9]
	v_pk_fma_f32 v[10:11], v[128:129], v[230:231], v[10:11]
	v_pk_fma_f32 v[12:13], v[130:131], v[232:233], v[12:13]
	v_pk_fma_f32 v[14:15], v[132:133], v[234:235], v[14:15]
	v_pk_fma_f32 v[16:17], v[134:135], v[236:237], v[16:17]
	v_pk_fma_f32 v[2:3], v[136:137], v[190:191], v[2:3]
	v_pk_fma_f32 v[4:5], v[138:139], v[192:193], v[4:5]
	v_pk_fma_f32 v[6:7], v[140:141], v[194:195], v[6:7]
	v_pk_fma_f32 v[8:9], v[142:143], v[196:197], v[8:9]
	v_pk_fma_f32 v[10:11], v[144:145], v[198:199], v[10:11]
	v_pk_fma_f32 v[12:13], v[146:147], v[200:201], v[12:13]
	v_pk_fma_f32 v[14:15], v[148:149], v[202:203], v[14:15]
	v_pk_fma_f32 v[16:17], v[150:151], v[204:205], v[16:17]
	v_mul_f32_e32 v18, 0xbfb8aa3b, v2
	v_mul_f32_e32 v19, 0xbfb8aa3b, v3
	v_mul_f32_e32 v20, 0xbfb8aa3b, v4
	v_mul_f32_e32 v21, 0xbfb8aa3b, v5
	v_mul_f32_e32 v22, 0xbfb8aa3b, v6
	v_mul_f32_e32 v23, 0xbfb8aa3b, v7
	v_mul_f32_e32 v24, 0xbfb8aa3b, v8
	v_mul_f32_e32 v25, 0xbfb8aa3b, v9
	v_exp_f32_e32 v18, v18
	v_exp_f32_e32 v19, v19
	v_exp_f32_e32 v20, v20
	v_exp_f32_e32 v21, v21
	v_exp_f32_e32 v22, v22
	v_exp_f32_e32 v23, v23
	v_exp_f32_e32 v24, v24
	v_exp_f32_e32 v25, v25
	v_add_f32_e32 v18, 1.0, v18
	v_add_f32_e32 v19, 1.0, v19
	v_add_f32_e32 v20, 1.0, v20
	v_add_f32_e32 v21, 1.0, v21
	v_add_f32_e32 v22, 1.0, v22
	v_add_f32_e32 v23, 1.0, v23
	v_add_f32_e32 v24, 1.0, v24
	v_add_f32_e32 v25, 1.0, v25
	v_rcp_f32_e32 v18, v18
	v_rcp_f32_e32 v19, v19
	v_rcp_f32_e32 v20, v20
	v_rcp_f32_e32 v21, v21
	v_rcp_f32_e32 v22, v22
	v_rcp_f32_e32 v23, v23
	v_rcp_f32_e32 v24, v24
	v_rcp_f32_e32 v25, v25
	v_mul_f32_e32 v18, v2, v18
	v_mul_f32_e32 v19, v3, v19
	v_mul_f32_e32 v20, v4, v20
	v_mul_f32_e32 v21, v5, v21
	v_mul_f32_e32 v22, v6, v22
	v_mul_f32_e32 v23, v7, v23
	v_mul_f32_e32 v24, v8, v24
	v_mul_f32_e32 v25, v9, v25
	v_mul_f32_e32 v18, v10, v18
	v_mul_f32_e32 v19, v11, v19
	v_mul_f32_e32 v20, v12, v20
	v_mul_f32_e32 v21, v13, v21
	v_mul_f32_e32 v22, v14, v22
	v_mul_f32_e32 v23, v15, v23
	v_mul_f32_e32 v24, v16, v24
	v_mul_f32_e32 v25, v17, v25
	v_cvt_pk_bf16_f32 v26, v18, v19
	v_cvt_pk_bf16_f32 v27, v20, v21
	v_cvt_pk_bf16_f32 v28, v22, v23
	v_cvt_pk_bf16_f32 v29, v24, v25
	global_store_dwordx4 v[162:163], v[26:29], off sc1
	v_lshl_add_u64 v[162:163], v[162:163], 0, v[30:31]
	v_lshlrev_b32_e32 v206, 16, v96
	v_and_b32_e32 v207, 0xffff0000, v96
	v_lshlrev_b32_e32 v208, 16, v97
	v_and_b32_e32 v209, 0xffff0000, v97
	v_lshlrev_b32_e32 v210, 16, v98
	v_and_b32_e32 v211, 0xffff0000, v98
	v_lshlrev_b32_e32 v212, 16, v99
	v_and_b32_e32 v213, 0xffff0000, v99
	v_lshlrev_b32_e32 v214, 16, v100
	v_and_b32_e32 v215, 0xffff0000, v100
	v_lshlrev_b32_e32 v216, 16, v101
	v_and_b32_e32 v217, 0xffff0000, v101
	v_lshlrev_b32_e32 v218, 16, v102
	v_and_b32_e32 v219, 0xffff0000, v102
	v_lshlrev_b32_e32 v220, 16, v103
	v_and_b32_e32 v221, 0xffff0000, v103
	v_pk_fma_f32 v[2:3], v[104:105], v[222:223], v[174:175]
	v_pk_fma_f32 v[4:5], v[106:107], v[224:225], v[176:177]
	v_pk_fma_f32 v[6:7], v[108:109], v[226:227], v[178:179]
	v_pk_fma_f32 v[8:9], v[110:111], v[228:229], v[180:181]
	v_pk_fma_f32 v[10:11], v[112:113], v[230:231], v[182:183]
	v_pk_fma_f32 v[12:13], v[114:115], v[232:233], v[184:185]
	v_pk_fma_f32 v[14:15], v[116:117], v[234:235], v[186:187]
	v_pk_fma_f32 v[16:17], v[118:119], v[236:237], v[188:189]
	v_pk_fma_f32 v[2:3], v[120:121], v[190:191], v[2:3]
	v_pk_fma_f32 v[4:5], v[122:123], v[192:193], v[4:5]
	v_pk_fma_f32 v[6:7], v[124:125], v[194:195], v[6:7]
	v_pk_fma_f32 v[8:9], v[126:127], v[196:197], v[8:9]
	v_pk_fma_f32 v[10:11], v[128:129], v[198:199], v[10:11]
	v_pk_fma_f32 v[12:13], v[130:131], v[200:201], v[12:13]
	v_pk_fma_f32 v[14:15], v[132:133], v[202:203], v[14:15]
	v_pk_fma_f32 v[16:17], v[134:135], v[204:205], v[16:17]
	v_pk_fma_f32 v[2:3], v[136:137], v[206:207], v[2:3]
	v_pk_fma_f32 v[4:5], v[138:139], v[208:209], v[4:5]
	v_pk_fma_f32 v[6:7], v[140:141], v[210:211], v[6:7]
	v_pk_fma_f32 v[8:9], v[142:143], v[212:213], v[8:9]
	v_pk_fma_f32 v[10:11], v[144:145], v[214:215], v[10:11]
	v_pk_fma_f32 v[12:13], v[146:147], v[216:217], v[12:13]
	v_pk_fma_f32 v[14:15], v[148:149], v[218:219], v[14:15]
	v_pk_fma_f32 v[16:17], v[150:151], v[220:221], v[16:17]
	v_mul_f32_e32 v18, 0xbfb8aa3b, v2
	v_mul_f32_e32 v19, 0xbfb8aa3b, v3
	v_mul_f32_e32 v20, 0xbfb8aa3b, v4
	v_mul_f32_e32 v21, 0xbfb8aa3b, v5
	v_mul_f32_e32 v22, 0xbfb8aa3b, v6
	v_mul_f32_e32 v23, 0xbfb8aa3b, v7
	v_mul_f32_e32 v24, 0xbfb8aa3b, v8
	v_mul_f32_e32 v25, 0xbfb8aa3b, v9
	v_exp_f32_e32 v18, v18
	v_exp_f32_e32 v19, v19
	v_exp_f32_e32 v20, v20
	v_exp_f32_e32 v21, v21
	v_exp_f32_e32 v22, v22
	v_exp_f32_e32 v23, v23
	v_exp_f32_e32 v24, v24
	v_exp_f32_e32 v25, v25
	v_add_f32_e32 v18, 1.0, v18
	v_add_f32_e32 v19, 1.0, v19
	v_add_f32_e32 v20, 1.0, v20
	v_add_f32_e32 v21, 1.0, v21
	v_add_f32_e32 v22, 1.0, v22
	v_add_f32_e32 v23, 1.0, v23
	v_add_f32_e32 v24, 1.0, v24
	v_add_f32_e32 v25, 1.0, v25
	v_rcp_f32_e32 v18, v18
	v_rcp_f32_e32 v19, v19
	v_rcp_f32_e32 v20, v20
	v_rcp_f32_e32 v21, v21
	v_rcp_f32_e32 v22, v22
	v_rcp_f32_e32 v23, v23
	v_rcp_f32_e32 v24, v24
	v_rcp_f32_e32 v25, v25
	v_mul_f32_e32 v18, v2, v18
	v_mul_f32_e32 v19, v3, v19
	v_mul_f32_e32 v20, v4, v20
	v_mul_f32_e32 v21, v5, v21
	v_mul_f32_e32 v22, v6, v22
	v_mul_f32_e32 v23, v7, v23
	v_mul_f32_e32 v24, v8, v24
	v_mul_f32_e32 v25, v9, v25
	v_mul_f32_e32 v18, v10, v18
	v_mul_f32_e32 v19, v11, v19
	v_mul_f32_e32 v20, v12, v20
	v_mul_f32_e32 v21, v13, v21
	v_mul_f32_e32 v22, v14, v22
	v_mul_f32_e32 v23, v15, v23
	v_mul_f32_e32 v24, v16, v24
	v_mul_f32_e32 v25, v17, v25
	v_cvt_pk_bf16_f32 v26, v18, v19
	v_cvt_pk_bf16_f32 v27, v20, v21
	v_cvt_pk_bf16_f32 v28, v22, v23
	v_cvt_pk_bf16_f32 v29, v24, v25
	global_store_dwordx4 v[162:163], v[26:29], off sc1
	v_lshl_add_u64 v[162:163], v[162:163], 0, v[30:31]
	global_load_dwordx4 v[68:71], v[158:159], off nt
	global_load_dwordx4 v[72:75], v[160:161], off nt
	v_lshl_add_u64 v[158:159], v[158:159], 0, v[164:165]
	v_lshl_add_u64 v[160:161], v[160:161], 0, v[164:165]
	global_load_dwordx4 v[76:79], v[158:159], off nt
	global_load_dwordx4 v[80:83], v[160:161], off nt
	v_lshl_add_u64 v[158:159], v[158:159], 0, v[164:165]
	v_lshl_add_u64 v[160:161], v[160:161], 0, v[164:165]
	global_load_dwordx4 v[88:91], v[158:159], off nt
	global_load_dwordx4 v[92:95], v[160:161], off nt
	v_lshl_add_u64 v[158:159], v[158:159], 0, v[164:165]
	v_lshl_add_u64 v[160:161], v[160:161], 0, v[164:165]
	global_load_dwordx4 v[96:99], v[158:159], off nt
	global_load_dwordx4 v[100:103], v[160:161], off nt
	v_lshl_add_u64 v[158:159], v[158:159], 0, v[164:165]
	v_lshl_add_u64 v[160:161], v[160:161], 0, v[164:165]
	s_waitcnt vmcnt(12)
	v_lshlrev_b32_e32 v222, 16, v36
	v_and_b32_e32 v223, 0xffff0000, v36
	v_lshlrev_b32_e32 v224, 16, v37
	v_and_b32_e32 v225, 0xffff0000, v37
	v_lshlrev_b32_e32 v226, 16, v38
	v_and_b32_e32 v227, 0xffff0000, v38
	v_lshlrev_b32_e32 v228, 16, v39
	v_and_b32_e32 v229, 0xffff0000, v39
	v_lshlrev_b32_e32 v230, 16, v40
	v_and_b32_e32 v231, 0xffff0000, v40
	v_lshlrev_b32_e32 v232, 16, v41
	v_and_b32_e32 v233, 0xffff0000, v41
	v_lshlrev_b32_e32 v234, 16, v42
	v_and_b32_e32 v235, 0xffff0000, v42
	v_lshlrev_b32_e32 v236, 16, v43
	v_and_b32_e32 v237, 0xffff0000, v43
	v_pk_fma_f32 v[2:3], v[104:105], v[190:191], v[174:175]
	v_pk_fma_f32 v[4:5], v[106:107], v[192:193], v[176:177]
	v_pk_fma_f32 v[6:7], v[108:109], v[194:195], v[178:179]
	v_pk_fma_f32 v[8:9], v[110:111], v[196:197], v[180:181]
	v_pk_fma_f32 v[10:11], v[112:113], v[198:199], v[182:183]
	v_pk_fma_f32 v[12:13], v[114:115], v[200:201], v[184:185]
	v_pk_fma_f32 v[14:15], v[116:117], v[202:203], v[186:187]
	v_pk_fma_f32 v[16:17], v[118:119], v[204:205], v[188:189]
	v_pk_fma_f32 v[2:3], v[120:121], v[206:207], v[2:3]
	v_pk_fma_f32 v[4:5], v[122:123], v[208:209], v[4:5]
	v_pk_fma_f32 v[6:7], v[124:125], v[210:211], v[6:7]
	v_pk_fma_f32 v[8:9], v[126:127], v[212:213], v[8:9]
	v_pk_fma_f32 v[10:11], v[128:129], v[214:215], v[10:11]
	v_pk_fma_f32 v[12:13], v[130:131], v[216:217], v[12:13]
	v_pk_fma_f32 v[14:15], v[132:133], v[218:219], v[14:15]
	v_pk_fma_f32 v[16:17], v[134:135], v[220:221], v[16:17]
	v_pk_fma_f32 v[2:3], v[136:137], v[222:223], v[2:3]
	v_pk_fma_f32 v[4:5], v[138:139], v[224:225], v[4:5]
	v_pk_fma_f32 v[6:7], v[140:141], v[226:227], v[6:7]
	v_pk_fma_f32 v[8:9], v[142:143], v[228:229], v[8:9]
	v_pk_fma_f32 v[10:11], v[144:145], v[230:231], v[10:11]
	v_pk_fma_f32 v[12:13], v[146:147], v[232:233], v[12:13]
	v_pk_fma_f32 v[14:15], v[148:149], v[234:235], v[14:15]
	v_pk_fma_f32 v[16:17], v[150:151], v[236:237], v[16:17]
	v_mul_f32_e32 v18, 0xbfb8aa3b, v2
	v_mul_f32_e32 v19, 0xbfb8aa3b, v3
	v_mul_f32_e32 v20, 0xbfb8aa3b, v4
	v_mul_f32_e32 v21, 0xbfb8aa3b, v5
	v_mul_f32_e32 v22, 0xbfb8aa3b, v6
	v_mul_f32_e32 v23, 0xbfb8aa3b, v7
	v_mul_f32_e32 v24, 0xbfb8aa3b, v8
	v_mul_f32_e32 v25, 0xbfb8aa3b, v9
	v_exp_f32_e32 v18, v18
	v_exp_f32_e32 v19, v19
	v_exp_f32_e32 v20, v20
	v_exp_f32_e32 v21, v21
	v_exp_f32_e32 v22, v22
	v_exp_f32_e32 v23, v23
	v_exp_f32_e32 v24, v24
	v_exp_f32_e32 v25, v25
	v_add_f32_e32 v18, 1.0, v18
	v_add_f32_e32 v19, 1.0, v19
	v_add_f32_e32 v20, 1.0, v20
	v_add_f32_e32 v21, 1.0, v21
	v_add_f32_e32 v22, 1.0, v22
	v_add_f32_e32 v23, 1.0, v23
	v_add_f32_e32 v24, 1.0, v24
	v_add_f32_e32 v25, 1.0, v25
	v_rcp_f32_e32 v18, v18
	v_rcp_f32_e32 v19, v19
	v_rcp_f32_e32 v20, v20
	v_rcp_f32_e32 v21, v21
	v_rcp_f32_e32 v22, v22
	v_rcp_f32_e32 v23, v23
	v_rcp_f32_e32 v24, v24
	v_rcp_f32_e32 v25, v25
	v_mul_f32_e32 v18, v2, v18
	v_mul_f32_e32 v19, v3, v19
	v_mul_f32_e32 v20, v4, v20
	v_mul_f32_e32 v21, v5, v21
	v_mul_f32_e32 v22, v6, v22
	v_mul_f32_e32 v23, v7, v23
	v_mul_f32_e32 v24, v8, v24
	v_mul_f32_e32 v25, v9, v25
	v_mul_f32_e32 v18, v10, v18
	v_mul_f32_e32 v19, v11, v19
	v_mul_f32_e32 v20, v12, v20
	v_mul_f32_e32 v21, v13, v21
	v_mul_f32_e32 v22, v14, v22
	v_mul_f32_e32 v23, v15, v23
	v_mul_f32_e32 v24, v16, v24
	v_mul_f32_e32 v25, v17, v25
	v_cvt_pk_bf16_f32 v26, v18, v19
	v_cvt_pk_bf16_f32 v27, v20, v21
	v_cvt_pk_bf16_f32 v28, v22, v23
	v_cvt_pk_bf16_f32 v29, v24, v25
	global_store_dwordx4 v[162:163], v[26:29], off sc1
	v_lshl_add_u64 v[162:163], v[162:163], 0, v[30:31]
	v_lshlrev_b32_e32 v190, 16, v44
	v_and_b32_e32 v191, 0xffff0000, v44
	v_lshlrev_b32_e32 v192, 16, v45
	v_and_b32_e32 v193, 0xffff0000, v45
	v_lshlrev_b32_e32 v194, 16, v46
	v_and_b32_e32 v195, 0xffff0000, v46
	v_lshlrev_b32_e32 v196, 16, v47
	v_and_b32_e32 v197, 0xffff0000, v47
	v_lshlrev_b32_e32 v198, 16, v48
	v_and_b32_e32 v199, 0xffff0000, v48
	v_lshlrev_b32_e32 v200, 16, v49
	v_and_b32_e32 v201, 0xffff0000, v49
	v_lshlrev_b32_e32 v202, 16, v50
	v_and_b32_e32 v203, 0xffff0000, v50
	v_lshlrev_b32_e32 v204, 16, v51
	v_and_b32_e32 v205, 0xffff0000, v51
	v_pk_fma_f32 v[2:3], v[104:105], v[206:207], v[174:175]
	v_pk_fma_f32 v[4:5], v[106:107], v[208:209], v[176:177]
	v_pk_fma_f32 v[6:7], v[108:109], v[210:211], v[178:179]
	v_pk_fma_f32 v[8:9], v[110:111], v[212:213], v[180:181]
	v_pk_fma_f32 v[10:11], v[112:113], v[214:215], v[182:183]
	v_pk_fma_f32 v[12:13], v[114:115], v[216:217], v[184:185]
	v_pk_fma_f32 v[14:15], v[116:117], v[218:219], v[186:187]
	v_pk_fma_f32 v[16:17], v[118:119], v[220:221], v[188:189]
	v_pk_fma_f32 v[2:3], v[120:121], v[222:223], v[2:3]
	v_pk_fma_f32 v[4:5], v[122:123], v[224:225], v[4:5]
	v_pk_fma_f32 v[6:7], v[124:125], v[226:227], v[6:7]
	v_pk_fma_f32 v[8:9], v[126:127], v[228:229], v[8:9]
	v_pk_fma_f32 v[10:11], v[128:129], v[230:231], v[10:11]
	v_pk_fma_f32 v[12:13], v[130:131], v[232:233], v[12:13]
	v_pk_fma_f32 v[14:15], v[132:133], v[234:235], v[14:15]
	v_pk_fma_f32 v[16:17], v[134:135], v[236:237], v[16:17]
	v_pk_fma_f32 v[2:3], v[136:137], v[190:191], v[2:3]
	v_pk_fma_f32 v[4:5], v[138:139], v[192:193], v[4:5]
	v_pk_fma_f32 v[6:7], v[140:141], v[194:195], v[6:7]
	v_pk_fma_f32 v[8:9], v[142:143], v[196:197], v[8:9]
	v_pk_fma_f32 v[10:11], v[144:145], v[198:199], v[10:11]
	v_pk_fma_f32 v[12:13], v[146:147], v[200:201], v[12:13]
	v_pk_fma_f32 v[14:15], v[148:149], v[202:203], v[14:15]
	v_pk_fma_f32 v[16:17], v[150:151], v[204:205], v[16:17]
	v_mul_f32_e32 v18, 0xbfb8aa3b, v2
	v_mul_f32_e32 v19, 0xbfb8aa3b, v3
	v_mul_f32_e32 v20, 0xbfb8aa3b, v4
	v_mul_f32_e32 v21, 0xbfb8aa3b, v5
	v_mul_f32_e32 v22, 0xbfb8aa3b, v6
	v_mul_f32_e32 v23, 0xbfb8aa3b, v7
	v_mul_f32_e32 v24, 0xbfb8aa3b, v8
	v_mul_f32_e32 v25, 0xbfb8aa3b, v9
	v_exp_f32_e32 v18, v18
	v_exp_f32_e32 v19, v19
	v_exp_f32_e32 v20, v20
	v_exp_f32_e32 v21, v21
	v_exp_f32_e32 v22, v22
	v_exp_f32_e32 v23, v23
	v_exp_f32_e32 v24, v24
	v_exp_f32_e32 v25, v25
	v_add_f32_e32 v18, 1.0, v18
	v_add_f32_e32 v19, 1.0, v19
	v_add_f32_e32 v20, 1.0, v20
	v_add_f32_e32 v21, 1.0, v21
	v_add_f32_e32 v22, 1.0, v22
	v_add_f32_e32 v23, 1.0, v23
	v_add_f32_e32 v24, 1.0, v24
	v_add_f32_e32 v25, 1.0, v25
	v_rcp_f32_e32 v18, v18
	v_rcp_f32_e32 v19, v19
	v_rcp_f32_e32 v20, v20
	v_rcp_f32_e32 v21, v21
	v_rcp_f32_e32 v22, v22
	v_rcp_f32_e32 v23, v23
	v_rcp_f32_e32 v24, v24
	v_rcp_f32_e32 v25, v25
	v_mul_f32_e32 v18, v2, v18
	v_mul_f32_e32 v19, v3, v19
	v_mul_f32_e32 v20, v4, v20
	v_mul_f32_e32 v21, v5, v21
	v_mul_f32_e32 v22, v6, v22
	v_mul_f32_e32 v23, v7, v23
	v_mul_f32_e32 v24, v8, v24
	v_mul_f32_e32 v25, v9, v25
	v_mul_f32_e32 v18, v10, v18
	v_mul_f32_e32 v19, v11, v19
	v_mul_f32_e32 v20, v12, v20
	v_mul_f32_e32 v21, v13, v21
	v_mul_f32_e32 v22, v14, v22
	v_mul_f32_e32 v23, v15, v23
	v_mul_f32_e32 v24, v16, v24
	v_mul_f32_e32 v25, v17, v25
	v_cvt_pk_bf16_f32 v26, v18, v19
	v_cvt_pk_bf16_f32 v27, v20, v21
	v_cvt_pk_bf16_f32 v28, v22, v23
	v_cvt_pk_bf16_f32 v29, v24, v25
	global_store_dwordx4 v[162:163], v[26:29], off sc1
	v_lshl_add_u64 v[162:163], v[162:163], 0, v[30:31]
	v_lshlrev_b32_e32 v206, 16, v52
	v_and_b32_e32 v207, 0xffff0000, v52
	v_lshlrev_b32_e32 v208, 16, v53
	v_and_b32_e32 v209, 0xffff0000, v53
	v_lshlrev_b32_e32 v210, 16, v54
	v_and_b32_e32 v211, 0xffff0000, v54
	v_lshlrev_b32_e32 v212, 16, v55
	v_and_b32_e32 v213, 0xffff0000, v55
	v_lshlrev_b32_e32 v214, 16, v56
	v_and_b32_e32 v215, 0xffff0000, v56
	v_lshlrev_b32_e32 v216, 16, v57
	v_and_b32_e32 v217, 0xffff0000, v57
	v_lshlrev_b32_e32 v218, 16, v58
	v_and_b32_e32 v219, 0xffff0000, v58
	v_lshlrev_b32_e32 v220, 16, v59
	v_and_b32_e32 v221, 0xffff0000, v59
	v_pk_fma_f32 v[2:3], v[104:105], v[222:223], v[174:175]
	v_pk_fma_f32 v[4:5], v[106:107], v[224:225], v[176:177]
	v_pk_fma_f32 v[6:7], v[108:109], v[226:227], v[178:179]
	v_pk_fma_f32 v[8:9], v[110:111], v[228:229], v[180:181]
	v_pk_fma_f32 v[10:11], v[112:113], v[230:231], v[182:183]
	v_pk_fma_f32 v[12:13], v[114:115], v[232:233], v[184:185]
	v_pk_fma_f32 v[14:15], v[116:117], v[234:235], v[186:187]
	v_pk_fma_f32 v[16:17], v[118:119], v[236:237], v[188:189]
	v_pk_fma_f32 v[2:3], v[120:121], v[190:191], v[2:3]
	v_pk_fma_f32 v[4:5], v[122:123], v[192:193], v[4:5]
	v_pk_fma_f32 v[6:7], v[124:125], v[194:195], v[6:7]
	v_pk_fma_f32 v[8:9], v[126:127], v[196:197], v[8:9]
	v_pk_fma_f32 v[10:11], v[128:129], v[198:199], v[10:11]
	v_pk_fma_f32 v[12:13], v[130:131], v[200:201], v[12:13]
	v_pk_fma_f32 v[14:15], v[132:133], v[202:203], v[14:15]
	v_pk_fma_f32 v[16:17], v[134:135], v[204:205], v[16:17]
	v_pk_fma_f32 v[2:3], v[136:137], v[206:207], v[2:3]
	v_pk_fma_f32 v[4:5], v[138:139], v[208:209], v[4:5]
	v_pk_fma_f32 v[6:7], v[140:141], v[210:211], v[6:7]
	v_pk_fma_f32 v[8:9], v[142:143], v[212:213], v[8:9]
	v_pk_fma_f32 v[10:11], v[144:145], v[214:215], v[10:11]
	v_pk_fma_f32 v[12:13], v[146:147], v[216:217], v[12:13]
	v_pk_fma_f32 v[14:15], v[148:149], v[218:219], v[14:15]
	v_pk_fma_f32 v[16:17], v[150:151], v[220:221], v[16:17]
	v_mul_f32_e32 v18, 0xbfb8aa3b, v2
	v_mul_f32_e32 v19, 0xbfb8aa3b, v3
	v_mul_f32_e32 v20, 0xbfb8aa3b, v4
	v_mul_f32_e32 v21, 0xbfb8aa3b, v5
	v_mul_f32_e32 v22, 0xbfb8aa3b, v6
	v_mul_f32_e32 v23, 0xbfb8aa3b, v7
	v_mul_f32_e32 v24, 0xbfb8aa3b, v8
	v_mul_f32_e32 v25, 0xbfb8aa3b, v9
	v_exp_f32_e32 v18, v18
	v_exp_f32_e32 v19, v19
	v_exp_f32_e32 v20, v20
	v_exp_f32_e32 v21, v21
	v_exp_f32_e32 v22, v22
	v_exp_f32_e32 v23, v23
	v_exp_f32_e32 v24, v24
	v_exp_f32_e32 v25, v25
	v_add_f32_e32 v18, 1.0, v18
	v_add_f32_e32 v19, 1.0, v19
	v_add_f32_e32 v20, 1.0, v20
	v_add_f32_e32 v21, 1.0, v21
	v_add_f32_e32 v22, 1.0, v22
	v_add_f32_e32 v23, 1.0, v23
	v_add_f32_e32 v24, 1.0, v24
	v_add_f32_e32 v25, 1.0, v25
	v_rcp_f32_e32 v18, v18
	v_rcp_f32_e32 v19, v19
	v_rcp_f32_e32 v20, v20
	v_rcp_f32_e32 v21, v21
	v_rcp_f32_e32 v22, v22
	v_rcp_f32_e32 v23, v23
	v_rcp_f32_e32 v24, v24
	v_rcp_f32_e32 v25, v25
	v_mul_f32_e32 v18, v2, v18
	v_mul_f32_e32 v19, v3, v19
	v_mul_f32_e32 v20, v4, v20
	v_mul_f32_e32 v21, v5, v21
	v_mul_f32_e32 v22, v6, v22
	v_mul_f32_e32 v23, v7, v23
	v_mul_f32_e32 v24, v8, v24
	v_mul_f32_e32 v25, v9, v25
	v_mul_f32_e32 v18, v10, v18
	v_mul_f32_e32 v19, v11, v19
	v_mul_f32_e32 v20, v12, v20
	v_mul_f32_e32 v21, v13, v21
	v_mul_f32_e32 v22, v14, v22
	v_mul_f32_e32 v23, v15, v23
	v_mul_f32_e32 v24, v16, v24
	v_mul_f32_e32 v25, v17, v25
	v_cvt_pk_bf16_f32 v26, v18, v19
	v_cvt_pk_bf16_f32 v27, v20, v21
	v_cvt_pk_bf16_f32 v28, v22, v23
	v_cvt_pk_bf16_f32 v29, v24, v25
	global_store_dwordx4 v[162:163], v[26:29], off sc1
	v_lshl_add_u64 v[162:163], v[162:163], 0, v[30:31]
	v_lshlrev_b32_e32 v222, 16, v60
	v_and_b32_e32 v223, 0xffff0000, v60
	v_lshlrev_b32_e32 v224, 16, v61
	v_and_b32_e32 v225, 0xffff0000, v61
	v_lshlrev_b32_e32 v226, 16, v62
	v_and_b32_e32 v227, 0xffff0000, v62
	v_lshlrev_b32_e32 v228, 16, v63
	v_and_b32_e32 v229, 0xffff0000, v63
	v_lshlrev_b32_e32 v230, 16, v64
	v_and_b32_e32 v231, 0xffff0000, v64
	v_lshlrev_b32_e32 v232, 16, v65
	v_and_b32_e32 v233, 0xffff0000, v65
	v_lshlrev_b32_e32 v234, 16, v66
	v_and_b32_e32 v235, 0xffff0000, v66
	v_lshlrev_b32_e32 v236, 16, v67
	v_and_b32_e32 v237, 0xffff0000, v67
	v_pk_fma_f32 v[2:3], v[104:105], v[190:191], v[174:175]
	v_pk_fma_f32 v[4:5], v[106:107], v[192:193], v[176:177]
	v_pk_fma_f32 v[6:7], v[108:109], v[194:195], v[178:179]
	v_pk_fma_f32 v[8:9], v[110:111], v[196:197], v[180:181]
	v_pk_fma_f32 v[10:11], v[112:113], v[198:199], v[182:183]
	v_pk_fma_f32 v[12:13], v[114:115], v[200:201], v[184:185]
	v_pk_fma_f32 v[14:15], v[116:117], v[202:203], v[186:187]
	v_pk_fma_f32 v[16:17], v[118:119], v[204:205], v[188:189]
	v_pk_fma_f32 v[2:3], v[120:121], v[206:207], v[2:3]
	v_pk_fma_f32 v[4:5], v[122:123], v[208:209], v[4:5]
	v_pk_fma_f32 v[6:7], v[124:125], v[210:211], v[6:7]
	v_pk_fma_f32 v[8:9], v[126:127], v[212:213], v[8:9]
	v_pk_fma_f32 v[10:11], v[128:129], v[214:215], v[10:11]
	v_pk_fma_f32 v[12:13], v[130:131], v[216:217], v[12:13]
	v_pk_fma_f32 v[14:15], v[132:133], v[218:219], v[14:15]
	v_pk_fma_f32 v[16:17], v[134:135], v[220:221], v[16:17]
	v_pk_fma_f32 v[2:3], v[136:137], v[222:223], v[2:3]
	v_pk_fma_f32 v[4:5], v[138:139], v[224:225], v[4:5]
	v_pk_fma_f32 v[6:7], v[140:141], v[226:227], v[6:7]
	v_pk_fma_f32 v[8:9], v[142:143], v[228:229], v[8:9]
	v_pk_fma_f32 v[10:11], v[144:145], v[230:231], v[10:11]
	v_pk_fma_f32 v[12:13], v[146:147], v[232:233], v[12:13]
	v_pk_fma_f32 v[14:15], v[148:149], v[234:235], v[14:15]
	v_pk_fma_f32 v[16:17], v[150:151], v[236:237], v[16:17]
	v_mul_f32_e32 v18, 0xbfb8aa3b, v2
	v_mul_f32_e32 v19, 0xbfb8aa3b, v3
	v_mul_f32_e32 v20, 0xbfb8aa3b, v4
	v_mul_f32_e32 v21, 0xbfb8aa3b, v5
	v_mul_f32_e32 v22, 0xbfb8aa3b, v6
	v_mul_f32_e32 v23, 0xbfb8aa3b, v7
	v_mul_f32_e32 v24, 0xbfb8aa3b, v8
	v_mul_f32_e32 v25, 0xbfb8aa3b, v9
	v_exp_f32_e32 v18, v18
	v_exp_f32_e32 v19, v19
	v_exp_f32_e32 v20, v20
	v_exp_f32_e32 v21, v21
	v_exp_f32_e32 v22, v22
	v_exp_f32_e32 v23, v23
	v_exp_f32_e32 v24, v24
	v_exp_f32_e32 v25, v25
	v_add_f32_e32 v18, 1.0, v18
	v_add_f32_e32 v19, 1.0, v19
	v_add_f32_e32 v20, 1.0, v20
	v_add_f32_e32 v21, 1.0, v21
	v_add_f32_e32 v22, 1.0, v22
	v_add_f32_e32 v23, 1.0, v23
	v_add_f32_e32 v24, 1.0, v24
	v_add_f32_e32 v25, 1.0, v25
	v_rcp_f32_e32 v18, v18
	v_rcp_f32_e32 v19, v19
	v_rcp_f32_e32 v20, v20
	v_rcp_f32_e32 v21, v21
	v_rcp_f32_e32 v22, v22
	v_rcp_f32_e32 v23, v23
	v_rcp_f32_e32 v24, v24
	v_rcp_f32_e32 v25, v25
	v_mul_f32_e32 v18, v2, v18
	v_mul_f32_e32 v19, v3, v19
	v_mul_f32_e32 v20, v4, v20
	v_mul_f32_e32 v21, v5, v21
	v_mul_f32_e32 v22, v6, v22
	v_mul_f32_e32 v23, v7, v23
	v_mul_f32_e32 v24, v8, v24
	v_mul_f32_e32 v25, v9, v25
	v_mul_f32_e32 v18, v10, v18
	v_mul_f32_e32 v19, v11, v19
	v_mul_f32_e32 v20, v12, v20
	v_mul_f32_e32 v21, v13, v21
	v_mul_f32_e32 v22, v14, v22
	v_mul_f32_e32 v23, v15, v23
	v_mul_f32_e32 v24, v16, v24
	v_mul_f32_e32 v25, v17, v25
	v_cvt_pk_bf16_f32 v26, v18, v19
	v_cvt_pk_bf16_f32 v27, v20, v21
	v_cvt_pk_bf16_f32 v28, v22, v23
	v_cvt_pk_bf16_f32 v29, v24, v25
	global_store_dwordx4 v[162:163], v[26:29], off sc1
	v_lshl_add_u64 v[162:163], v[162:163], 0, v[30:31]
	s_waitcnt vmcnt(4)
	v_lshlrev_b32_e32 v190, 16, v68
	v_and_b32_e32 v191, 0xffff0000, v68
	v_lshlrev_b32_e32 v192, 16, v69
	v_and_b32_e32 v193, 0xffff0000, v69
	v_lshlrev_b32_e32 v194, 16, v70
	v_and_b32_e32 v195, 0xffff0000, v70
	v_lshlrev_b32_e32 v196, 16, v71
	v_and_b32_e32 v197, 0xffff0000, v71
	v_lshlrev_b32_e32 v198, 16, v72
	v_and_b32_e32 v199, 0xffff0000, v72
	v_lshlrev_b32_e32 v200, 16, v73
	v_and_b32_e32 v201, 0xffff0000, v73
	v_lshlrev_b32_e32 v202, 16, v74
	v_and_b32_e32 v203, 0xffff0000, v74
	v_lshlrev_b32_e32 v204, 16, v75
	v_and_b32_e32 v205, 0xffff0000, v75
	v_pk_fma_f32 v[2:3], v[104:105], v[206:207], v[174:175]
	v_pk_fma_f32 v[4:5], v[106:107], v[208:209], v[176:177]
	v_pk_fma_f32 v[6:7], v[108:109], v[210:211], v[178:179]
	v_pk_fma_f32 v[8:9], v[110:111], v[212:213], v[180:181]
	v_pk_fma_f32 v[10:11], v[112:113], v[214:215], v[182:183]
	v_pk_fma_f32 v[12:13], v[114:115], v[216:217], v[184:185]
	v_pk_fma_f32 v[14:15], v[116:117], v[218:219], v[186:187]
	v_pk_fma_f32 v[16:17], v[118:119], v[220:221], v[188:189]
	v_pk_fma_f32 v[2:3], v[120:121], v[222:223], v[2:3]
	v_pk_fma_f32 v[4:5], v[122:123], v[224:225], v[4:5]
	v_pk_fma_f32 v[6:7], v[124:125], v[226:227], v[6:7]
	v_pk_fma_f32 v[8:9], v[126:127], v[228:229], v[8:9]
	v_pk_fma_f32 v[10:11], v[128:129], v[230:231], v[10:11]
	v_pk_fma_f32 v[12:13], v[130:131], v[232:233], v[12:13]
	v_pk_fma_f32 v[14:15], v[132:133], v[234:235], v[14:15]
	v_pk_fma_f32 v[16:17], v[134:135], v[236:237], v[16:17]
	v_pk_fma_f32 v[2:3], v[136:137], v[190:191], v[2:3]
	v_pk_fma_f32 v[4:5], v[138:139], v[192:193], v[4:5]
	v_pk_fma_f32 v[6:7], v[140:141], v[194:195], v[6:7]
	v_pk_fma_f32 v[8:9], v[142:143], v[196:197], v[8:9]
	v_pk_fma_f32 v[10:11], v[144:145], v[198:199], v[10:11]
	v_pk_fma_f32 v[12:13], v[146:147], v[200:201], v[12:13]
	v_pk_fma_f32 v[14:15], v[148:149], v[202:203], v[14:15]
	v_pk_fma_f32 v[16:17], v[150:151], v[204:205], v[16:17]
	v_mul_f32_e32 v18, 0xbfb8aa3b, v2
	v_mul_f32_e32 v19, 0xbfb8aa3b, v3
	v_mul_f32_e32 v20, 0xbfb8aa3b, v4
	v_mul_f32_e32 v21, 0xbfb8aa3b, v5
	v_mul_f32_e32 v22, 0xbfb8aa3b, v6
	v_mul_f32_e32 v23, 0xbfb8aa3b, v7
	v_mul_f32_e32 v24, 0xbfb8aa3b, v8
	v_mul_f32_e32 v25, 0xbfb8aa3b, v9
	v_exp_f32_e32 v18, v18
	v_exp_f32_e32 v19, v19
	v_exp_f32_e32 v20, v20
	v_exp_f32_e32 v21, v21
	v_exp_f32_e32 v22, v22
	v_exp_f32_e32 v23, v23
	v_exp_f32_e32 v24, v24
	v_exp_f32_e32 v25, v25
	v_add_f32_e32 v18, 1.0, v18
	v_add_f32_e32 v19, 1.0, v19
	v_add_f32_e32 v20, 1.0, v20
	v_add_f32_e32 v21, 1.0, v21
	v_add_f32_e32 v22, 1.0, v22
	v_add_f32_e32 v23, 1.0, v23
	v_add_f32_e32 v24, 1.0, v24
	v_add_f32_e32 v25, 1.0, v25
	v_rcp_f32_e32 v18, v18
	v_rcp_f32_e32 v19, v19
	v_rcp_f32_e32 v20, v20
	v_rcp_f32_e32 v21, v21
	v_rcp_f32_e32 v22, v22
	v_rcp_f32_e32 v23, v23
	v_rcp_f32_e32 v24, v24
	v_rcp_f32_e32 v25, v25
	v_mul_f32_e32 v18, v2, v18
	v_mul_f32_e32 v19, v3, v19
	v_mul_f32_e32 v20, v4, v20
	v_mul_f32_e32 v21, v5, v21
	v_mul_f32_e32 v22, v6, v22
	v_mul_f32_e32 v23, v7, v23
	v_mul_f32_e32 v24, v8, v24
	v_mul_f32_e32 v25, v9, v25
	v_mul_f32_e32 v18, v10, v18
	v_mul_f32_e32 v19, v11, v19
	v_mul_f32_e32 v20, v12, v20
	v_mul_f32_e32 v21, v13, v21
	v_mul_f32_e32 v22, v14, v22
	v_mul_f32_e32 v23, v15, v23
	v_mul_f32_e32 v24, v16, v24
	v_mul_f32_e32 v25, v17, v25
	v_cvt_pk_bf16_f32 v26, v18, v19
	v_cvt_pk_bf16_f32 v27, v20, v21
	v_cvt_pk_bf16_f32 v28, v22, v23
	v_cvt_pk_bf16_f32 v29, v24, v25
	global_store_dwordx4 v[162:163], v[26:29], off sc1
	v_lshl_add_u64 v[162:163], v[162:163], 0, v[30:31]
	v_lshlrev_b32_e32 v206, 16, v76
	v_and_b32_e32 v207, 0xffff0000, v76
	v_lshlrev_b32_e32 v208, 16, v77
	v_and_b32_e32 v209, 0xffff0000, v77
	v_lshlrev_b32_e32 v210, 16, v78
	v_and_b32_e32 v211, 0xffff0000, v78
	v_lshlrev_b32_e32 v212, 16, v79
	v_and_b32_e32 v213, 0xffff0000, v79
	v_lshlrev_b32_e32 v214, 16, v80
	v_and_b32_e32 v215, 0xffff0000, v80
	v_lshlrev_b32_e32 v216, 16, v81
	v_and_b32_e32 v217, 0xffff0000, v81
	v_lshlrev_b32_e32 v218, 16, v82
	v_and_b32_e32 v219, 0xffff0000, v82
	v_lshlrev_b32_e32 v220, 16, v83
	v_and_b32_e32 v221, 0xffff0000, v83
	v_pk_fma_f32 v[2:3], v[104:105], v[222:223], v[174:175]
	v_pk_fma_f32 v[4:5], v[106:107], v[224:225], v[176:177]
	v_pk_fma_f32 v[6:7], v[108:109], v[226:227], v[178:179]
	v_pk_fma_f32 v[8:9], v[110:111], v[228:229], v[180:181]
	v_pk_fma_f32 v[10:11], v[112:113], v[230:231], v[182:183]
	v_pk_fma_f32 v[12:13], v[114:115], v[232:233], v[184:185]
	v_pk_fma_f32 v[14:15], v[116:117], v[234:235], v[186:187]
	v_pk_fma_f32 v[16:17], v[118:119], v[236:237], v[188:189]
	v_pk_fma_f32 v[2:3], v[120:121], v[190:191], v[2:3]
	v_pk_fma_f32 v[4:5], v[122:123], v[192:193], v[4:5]
	v_pk_fma_f32 v[6:7], v[124:125], v[194:195], v[6:7]
	v_pk_fma_f32 v[8:9], v[126:127], v[196:197], v[8:9]
	v_pk_fma_f32 v[10:11], v[128:129], v[198:199], v[10:11]
	v_pk_fma_f32 v[12:13], v[130:131], v[200:201], v[12:13]
	v_pk_fma_f32 v[14:15], v[132:133], v[202:203], v[14:15]
	v_pk_fma_f32 v[16:17], v[134:135], v[204:205], v[16:17]
	v_pk_fma_f32 v[2:3], v[136:137], v[206:207], v[2:3]
	v_pk_fma_f32 v[4:5], v[138:139], v[208:209], v[4:5]
	v_pk_fma_f32 v[6:7], v[140:141], v[210:211], v[6:7]
	v_pk_fma_f32 v[8:9], v[142:143], v[212:213], v[8:9]
	v_pk_fma_f32 v[10:11], v[144:145], v[214:215], v[10:11]
	v_pk_fma_f32 v[12:13], v[146:147], v[216:217], v[12:13]
	v_pk_fma_f32 v[14:15], v[148:149], v[218:219], v[14:15]
	v_pk_fma_f32 v[16:17], v[150:151], v[220:221], v[16:17]
	v_mul_f32_e32 v18, 0xbfb8aa3b, v2
	v_mul_f32_e32 v19, 0xbfb8aa3b, v3
	v_mul_f32_e32 v20, 0xbfb8aa3b, v4
	v_mul_f32_e32 v21, 0xbfb8aa3b, v5
	v_mul_f32_e32 v22, 0xbfb8aa3b, v6
	v_mul_f32_e32 v23, 0xbfb8aa3b, v7
	v_mul_f32_e32 v24, 0xbfb8aa3b, v8
	v_mul_f32_e32 v25, 0xbfb8aa3b, v9
	v_exp_f32_e32 v18, v18
	v_exp_f32_e32 v19, v19
	v_exp_f32_e32 v20, v20
	v_exp_f32_e32 v21, v21
	v_exp_f32_e32 v22, v22
	v_exp_f32_e32 v23, v23
	v_exp_f32_e32 v24, v24
	v_exp_f32_e32 v25, v25
	v_add_f32_e32 v18, 1.0, v18
	v_add_f32_e32 v19, 1.0, v19
	v_add_f32_e32 v20, 1.0, v20
	v_add_f32_e32 v21, 1.0, v21
	v_add_f32_e32 v22, 1.0, v22
	v_add_f32_e32 v23, 1.0, v23
	v_add_f32_e32 v24, 1.0, v24
	v_add_f32_e32 v25, 1.0, v25
	v_rcp_f32_e32 v18, v18
	v_rcp_f32_e32 v19, v19
	v_rcp_f32_e32 v20, v20
	v_rcp_f32_e32 v21, v21
	v_rcp_f32_e32 v22, v22
	v_rcp_f32_e32 v23, v23
	v_rcp_f32_e32 v24, v24
	v_rcp_f32_e32 v25, v25
	v_mul_f32_e32 v18, v2, v18
	v_mul_f32_e32 v19, v3, v19
	v_mul_f32_e32 v20, v4, v20
	v_mul_f32_e32 v21, v5, v21
	v_mul_f32_e32 v22, v6, v22
	v_mul_f32_e32 v23, v7, v23
	v_mul_f32_e32 v24, v8, v24
	v_mul_f32_e32 v25, v9, v25
	v_mul_f32_e32 v18, v10, v18
	v_mul_f32_e32 v19, v11, v19
	v_mul_f32_e32 v20, v12, v20
	v_mul_f32_e32 v21, v13, v21
	v_mul_f32_e32 v22, v14, v22
	v_mul_f32_e32 v23, v15, v23
	v_mul_f32_e32 v24, v16, v24
	v_mul_f32_e32 v25, v17, v25
	v_cvt_pk_bf16_f32 v26, v18, v19
	v_cvt_pk_bf16_f32 v27, v20, v21
	v_cvt_pk_bf16_f32 v28, v22, v23
	v_cvt_pk_bf16_f32 v29, v24, v25
	global_store_dwordx4 v[162:163], v[26:29], off sc1
	v_lshl_add_u64 v[162:163], v[162:163], 0, v[30:31]
	v_lshlrev_b32_e32 v222, 16, v88
	v_and_b32_e32 v223, 0xffff0000, v88
	v_lshlrev_b32_e32 v224, 16, v89
	v_and_b32_e32 v225, 0xffff0000, v89
	v_lshlrev_b32_e32 v226, 16, v90
	v_and_b32_e32 v227, 0xffff0000, v90
	v_lshlrev_b32_e32 v228, 16, v91
	v_and_b32_e32 v229, 0xffff0000, v91
	v_lshlrev_b32_e32 v230, 16, v92
	v_and_b32_e32 v231, 0xffff0000, v92
	v_lshlrev_b32_e32 v232, 16, v93
	v_and_b32_e32 v233, 0xffff0000, v93
	v_lshlrev_b32_e32 v234, 16, v94
	v_and_b32_e32 v235, 0xffff0000, v94
	v_lshlrev_b32_e32 v236, 16, v95
	v_and_b32_e32 v237, 0xffff0000, v95
	v_pk_fma_f32 v[2:3], v[104:105], v[190:191], v[174:175]
	v_pk_fma_f32 v[4:5], v[106:107], v[192:193], v[176:177]
	v_pk_fma_f32 v[6:7], v[108:109], v[194:195], v[178:179]
	v_pk_fma_f32 v[8:9], v[110:111], v[196:197], v[180:181]
	v_pk_fma_f32 v[10:11], v[112:113], v[198:199], v[182:183]
	v_pk_fma_f32 v[12:13], v[114:115], v[200:201], v[184:185]
	v_pk_fma_f32 v[14:15], v[116:117], v[202:203], v[186:187]
	v_pk_fma_f32 v[16:17], v[118:119], v[204:205], v[188:189]
	v_pk_fma_f32 v[2:3], v[120:121], v[206:207], v[2:3]
	v_pk_fma_f32 v[4:5], v[122:123], v[208:209], v[4:5]
	v_pk_fma_f32 v[6:7], v[124:125], v[210:211], v[6:7]
	v_pk_fma_f32 v[8:9], v[126:127], v[212:213], v[8:9]
	v_pk_fma_f32 v[10:11], v[128:129], v[214:215], v[10:11]
	v_pk_fma_f32 v[12:13], v[130:131], v[216:217], v[12:13]
	v_pk_fma_f32 v[14:15], v[132:133], v[218:219], v[14:15]
	v_pk_fma_f32 v[16:17], v[134:135], v[220:221], v[16:17]
	v_pk_fma_f32 v[2:3], v[136:137], v[222:223], v[2:3]
	v_pk_fma_f32 v[4:5], v[138:139], v[224:225], v[4:5]
	v_pk_fma_f32 v[6:7], v[140:141], v[226:227], v[6:7]
	v_pk_fma_f32 v[8:9], v[142:143], v[228:229], v[8:9]
	v_pk_fma_f32 v[10:11], v[144:145], v[230:231], v[10:11]
	v_pk_fma_f32 v[12:13], v[146:147], v[232:233], v[12:13]
	v_pk_fma_f32 v[14:15], v[148:149], v[234:235], v[14:15]
	v_pk_fma_f32 v[16:17], v[150:151], v[236:237], v[16:17]
	v_mul_f32_e32 v18, 0xbfb8aa3b, v2
	v_mul_f32_e32 v19, 0xbfb8aa3b, v3
	v_mul_f32_e32 v20, 0xbfb8aa3b, v4
	v_mul_f32_e32 v21, 0xbfb8aa3b, v5
	v_mul_f32_e32 v22, 0xbfb8aa3b, v6
	v_mul_f32_e32 v23, 0xbfb8aa3b, v7
	v_mul_f32_e32 v24, 0xbfb8aa3b, v8
	v_mul_f32_e32 v25, 0xbfb8aa3b, v9
	v_exp_f32_e32 v18, v18
	v_exp_f32_e32 v19, v19
	v_exp_f32_e32 v20, v20
	v_exp_f32_e32 v21, v21
	v_exp_f32_e32 v22, v22
	v_exp_f32_e32 v23, v23
	v_exp_f32_e32 v24, v24
	v_exp_f32_e32 v25, v25
	v_add_f32_e32 v18, 1.0, v18
	v_add_f32_e32 v19, 1.0, v19
	v_add_f32_e32 v20, 1.0, v20
	v_add_f32_e32 v21, 1.0, v21
	v_add_f32_e32 v22, 1.0, v22
	v_add_f32_e32 v23, 1.0, v23
	v_add_f32_e32 v24, 1.0, v24
	v_add_f32_e32 v25, 1.0, v25
	v_rcp_f32_e32 v18, v18
	v_rcp_f32_e32 v19, v19
	v_rcp_f32_e32 v20, v20
	v_rcp_f32_e32 v21, v21
	v_rcp_f32_e32 v22, v22
	v_rcp_f32_e32 v23, v23
	v_rcp_f32_e32 v24, v24
	v_rcp_f32_e32 v25, v25
	v_mul_f32_e32 v18, v2, v18
	v_mul_f32_e32 v19, v3, v19
	v_mul_f32_e32 v20, v4, v20
	v_mul_f32_e32 v21, v5, v21
	v_mul_f32_e32 v22, v6, v22
	v_mul_f32_e32 v23, v7, v23
	v_mul_f32_e32 v24, v8, v24
	v_mul_f32_e32 v25, v9, v25
	v_mul_f32_e32 v18, v10, v18
	v_mul_f32_e32 v19, v11, v19
	v_mul_f32_e32 v20, v12, v20
	v_mul_f32_e32 v21, v13, v21
	v_mul_f32_e32 v22, v14, v22
	v_mul_f32_e32 v23, v15, v23
	v_mul_f32_e32 v24, v16, v24
	v_mul_f32_e32 v25, v17, v25
	v_cvt_pk_bf16_f32 v26, v18, v19
	v_cvt_pk_bf16_f32 v27, v20, v21
	v_cvt_pk_bf16_f32 v28, v22, v23
	v_cvt_pk_bf16_f32 v29, v24, v25
	global_store_dwordx4 v[162:163], v[26:29], off sc1
	v_lshl_add_u64 v[162:163], v[162:163], 0, v[30:31]
	v_lshlrev_b32_e32 v190, 16, v96
	v_and_b32_e32 v191, 0xffff0000, v96
	v_lshlrev_b32_e32 v192, 16, v97
	v_and_b32_e32 v193, 0xffff0000, v97
	v_lshlrev_b32_e32 v194, 16, v98
	v_and_b32_e32 v195, 0xffff0000, v98
	v_lshlrev_b32_e32 v196, 16, v99
	v_and_b32_e32 v197, 0xffff0000, v99
	v_lshlrev_b32_e32 v198, 16, v100
	v_and_b32_e32 v199, 0xffff0000, v100
	v_lshlrev_b32_e32 v200, 16, v101
	v_and_b32_e32 v201, 0xffff0000, v101
	v_lshlrev_b32_e32 v202, 16, v102
	v_and_b32_e32 v203, 0xffff0000, v102
	v_lshlrev_b32_e32 v204, 16, v103
	v_and_b32_e32 v205, 0xffff0000, v103
	v_pk_fma_f32 v[2:3], v[104:105], v[206:207], v[174:175]
	v_pk_fma_f32 v[4:5], v[106:107], v[208:209], v[176:177]
	v_pk_fma_f32 v[6:7], v[108:109], v[210:211], v[178:179]
	v_pk_fma_f32 v[8:9], v[110:111], v[212:213], v[180:181]
	v_pk_fma_f32 v[10:11], v[112:113], v[214:215], v[182:183]
	v_pk_fma_f32 v[12:13], v[114:115], v[216:217], v[184:185]
	v_pk_fma_f32 v[14:15], v[116:117], v[218:219], v[186:187]
	v_pk_fma_f32 v[16:17], v[118:119], v[220:221], v[188:189]
	v_pk_fma_f32 v[2:3], v[120:121], v[222:223], v[2:3]
	v_pk_fma_f32 v[4:5], v[122:123], v[224:225], v[4:5]
	v_pk_fma_f32 v[6:7], v[124:125], v[226:227], v[6:7]
	v_pk_fma_f32 v[8:9], v[126:127], v[228:229], v[8:9]
	v_pk_fma_f32 v[10:11], v[128:129], v[230:231], v[10:11]
	v_pk_fma_f32 v[12:13], v[130:131], v[232:233], v[12:13]
	v_pk_fma_f32 v[14:15], v[132:133], v[234:235], v[14:15]
	v_pk_fma_f32 v[16:17], v[134:135], v[236:237], v[16:17]
	v_pk_fma_f32 v[2:3], v[136:137], v[190:191], v[2:3]
	v_pk_fma_f32 v[4:5], v[138:139], v[192:193], v[4:5]
	v_pk_fma_f32 v[6:7], v[140:141], v[194:195], v[6:7]
	v_pk_fma_f32 v[8:9], v[142:143], v[196:197], v[8:9]
	v_pk_fma_f32 v[10:11], v[144:145], v[198:199], v[10:11]
	v_pk_fma_f32 v[12:13], v[146:147], v[200:201], v[12:13]
	v_pk_fma_f32 v[14:15], v[148:149], v[202:203], v[14:15]
	v_pk_fma_f32 v[16:17], v[150:151], v[204:205], v[16:17]
	v_mul_f32_e32 v18, 0xbfb8aa3b, v2
	v_mul_f32_e32 v19, 0xbfb8aa3b, v3
	v_mul_f32_e32 v20, 0xbfb8aa3b, v4
	v_mul_f32_e32 v21, 0xbfb8aa3b, v5
	v_mul_f32_e32 v22, 0xbfb8aa3b, v6
	v_mul_f32_e32 v23, 0xbfb8aa3b, v7
	v_mul_f32_e32 v24, 0xbfb8aa3b, v8
	v_mul_f32_e32 v25, 0xbfb8aa3b, v9
	v_exp_f32_e32 v18, v18
	v_exp_f32_e32 v19, v19
	v_exp_f32_e32 v20, v20
	v_exp_f32_e32 v21, v21
	v_exp_f32_e32 v22, v22
	v_exp_f32_e32 v23, v23
	v_exp_f32_e32 v24, v24
	v_exp_f32_e32 v25, v25
	v_add_f32_e32 v18, 1.0, v18
	v_add_f32_e32 v19, 1.0, v19
	v_add_f32_e32 v20, 1.0, v20
	v_add_f32_e32 v21, 1.0, v21
	v_add_f32_e32 v22, 1.0, v22
	v_add_f32_e32 v23, 1.0, v23
	v_add_f32_e32 v24, 1.0, v24
	v_add_f32_e32 v25, 1.0, v25
	v_rcp_f32_e32 v18, v18
	v_rcp_f32_e32 v19, v19
	v_rcp_f32_e32 v20, v20
	v_rcp_f32_e32 v21, v21
	v_rcp_f32_e32 v22, v22
	v_rcp_f32_e32 v23, v23
	v_rcp_f32_e32 v24, v24
	v_rcp_f32_e32 v25, v25
	v_mul_f32_e32 v18, v2, v18
	v_mul_f32_e32 v19, v3, v19
	v_mul_f32_e32 v20, v4, v20
	v_mul_f32_e32 v21, v5, v21
	v_mul_f32_e32 v22, v6, v22
	v_mul_f32_e32 v23, v7, v23
	v_mul_f32_e32 v24, v8, v24
	v_mul_f32_e32 v25, v9, v25
	v_mul_f32_e32 v18, v10, v18
	v_mul_f32_e32 v19, v11, v19
	v_mul_f32_e32 v20, v12, v20
	v_mul_f32_e32 v21, v13, v21
	v_mul_f32_e32 v22, v14, v22
	v_mul_f32_e32 v23, v15, v23
	v_mul_f32_e32 v24, v16, v24
	v_mul_f32_e32 v25, v17, v25
	v_cvt_pk_bf16_f32 v26, v18, v19
	v_cvt_pk_bf16_f32 v27, v20, v21
	v_cvt_pk_bf16_f32 v28, v22, v23
	v_cvt_pk_bf16_f32 v29, v24, v25
	global_store_dwordx4 v[162:163], v[26:29], off sc1
	v_lshl_add_u64 v[162:163], v[162:163], 0, v[30:31]
	s_cmpk_gt_u32 s28, 0xbf
	s_cbranch_scc1 .LBB0_2504
	v_add_u32_e32 v32, 0x80, v32
	v_add_u32_e32 v157, 0xba, v157
	v_cmp_lt_u32_e32 vcc, 0x2bf, v32
	v_subrev_u32_e32 v152, 0x2c0, v32
	s_nop 1
	v_cndmask_b32_e32 v32, v32, v152, vcc
	v_addc_co_u32_e32 v157, vcc, 0, v157, vcc
	v_mul_u32_u24_e32 v152, 0x58000, v157
	v_lshl_add_u32 v152, v32, 4, v152
	v_mov_b32_e32 v153, 0
	v_lshl_add_u64 v[158:159], s[36:37], 0, v[152:153]
	v_mul_u32_u24_e32 v152, 0x2c000, v157
	v_lshl_add_u32 v152, v32, 4, v152
	v_lshl_add_u64 v[162:163], s[38:39], 0, v[152:153]
	v_lshlrev_b32_e32 v33, 5, v32
	v_and_b32_e32 v152, 0x7f, v157
	v_cmp_eq_u32_e64 s[40:41], 0, v152
	v_mov_b32_e32 v152, 0x2c00
	v_lshl_add_u64 v[160:161], v[158:159], 0, v[152:153]
	global_load_dwordx4 v[104:107], v33, s[12:13]
	global_load_dwordx4 v[108:111], v33, s[12:13] offset:16
	global_load_dwordx4 v[112:115], v33, s[14:15]
	global_load_dwordx4 v[116:119], v33, s[14:15] offset:16
	global_load_dwordx4 v[120:123], v33, s[16:17]
	global_load_dwordx4 v[124:127], v33, s[16:17] offset:16
	global_load_dwordx4 v[128:131], v33, s[18:19]
	global_load_dwordx4 v[132:135], v33, s[18:19] offset:16
	global_load_dwordx4 v[136:139], v33, s[20:21]
	global_load_dwordx4 v[140:143], v33, s[20:21] offset:16
	global_load_dwordx4 v[144:147], v33, s[22:23]
	global_load_dwordx4 v[148:151], v33, s[22:23] offset:16
	global_load_dwordx4 v[174:177], v33, s[24:25]
	global_load_dwordx4 v[178:181], v33, s[24:25] offset:16
	global_load_dwordx4 v[182:185], v33, s[26:27]
	global_load_dwordx4 v[186:189], v33, s[26:27] offset:16
	v_mov_b32_e32 v152, 0xffffa800
	v_mov_b32_e32 v153, -1
	v_lshl_add_u64 v[154:155], v[158:159], 0, v[152:153]
	global_load_dwordx4 v[238:241], v[154:155], off
	v_lshl_add_u64 v[154:155], v[154:155], 0, v[152:153]
	global_load_dwordx4 v[246:249], v[154:155], off
	v_lshl_add_u64 v[154:155], v[160:161], 0, v[152:153]
	global_load_dwordx4 v[242:245], v[154:155], off
	v_lshl_add_u64 v[154:155], v[154:155], 0, v[152:153]
	global_load_dwordx4 v[250:253], v[154:155], off
	global_load_dwordx4 v[36:39], v[158:159], off nt
	global_load_dwordx4 v[40:43], v[160:161], off nt
	v_lshl_add_u64 v[158:159], v[158:159], 0, v[164:165]
	v_lshl_add_u64 v[160:161], v[160:161], 0, v[164:165]
	global_load_dwordx4 v[44:47], v[158:159], off nt
	global_load_dwordx4 v[48:51], v[160:161], off nt
	v_lshl_add_u64 v[158:159], v[158:159], 0, v[164:165]
	v_lshl_add_u64 v[160:161], v[160:161], 0, v[164:165]
	global_load_dwordx4 v[52:55], v[158:159], off nt
	global_load_dwordx4 v[56:59], v[160:161], off nt
	v_lshl_add_u64 v[158:159], v[158:159], 0, v[164:165]
	v_lshl_add_u64 v[160:161], v[160:161], 0, v[164:165]
	global_load_dwordx4 v[60:63], v[158:159], off nt
	global_load_dwordx4 v[64:67], v[160:161], off nt
	v_lshl_add_u64 v[158:159], v[158:159], 0, v[164:165]
	v_lshl_add_u64 v[160:161], v[160:161], 0, v[164:165]
	global_load_dwordx4 v[68:71], v[158:159], off nt
	global_load_dwordx4 v[72:75], v[160:161], off nt
	v_lshl_add_u64 v[158:159], v[158:159], 0, v[164:165]
	v_lshl_add_u64 v[160:161], v[160:161], 0, v[164:165]
	global_load_dwordx4 v[76:79], v[158:159], off nt
	global_load_dwordx4 v[80:83], v[160:161], off nt
	v_lshl_add_u64 v[158:159], v[158:159], 0, v[164:165]
	v_lshl_add_u64 v[160:161], v[160:161], 0, v[164:165]
	global_load_dwordx4 v[88:91], v[158:159], off nt
	global_load_dwordx4 v[92:95], v[160:161], off nt
	v_lshl_add_u64 v[158:159], v[158:159], 0, v[164:165]
	v_lshl_add_u64 v[160:161], v[160:161], 0, v[164:165]
	global_load_dwordx4 v[96:99], v[158:159], off nt
	global_load_dwordx4 v[100:103], v[160:161], off nt
	v_lshl_add_u64 v[158:159], v[158:159], 0, v[164:165]
	v_lshl_add_u64 v[160:161], v[160:161], 0, v[164:165]
	s_waitcnt vmcnt(8)
	v_lshlrev_b32_e32 v222, 16, v238
	v_and_b32_e32 v223, 0xffff0000, v238
	v_lshlrev_b32_e32 v224, 16, v239
	v_and_b32_e32 v225, 0xffff0000, v239
	v_lshlrev_b32_e32 v226, 16, v240
	v_and_b32_e32 v227, 0xffff0000, v240
	v_lshlrev_b32_e32 v228, 16, v241
	v_and_b32_e32 v229, 0xffff0000, v241
	v_lshlrev_b32_e32 v206, 16, v246
	v_and_b32_e32 v207, 0xffff0000, v246
	v_lshlrev_b32_e32 v208, 16, v247
	v_and_b32_e32 v209, 0xffff0000, v247
	v_lshlrev_b32_e32 v210, 16, v248
	v_and_b32_e32 v211, 0xffff0000, v248
	v_lshlrev_b32_e32 v212, 16, v249
	v_and_b32_e32 v213, 0xffff0000, v249
	v_lshlrev_b32_e32 v230, 16, v242
	v_and_b32_e32 v231, 0xffff0000, v242
	v_lshlrev_b32_e32 v232, 16, v243
	v_and_b32_e32 v233, 0xffff0000, v243
	v_lshlrev_b32_e32 v234, 16, v244
	v_and_b32_e32 v235, 0xffff0000, v244
	v_lshlrev_b32_e32 v236, 16, v245
	v_and_b32_e32 v237, 0xffff0000, v245
	v_lshlrev_b32_e32 v214, 16, v250
	v_and_b32_e32 v215, 0xffff0000, v250
	v_lshlrev_b32_e32 v216, 16, v251
	v_and_b32_e32 v217, 0xffff0000, v251
	v_lshlrev_b32_e32 v218, 16, v252
	v_and_b32_e32 v219, 0xffff0000, v252
	v_lshlrev_b32_e32 v220, 16, v253
	v_and_b32_e32 v221, 0xffff0000, v253
	v_cndmask_b32_e64 v206, v206, 0, s[40:41]
	v_cndmask_b32_e64 v207, v207, 0, s[40:41]
	v_cndmask_b32_e64 v208, v208, 0, s[40:41]
	v_cndmask_b32_e64 v209, v209, 0, s[40:41]
	v_cndmask_b32_e64 v210, v210, 0, s[40:41]
	v_cndmask_b32_e64 v211, v211, 0, s[40:41]
	v_cndmask_b32_e64 v212, v212, 0, s[40:41]
	v_cndmask_b32_e64 v213, v213, 0, s[40:41]
	v_cndmask_b32_e64 v214, v214, 0, s[40:41]
	v_cndmask_b32_e64 v215, v215, 0, s[40:41]
	v_cndmask_b32_e64 v216, v216, 0, s[40:41]
	v_cndmask_b32_e64 v217, v217, 0, s[40:41]
	v_cndmask_b32_e64 v218, v218, 0, s[40:41]
	v_cndmask_b32_e64 v219, v219, 0, s[40:41]
	v_cndmask_b32_e64 v220, v220, 0, s[40:41]
	v_cndmask_b32_e64 v221, v221, 0, s[40:41]
	v_cndmask_b32_e64 v222, v222, 0, s[40:41]
	v_cndmask_b32_e64 v223, v223, 0, s[40:41]
	v_cndmask_b32_e64 v224, v224, 0, s[40:41]
	v_cndmask_b32_e64 v225, v225, 0, s[40:41]
	v_cndmask_b32_e64 v226, v226, 0, s[40:41]
	v_cndmask_b32_e64 v227, v227, 0, s[40:41]
	v_cndmask_b32_e64 v228, v228, 0, s[40:41]
	v_cndmask_b32_e64 v229, v229, 0, s[40:41]
	v_cndmask_b32_e64 v230, v230, 0, s[40:41]
	v_cndmask_b32_e64 v231, v231, 0, s[40:41]
	v_cndmask_b32_e64 v232, v232, 0, s[40:41]
	v_cndmask_b32_e64 v233, v233, 0, s[40:41]
	v_cndmask_b32_e64 v234, v234, 0, s[40:41]
	v_cndmask_b32_e64 v235, v235, 0, s[40:41]
	v_cndmask_b32_e64 v236, v236, 0, s[40:41]
	v_cndmask_b32_e64 v237, v237, 0, s[40:41]
	v_lshlrev_b32_e32 v190, 16, v36
	v_and_b32_e32 v191, 0xffff0000, v36
	v_lshlrev_b32_e32 v192, 16, v37
	v_and_b32_e32 v193, 0xffff0000, v37
	v_lshlrev_b32_e32 v194, 16, v38
	v_and_b32_e32 v195, 0xffff0000, v38
	v_lshlrev_b32_e32 v196, 16, v39
	v_and_b32_e32 v197, 0xffff0000, v39
	v_lshlrev_b32_e32 v198, 16, v40
	v_and_b32_e32 v199, 0xffff0000, v40
	v_lshlrev_b32_e32 v200, 16, v41
	v_and_b32_e32 v201, 0xffff0000, v41
	v_lshlrev_b32_e32 v202, 16, v42
	v_and_b32_e32 v203, 0xffff0000, v42
	v_lshlrev_b32_e32 v204, 16, v43
	v_and_b32_e32 v205, 0xffff0000, v43
	v_pk_fma_f32 v[2:3], v[104:105], v[206:207], v[174:175]
	v_pk_fma_f32 v[4:5], v[106:107], v[208:209], v[176:177]
	v_pk_fma_f32 v[6:7], v[108:109], v[210:211], v[178:179]
	v_pk_fma_f32 v[8:9], v[110:111], v[212:213], v[180:181]
	v_pk_fma_f32 v[10:11], v[112:113], v[214:215], v[182:183]
	v_pk_fma_f32 v[12:13], v[114:115], v[216:217], v[184:185]
	v_pk_fma_f32 v[14:15], v[116:117], v[218:219], v[186:187]
	v_pk_fma_f32 v[16:17], v[118:119], v[220:221], v[188:189]
	v_pk_fma_f32 v[2:3], v[120:121], v[222:223], v[2:3]
	v_pk_fma_f32 v[4:5], v[122:123], v[224:225], v[4:5]
	v_pk_fma_f32 v[6:7], v[124:125], v[226:227], v[6:7]
	v_pk_fma_f32 v[8:9], v[126:127], v[228:229], v[8:9]
	v_pk_fma_f32 v[10:11], v[128:129], v[230:231], v[10:11]
	v_pk_fma_f32 v[12:13], v[130:131], v[232:233], v[12:13]
	v_pk_fma_f32 v[14:15], v[132:133], v[234:235], v[14:15]
	v_pk_fma_f32 v[16:17], v[134:135], v[236:237], v[16:17]
	v_pk_fma_f32 v[2:3], v[136:137], v[190:191], v[2:3]
	v_pk_fma_f32 v[4:5], v[138:139], v[192:193], v[4:5]
	v_pk_fma_f32 v[6:7], v[140:141], v[194:195], v[6:7]
	v_pk_fma_f32 v[8:9], v[142:143], v[196:197], v[8:9]
	v_pk_fma_f32 v[10:11], v[144:145], v[198:199], v[10:11]
	v_pk_fma_f32 v[12:13], v[146:147], v[200:201], v[12:13]
	v_pk_fma_f32 v[14:15], v[148:149], v[202:203], v[14:15]
	v_pk_fma_f32 v[16:17], v[150:151], v[204:205], v[16:17]
	v_mul_f32_e32 v18, 0xbfb8aa3b, v2
	v_mul_f32_e32 v19, 0xbfb8aa3b, v3
	v_mul_f32_e32 v20, 0xbfb8aa3b, v4
	v_mul_f32_e32 v21, 0xbfb8aa3b, v5
	v_mul_f32_e32 v22, 0xbfb8aa3b, v6
	v_mul_f32_e32 v23, 0xbfb8aa3b, v7
	v_mul_f32_e32 v24, 0xbfb8aa3b, v8
	v_mul_f32_e32 v25, 0xbfb8aa3b, v9
	v_exp_f32_e32 v18, v18
	v_exp_f32_e32 v19, v19
	v_exp_f32_e32 v20, v20
	v_exp_f32_e32 v21, v21
	v_exp_f32_e32 v22, v22
	v_exp_f32_e32 v23, v23
	v_exp_f32_e32 v24, v24
	v_exp_f32_e32 v25, v25
	v_add_f32_e32 v18, 1.0, v18
	v_add_f32_e32 v19, 1.0, v19
	v_add_f32_e32 v20, 1.0, v20
	v_add_f32_e32 v21, 1.0, v21
	v_add_f32_e32 v22, 1.0, v22
	v_add_f32_e32 v23, 1.0, v23
	v_add_f32_e32 v24, 1.0, v24
	v_add_f32_e32 v25, 1.0, v25
	v_rcp_f32_e32 v18, v18
	v_rcp_f32_e32 v19, v19
	v_rcp_f32_e32 v20, v20
	v_rcp_f32_e32 v21, v21
	v_rcp_f32_e32 v22, v22
	v_rcp_f32_e32 v23, v23
	v_rcp_f32_e32 v24, v24
	v_rcp_f32_e32 v25, v25
	v_mul_f32_e32 v18, v2, v18
	v_mul_f32_e32 v19, v3, v19
	v_mul_f32_e32 v20, v4, v20
	v_mul_f32_e32 v21, v5, v21
	v_mul_f32_e32 v22, v6, v22
	v_mul_f32_e32 v23, v7, v23
	v_mul_f32_e32 v24, v8, v24
	v_mul_f32_e32 v25, v9, v25
	v_mul_f32_e32 v18, v10, v18
	v_mul_f32_e32 v19, v11, v19
	v_mul_f32_e32 v20, v12, v20
	v_mul_f32_e32 v21, v13, v21
	v_mul_f32_e32 v22, v14, v22
	v_mul_f32_e32 v23, v15, v23
	v_mul_f32_e32 v24, v16, v24
	v_mul_f32_e32 v25, v17, v25
	v_cvt_pk_bf16_f32 v26, v18, v19
	v_cvt_pk_bf16_f32 v27, v20, v21
	v_cvt_pk_bf16_f32 v28, v22, v23
	v_cvt_pk_bf16_f32 v29, v24, v25
	global_store_dwordx4 v[162:163], v[26:29], off sc1
	v_lshl_add_u64 v[162:163], v[162:163], 0, v[30:31]
	v_lshlrev_b32_e32 v206, 16, v44
	v_and_b32_e32 v207, 0xffff0000, v44
	v_lshlrev_b32_e32 v208, 16, v45
	v_and_b32_e32 v209, 0xffff0000, v45
	v_lshlrev_b32_e32 v210, 16, v46
	v_and_b32_e32 v211, 0xffff0000, v46
	v_lshlrev_b32_e32 v212, 16, v47
	v_and_b32_e32 v213, 0xffff0000, v47
	v_lshlrev_b32_e32 v214, 16, v48
	v_and_b32_e32 v215, 0xffff0000, v48
	v_lshlrev_b32_e32 v216, 16, v49
	v_and_b32_e32 v217, 0xffff0000, v49
	v_lshlrev_b32_e32 v218, 16, v50
	v_and_b32_e32 v219, 0xffff0000, v50
	v_lshlrev_b32_e32 v220, 16, v51
	v_and_b32_e32 v221, 0xffff0000, v51
	v_pk_fma_f32 v[2:3], v[104:105], v[222:223], v[174:175]
	v_pk_fma_f32 v[4:5], v[106:107], v[224:225], v[176:177]
	v_pk_fma_f32 v[6:7], v[108:109], v[226:227], v[178:179]
	v_pk_fma_f32 v[8:9], v[110:111], v[228:229], v[180:181]
	v_pk_fma_f32 v[10:11], v[112:113], v[230:231], v[182:183]
	v_pk_fma_f32 v[12:13], v[114:115], v[232:233], v[184:185]
	v_pk_fma_f32 v[14:15], v[116:117], v[234:235], v[186:187]
	v_pk_fma_f32 v[16:17], v[118:119], v[236:237], v[188:189]
	v_pk_fma_f32 v[2:3], v[120:121], v[190:191], v[2:3]
	v_pk_fma_f32 v[4:5], v[122:123], v[192:193], v[4:5]
	v_pk_fma_f32 v[6:7], v[124:125], v[194:195], v[6:7]
	v_pk_fma_f32 v[8:9], v[126:127], v[196:197], v[8:9]
	v_pk_fma_f32 v[10:11], v[128:129], v[198:199], v[10:11]
	v_pk_fma_f32 v[12:13], v[130:131], v[200:201], v[12:13]
	v_pk_fma_f32 v[14:15], v[132:133], v[202:203], v[14:15]
	v_pk_fma_f32 v[16:17], v[134:135], v[204:205], v[16:17]
	v_pk_fma_f32 v[2:3], v[136:137], v[206:207], v[2:3]
	v_pk_fma_f32 v[4:5], v[138:139], v[208:209], v[4:5]
	v_pk_fma_f32 v[6:7], v[140:141], v[210:211], v[6:7]
	v_pk_fma_f32 v[8:9], v[142:143], v[212:213], v[8:9]
	v_pk_fma_f32 v[10:11], v[144:145], v[214:215], v[10:11]
	v_pk_fma_f32 v[12:13], v[146:147], v[216:217], v[12:13]
	v_pk_fma_f32 v[14:15], v[148:149], v[218:219], v[14:15]
	v_pk_fma_f32 v[16:17], v[150:151], v[220:221], v[16:17]
	v_mul_f32_e32 v18, 0xbfb8aa3b, v2
	v_mul_f32_e32 v19, 0xbfb8aa3b, v3
	v_mul_f32_e32 v20, 0xbfb8aa3b, v4
	v_mul_f32_e32 v21, 0xbfb8aa3b, v5
	v_mul_f32_e32 v22, 0xbfb8aa3b, v6
	v_mul_f32_e32 v23, 0xbfb8aa3b, v7
	v_mul_f32_e32 v24, 0xbfb8aa3b, v8
	v_mul_f32_e32 v25, 0xbfb8aa3b, v9
	v_exp_f32_e32 v18, v18
	v_exp_f32_e32 v19, v19
	v_exp_f32_e32 v20, v20
	v_exp_f32_e32 v21, v21
	v_exp_f32_e32 v22, v22
	v_exp_f32_e32 v23, v23
	v_exp_f32_e32 v24, v24
	v_exp_f32_e32 v25, v25
	v_add_f32_e32 v18, 1.0, v18
	v_add_f32_e32 v19, 1.0, v19
	v_add_f32_e32 v20, 1.0, v20
	v_add_f32_e32 v21, 1.0, v21
	v_add_f32_e32 v22, 1.0, v22
	v_add_f32_e32 v23, 1.0, v23
	v_add_f32_e32 v24, 1.0, v24
	v_add_f32_e32 v25, 1.0, v25
	v_rcp_f32_e32 v18, v18
	v_rcp_f32_e32 v19, v19
	v_rcp_f32_e32 v20, v20
	v_rcp_f32_e32 v21, v21
	v_rcp_f32_e32 v22, v22
	v_rcp_f32_e32 v23, v23
	v_rcp_f32_e32 v24, v24
	v_rcp_f32_e32 v25, v25
	v_mul_f32_e32 v18, v2, v18
	v_mul_f32_e32 v19, v3, v19
	v_mul_f32_e32 v20, v4, v20
	v_mul_f32_e32 v21, v5, v21
	v_mul_f32_e32 v22, v6, v22
	v_mul_f32_e32 v23, v7, v23
	v_mul_f32_e32 v24, v8, v24
	v_mul_f32_e32 v25, v9, v25
	v_mul_f32_e32 v18, v10, v18
	v_mul_f32_e32 v19, v11, v19
	v_mul_f32_e32 v20, v12, v20
	v_mul_f32_e32 v21, v13, v21
	v_mul_f32_e32 v22, v14, v22
	v_mul_f32_e32 v23, v15, v23
	v_mul_f32_e32 v24, v16, v24
	v_mul_f32_e32 v25, v17, v25
	v_cvt_pk_bf16_f32 v26, v18, v19
	v_cvt_pk_bf16_f32 v27, v20, v21
	v_cvt_pk_bf16_f32 v28, v22, v23
	v_cvt_pk_bf16_f32 v29, v24, v25
	global_store_dwordx4 v[162:163], v[26:29], off sc1
	v_lshl_add_u64 v[162:163], v[162:163], 0, v[30:31]
	v_lshlrev_b32_e32 v222, 16, v52
	v_and_b32_e32 v223, 0xffff0000, v52
	v_lshlrev_b32_e32 v224, 16, v53
	v_and_b32_e32 v225, 0xffff0000, v53
	v_lshlrev_b32_e32 v226, 16, v54
	v_and_b32_e32 v227, 0xffff0000, v54
	v_lshlrev_b32_e32 v228, 16, v55
	v_and_b32_e32 v229, 0xffff0000, v55
	v_lshlrev_b32_e32 v230, 16, v56
	v_and_b32_e32 v231, 0xffff0000, v56
	v_lshlrev_b32_e32 v232, 16, v57
	v_and_b32_e32 v233, 0xffff0000, v57
	v_lshlrev_b32_e32 v234, 16, v58
	v_and_b32_e32 v235, 0xffff0000, v58
	v_lshlrev_b32_e32 v236, 16, v59
	v_and_b32_e32 v237, 0xffff0000, v59
	v_pk_fma_f32 v[2:3], v[104:105], v[190:191], v[174:175]
	v_pk_fma_f32 v[4:5], v[106:107], v[192:193], v[176:177]
	v_pk_fma_f32 v[6:7], v[108:109], v[194:195], v[178:179]
	v_pk_fma_f32 v[8:9], v[110:111], v[196:197], v[180:181]
	v_pk_fma_f32 v[10:11], v[112:113], v[198:199], v[182:183]
	v_pk_fma_f32 v[12:13], v[114:115], v[200:201], v[184:185]
	v_pk_fma_f32 v[14:15], v[116:117], v[202:203], v[186:187]
	v_pk_fma_f32 v[16:17], v[118:119], v[204:205], v[188:189]
	v_pk_fma_f32 v[2:3], v[120:121], v[206:207], v[2:3]
	v_pk_fma_f32 v[4:5], v[122:123], v[208:209], v[4:5]
	v_pk_fma_f32 v[6:7], v[124:125], v[210:211], v[6:7]
	v_pk_fma_f32 v[8:9], v[126:127], v[212:213], v[8:9]
	v_pk_fma_f32 v[10:11], v[128:129], v[214:215], v[10:11]
	v_pk_fma_f32 v[12:13], v[130:131], v[216:217], v[12:13]
	v_pk_fma_f32 v[14:15], v[132:133], v[218:219], v[14:15]
	v_pk_fma_f32 v[16:17], v[134:135], v[220:221], v[16:17]
	v_pk_fma_f32 v[2:3], v[136:137], v[222:223], v[2:3]
	v_pk_fma_f32 v[4:5], v[138:139], v[224:225], v[4:5]
	v_pk_fma_f32 v[6:7], v[140:141], v[226:227], v[6:7]
	v_pk_fma_f32 v[8:9], v[142:143], v[228:229], v[8:9]
	v_pk_fma_f32 v[10:11], v[144:145], v[230:231], v[10:11]
	v_pk_fma_f32 v[12:13], v[146:147], v[232:233], v[12:13]
	v_pk_fma_f32 v[14:15], v[148:149], v[234:235], v[14:15]
	v_pk_fma_f32 v[16:17], v[150:151], v[236:237], v[16:17]
	v_mul_f32_e32 v18, 0xbfb8aa3b, v2
	v_mul_f32_e32 v19, 0xbfb8aa3b, v3
	v_mul_f32_e32 v20, 0xbfb8aa3b, v4
	v_mul_f32_e32 v21, 0xbfb8aa3b, v5
	v_mul_f32_e32 v22, 0xbfb8aa3b, v6
	v_mul_f32_e32 v23, 0xbfb8aa3b, v7
	v_mul_f32_e32 v24, 0xbfb8aa3b, v8
	v_mul_f32_e32 v25, 0xbfb8aa3b, v9
	v_exp_f32_e32 v18, v18
	v_exp_f32_e32 v19, v19
	v_exp_f32_e32 v20, v20
	v_exp_f32_e32 v21, v21
	v_exp_f32_e32 v22, v22
	v_exp_f32_e32 v23, v23
	v_exp_f32_e32 v24, v24
	v_exp_f32_e32 v25, v25
	v_add_f32_e32 v18, 1.0, v18
	v_add_f32_e32 v19, 1.0, v19
	v_add_f32_e32 v20, 1.0, v20
	v_add_f32_e32 v21, 1.0, v21
	v_add_f32_e32 v22, 1.0, v22
	v_add_f32_e32 v23, 1.0, v23
	v_add_f32_e32 v24, 1.0, v24
	v_add_f32_e32 v25, 1.0, v25
	v_rcp_f32_e32 v18, v18
	v_rcp_f32_e32 v19, v19
	v_rcp_f32_e32 v20, v20
	v_rcp_f32_e32 v21, v21
	v_rcp_f32_e32 v22, v22
	v_rcp_f32_e32 v23, v23
	v_rcp_f32_e32 v24, v24
	v_rcp_f32_e32 v25, v25
	v_mul_f32_e32 v18, v2, v18
	v_mul_f32_e32 v19, v3, v19
	v_mul_f32_e32 v20, v4, v20
	v_mul_f32_e32 v21, v5, v21
	v_mul_f32_e32 v22, v6, v22
	v_mul_f32_e32 v23, v7, v23
	v_mul_f32_e32 v24, v8, v24
	v_mul_f32_e32 v25, v9, v25
	v_mul_f32_e32 v18, v10, v18
	v_mul_f32_e32 v19, v11, v19
	v_mul_f32_e32 v20, v12, v20
	v_mul_f32_e32 v21, v13, v21
	v_mul_f32_e32 v22, v14, v22
	v_mul_f32_e32 v23, v15, v23
	v_mul_f32_e32 v24, v16, v24
	v_mul_f32_e32 v25, v17, v25
	v_cvt_pk_bf16_f32 v26, v18, v19
	v_cvt_pk_bf16_f32 v27, v20, v21
	v_cvt_pk_bf16_f32 v28, v22, v23
	v_cvt_pk_bf16_f32 v29, v24, v25
	global_store_dwordx4 v[162:163], v[26:29], off sc1
	v_lshl_add_u64 v[162:163], v[162:163], 0, v[30:31]
	v_lshlrev_b32_e32 v190, 16, v60
	v_and_b32_e32 v191, 0xffff0000, v60
	v_lshlrev_b32_e32 v192, 16, v61
	v_and_b32_e32 v193, 0xffff0000, v61
	v_lshlrev_b32_e32 v194, 16, v62
	v_and_b32_e32 v195, 0xffff0000, v62
	v_lshlrev_b32_e32 v196, 16, v63
	v_and_b32_e32 v197, 0xffff0000, v63
	v_lshlrev_b32_e32 v198, 16, v64
	v_and_b32_e32 v199, 0xffff0000, v64
	v_lshlrev_b32_e32 v200, 16, v65
	v_and_b32_e32 v201, 0xffff0000, v65
	v_lshlrev_b32_e32 v202, 16, v66
	v_and_b32_e32 v203, 0xffff0000, v66
	v_lshlrev_b32_e32 v204, 16, v67
	v_and_b32_e32 v205, 0xffff0000, v67
	v_pk_fma_f32 v[2:3], v[104:105], v[206:207], v[174:175]
	v_pk_fma_f32 v[4:5], v[106:107], v[208:209], v[176:177]
	v_pk_fma_f32 v[6:7], v[108:109], v[210:211], v[178:179]
	v_pk_fma_f32 v[8:9], v[110:111], v[212:213], v[180:181]
	v_pk_fma_f32 v[10:11], v[112:113], v[214:215], v[182:183]
	v_pk_fma_f32 v[12:13], v[114:115], v[216:217], v[184:185]
	v_pk_fma_f32 v[14:15], v[116:117], v[218:219], v[186:187]
	v_pk_fma_f32 v[16:17], v[118:119], v[220:221], v[188:189]
	v_pk_fma_f32 v[2:3], v[120:121], v[222:223], v[2:3]
	v_pk_fma_f32 v[4:5], v[122:123], v[224:225], v[4:5]
	v_pk_fma_f32 v[6:7], v[124:125], v[226:227], v[6:7]
	v_pk_fma_f32 v[8:9], v[126:127], v[228:229], v[8:9]
	v_pk_fma_f32 v[10:11], v[128:129], v[230:231], v[10:11]
	v_pk_fma_f32 v[12:13], v[130:131], v[232:233], v[12:13]
	v_pk_fma_f32 v[14:15], v[132:133], v[234:235], v[14:15]
	v_pk_fma_f32 v[16:17], v[134:135], v[236:237], v[16:17]
	v_pk_fma_f32 v[2:3], v[136:137], v[190:191], v[2:3]
	v_pk_fma_f32 v[4:5], v[138:139], v[192:193], v[4:5]
	v_pk_fma_f32 v[6:7], v[140:141], v[194:195], v[6:7]
	v_pk_fma_f32 v[8:9], v[142:143], v[196:197], v[8:9]
	v_pk_fma_f32 v[10:11], v[144:145], v[198:199], v[10:11]
	v_pk_fma_f32 v[12:13], v[146:147], v[200:201], v[12:13]
	v_pk_fma_f32 v[14:15], v[148:149], v[202:203], v[14:15]
	v_pk_fma_f32 v[16:17], v[150:151], v[204:205], v[16:17]
	v_mul_f32_e32 v18, 0xbfb8aa3b, v2
	v_mul_f32_e32 v19, 0xbfb8aa3b, v3
	v_mul_f32_e32 v20, 0xbfb8aa3b, v4
	v_mul_f32_e32 v21, 0xbfb8aa3b, v5
	v_mul_f32_e32 v22, 0xbfb8aa3b, v6
	v_mul_f32_e32 v23, 0xbfb8aa3b, v7
	v_mul_f32_e32 v24, 0xbfb8aa3b, v8
	v_mul_f32_e32 v25, 0xbfb8aa3b, v9
	v_exp_f32_e32 v18, v18
	v_exp_f32_e32 v19, v19
	v_exp_f32_e32 v20, v20
	v_exp_f32_e32 v21, v21
	v_exp_f32_e32 v22, v22
	v_exp_f32_e32 v23, v23
	v_exp_f32_e32 v24, v24
	v_exp_f32_e32 v25, v25
	v_add_f32_e32 v18, 1.0, v18
	v_add_f32_e32 v19, 1.0, v19
	v_add_f32_e32 v20, 1.0, v20
	v_add_f32_e32 v21, 1.0, v21
	v_add_f32_e32 v22, 1.0, v22
	v_add_f32_e32 v23, 1.0, v23
	v_add_f32_e32 v24, 1.0, v24
	v_add_f32_e32 v25, 1.0, v25
	v_rcp_f32_e32 v18, v18
	v_rcp_f32_e32 v19, v19
	v_rcp_f32_e32 v20, v20
	v_rcp_f32_e32 v21, v21
	v_rcp_f32_e32 v22, v22
	v_rcp_f32_e32 v23, v23
	v_rcp_f32_e32 v24, v24
	v_rcp_f32_e32 v25, v25
	v_mul_f32_e32 v18, v2, v18
	v_mul_f32_e32 v19, v3, v19
	v_mul_f32_e32 v20, v4, v20
	v_mul_f32_e32 v21, v5, v21
	v_mul_f32_e32 v22, v6, v22
	v_mul_f32_e32 v23, v7, v23
	v_mul_f32_e32 v24, v8, v24
	v_mul_f32_e32 v25, v9, v25
	v_mul_f32_e32 v18, v10, v18
	v_mul_f32_e32 v19, v11, v19
	v_mul_f32_e32 v20, v12, v20
	v_mul_f32_e32 v21, v13, v21
	v_mul_f32_e32 v22, v14, v22
	v_mul_f32_e32 v23, v15, v23
	v_mul_f32_e32 v24, v16, v24
	v_mul_f32_e32 v25, v17, v25
	v_cvt_pk_bf16_f32 v26, v18, v19
	v_cvt_pk_bf16_f32 v27, v20, v21
	v_cvt_pk_bf16_f32 v28, v22, v23
	v_cvt_pk_bf16_f32 v29, v24, v25
	global_store_dwordx4 v[162:163], v[26:29], off sc1
	v_lshl_add_u64 v[162:163], v[162:163], 0, v[30:31]
	global_load_dwordx4 v[36:39], v[158:159], off nt
	global_load_dwordx4 v[40:43], v[160:161], off nt
	v_lshl_add_u64 v[158:159], v[158:159], 0, v[164:165]
	v_lshl_add_u64 v[160:161], v[160:161], 0, v[164:165]
	global_load_dwordx4 v[44:47], v[158:159], off nt
	global_load_dwordx4 v[48:51], v[160:161], off nt
	v_lshl_add_u64 v[158:159], v[158:159], 0, v[164:165]
	v_lshl_add_u64 v[160:161], v[160:161], 0, v[164:165]
	global_load_dwordx4 v[52:55], v[158:159], off nt
	global_load_dwordx4 v[56:59], v[160:161], off nt
	v_lshl_add_u64 v[158:159], v[158:159], 0, v[164:165]
	v_lshl_add_u64 v[160:161], v[160:161], 0, v[164:165]
	global_load_dwordx4 v[60:63], v[158:159], off nt
	global_load_dwordx4 v[64:67], v[160:161], off nt
	v_lshl_add_u64 v[158:159], v[158:159], 0, v[164:165]
	v_lshl_add_u64 v[160:161], v[160:161], 0, v[164:165]
	s_waitcnt vmcnt(12)
	v_lshlrev_b32_e32 v206, 16, v68
	v_and_b32_e32 v207, 0xffff0000, v68
	v_lshlrev_b32_e32 v208, 16, v69
	v_and_b32_e32 v209, 0xffff0000, v69
	v_lshlrev_b32_e32 v210, 16, v70
	v_and_b32_e32 v211, 0xffff0000, v70
	v_lshlrev_b32_e32 v212, 16, v71
	v_and_b32_e32 v213, 0xffff0000, v71
	v_lshlrev_b32_e32 v214, 16, v72
	v_and_b32_e32 v215, 0xffff0000, v72
	v_lshlrev_b32_e32 v216, 16, v73
	v_and_b32_e32 v217, 0xffff0000, v73
	v_lshlrev_b32_e32 v218, 16, v74
	v_and_b32_e32 v219, 0xffff0000, v74
	v_lshlrev_b32_e32 v220, 16, v75
	v_and_b32_e32 v221, 0xffff0000, v75
	v_pk_fma_f32 v[2:3], v[104:105], v[222:223], v[174:175]
	v_pk_fma_f32 v[4:5], v[106:107], v[224:225], v[176:177]
	v_pk_fma_f32 v[6:7], v[108:109], v[226:227], v[178:179]
	v_pk_fma_f32 v[8:9], v[110:111], v[228:229], v[180:181]
	v_pk_fma_f32 v[10:11], v[112:113], v[230:231], v[182:183]
	v_pk_fma_f32 v[12:13], v[114:115], v[232:233], v[184:185]
	v_pk_fma_f32 v[14:15], v[116:117], v[234:235], v[186:187]
	v_pk_fma_f32 v[16:17], v[118:119], v[236:237], v[188:189]
	v_pk_fma_f32 v[2:3], v[120:121], v[190:191], v[2:3]
	v_pk_fma_f32 v[4:5], v[122:123], v[192:193], v[4:5]
	v_pk_fma_f32 v[6:7], v[124:125], v[194:195], v[6:7]
	v_pk_fma_f32 v[8:9], v[126:127], v[196:197], v[8:9]
	v_pk_fma_f32 v[10:11], v[128:129], v[198:199], v[10:11]
	v_pk_fma_f32 v[12:13], v[130:131], v[200:201], v[12:13]
	v_pk_fma_f32 v[14:15], v[132:133], v[202:203], v[14:15]
	v_pk_fma_f32 v[16:17], v[134:135], v[204:205], v[16:17]
	v_pk_fma_f32 v[2:3], v[136:137], v[206:207], v[2:3]
	v_pk_fma_f32 v[4:5], v[138:139], v[208:209], v[4:5]
	v_pk_fma_f32 v[6:7], v[140:141], v[210:211], v[6:7]
	v_pk_fma_f32 v[8:9], v[142:143], v[212:213], v[8:9]
	v_pk_fma_f32 v[10:11], v[144:145], v[214:215], v[10:11]
	v_pk_fma_f32 v[12:13], v[146:147], v[216:217], v[12:13]
	v_pk_fma_f32 v[14:15], v[148:149], v[218:219], v[14:15]
	v_pk_fma_f32 v[16:17], v[150:151], v[220:221], v[16:17]
	v_mul_f32_e32 v18, 0xbfb8aa3b, v2
	v_mul_f32_e32 v19, 0xbfb8aa3b, v3
	v_mul_f32_e32 v20, 0xbfb8aa3b, v4
	v_mul_f32_e32 v21, 0xbfb8aa3b, v5
	v_mul_f32_e32 v22, 0xbfb8aa3b, v6
	v_mul_f32_e32 v23, 0xbfb8aa3b, v7
	v_mul_f32_e32 v24, 0xbfb8aa3b, v8
	v_mul_f32_e32 v25, 0xbfb8aa3b, v9
	v_exp_f32_e32 v18, v18
	v_exp_f32_e32 v19, v19
	v_exp_f32_e32 v20, v20
	v_exp_f32_e32 v21, v21
	v_exp_f32_e32 v22, v22
	v_exp_f32_e32 v23, v23
	v_exp_f32_e32 v24, v24
	v_exp_f32_e32 v25, v25
	v_add_f32_e32 v18, 1.0, v18
	v_add_f32_e32 v19, 1.0, v19
	v_add_f32_e32 v20, 1.0, v20
	v_add_f32_e32 v21, 1.0, v21
	v_add_f32_e32 v22, 1.0, v22
	v_add_f32_e32 v23, 1.0, v23
	v_add_f32_e32 v24, 1.0, v24
	v_add_f32_e32 v25, 1.0, v25
	v_rcp_f32_e32 v18, v18
	v_rcp_f32_e32 v19, v19
	v_rcp_f32_e32 v20, v20
	v_rcp_f32_e32 v21, v21
	v_rcp_f32_e32 v22, v22
	v_rcp_f32_e32 v23, v23
	v_rcp_f32_e32 v24, v24
	v_rcp_f32_e32 v25, v25
	v_mul_f32_e32 v18, v2, v18
	v_mul_f32_e32 v19, v3, v19
	v_mul_f32_e32 v20, v4, v20
	v_mul_f32_e32 v21, v5, v21
	v_mul_f32_e32 v22, v6, v22
	v_mul_f32_e32 v23, v7, v23
	v_mul_f32_e32 v24, v8, v24
	v_mul_f32_e32 v25, v9, v25
	v_mul_f32_e32 v18, v10, v18
	v_mul_f32_e32 v19, v11, v19
	v_mul_f32_e32 v20, v12, v20
	v_mul_f32_e32 v21, v13, v21
	v_mul_f32_e32 v22, v14, v22
	v_mul_f32_e32 v23, v15, v23
	v_mul_f32_e32 v24, v16, v24
	v_mul_f32_e32 v25, v17, v25
	v_cvt_pk_bf16_f32 v26, v18, v19
	v_cvt_pk_bf16_f32 v27, v20, v21
	v_cvt_pk_bf16_f32 v28, v22, v23
	v_cvt_pk_bf16_f32 v29, v24, v25
	global_store_dwordx4 v[162:163], v[26:29], off sc1
	v_lshl_add_u64 v[162:163], v[162:163], 0, v[30:31]
	v_lshlrev_b32_e32 v222, 16, v76
	v_and_b32_e32 v223, 0xffff0000, v76
	v_lshlrev_b32_e32 v224, 16, v77
	v_and_b32_e32 v225, 0xffff0000, v77
	v_lshlrev_b32_e32 v226, 16, v78
	v_and_b32_e32 v227, 0xffff0000, v78
	v_lshlrev_b32_e32 v228, 16, v79
	v_and_b32_e32 v229, 0xffff0000, v79
	v_lshlrev_b32_e32 v230, 16, v80
	v_and_b32_e32 v231, 0xffff0000, v80
	v_lshlrev_b32_e32 v232, 16, v81
	v_and_b32_e32 v233, 0xffff0000, v81
	v_lshlrev_b32_e32 v234, 16, v82
	v_and_b32_e32 v235, 0xffff0000, v82
	v_lshlrev_b32_e32 v236, 16, v83
	v_and_b32_e32 v237, 0xffff0000, v83
	v_pk_fma_f32 v[2:3], v[104:105], v[190:191], v[174:175]
	v_pk_fma_f32 v[4:5], v[106:107], v[192:193], v[176:177]
	v_pk_fma_f32 v[6:7], v[108:109], v[194:195], v[178:179]
	v_pk_fma_f32 v[8:9], v[110:111], v[196:197], v[180:181]
	v_pk_fma_f32 v[10:11], v[112:113], v[198:199], v[182:183]
	v_pk_fma_f32 v[12:13], v[114:115], v[200:201], v[184:185]
	v_pk_fma_f32 v[14:15], v[116:117], v[202:203], v[186:187]
	v_pk_fma_f32 v[16:17], v[118:119], v[204:205], v[188:189]
	v_pk_fma_f32 v[2:3], v[120:121], v[206:207], v[2:3]
	v_pk_fma_f32 v[4:5], v[122:123], v[208:209], v[4:5]
	v_pk_fma_f32 v[6:7], v[124:125], v[210:211], v[6:7]
	v_pk_fma_f32 v[8:9], v[126:127], v[212:213], v[8:9]
	v_pk_fma_f32 v[10:11], v[128:129], v[214:215], v[10:11]
	v_pk_fma_f32 v[12:13], v[130:131], v[216:217], v[12:13]
	v_pk_fma_f32 v[14:15], v[132:133], v[218:219], v[14:15]
	v_pk_fma_f32 v[16:17], v[134:135], v[220:221], v[16:17]
	v_pk_fma_f32 v[2:3], v[136:137], v[222:223], v[2:3]
	v_pk_fma_f32 v[4:5], v[138:139], v[224:225], v[4:5]
	v_pk_fma_f32 v[6:7], v[140:141], v[226:227], v[6:7]
	v_pk_fma_f32 v[8:9], v[142:143], v[228:229], v[8:9]
	v_pk_fma_f32 v[10:11], v[144:145], v[230:231], v[10:11]
	v_pk_fma_f32 v[12:13], v[146:147], v[232:233], v[12:13]
	v_pk_fma_f32 v[14:15], v[148:149], v[234:235], v[14:15]
	v_pk_fma_f32 v[16:17], v[150:151], v[236:237], v[16:17]
	v_mul_f32_e32 v18, 0xbfb8aa3b, v2
	v_mul_f32_e32 v19, 0xbfb8aa3b, v3
	v_mul_f32_e32 v20, 0xbfb8aa3b, v4
	v_mul_f32_e32 v21, 0xbfb8aa3b, v5
	v_mul_f32_e32 v22, 0xbfb8aa3b, v6
	v_mul_f32_e32 v23, 0xbfb8aa3b, v7
	v_mul_f32_e32 v24, 0xbfb8aa3b, v8
	v_mul_f32_e32 v25, 0xbfb8aa3b, v9
	v_exp_f32_e32 v18, v18
	v_exp_f32_e32 v19, v19
	v_exp_f32_e32 v20, v20
	v_exp_f32_e32 v21, v21
	v_exp_f32_e32 v22, v22
	v_exp_f32_e32 v23, v23
	v_exp_f32_e32 v24, v24
	v_exp_f32_e32 v25, v25
	v_add_f32_e32 v18, 1.0, v18
	v_add_f32_e32 v19, 1.0, v19
	v_add_f32_e32 v20, 1.0, v20
	v_add_f32_e32 v21, 1.0, v21
	v_add_f32_e32 v22, 1.0, v22
	v_add_f32_e32 v23, 1.0, v23
	v_add_f32_e32 v24, 1.0, v24
	v_add_f32_e32 v25, 1.0, v25
	v_rcp_f32_e32 v18, v18
	v_rcp_f32_e32 v19, v19
	v_rcp_f32_e32 v20, v20
	v_rcp_f32_e32 v21, v21
	v_rcp_f32_e32 v22, v22
	v_rcp_f32_e32 v23, v23
	v_rcp_f32_e32 v24, v24
	v_rcp_f32_e32 v25, v25
	v_mul_f32_e32 v18, v2, v18
	v_mul_f32_e32 v19, v3, v19
	v_mul_f32_e32 v20, v4, v20
	v_mul_f32_e32 v21, v5, v21
	v_mul_f32_e32 v22, v6, v22
	v_mul_f32_e32 v23, v7, v23
	v_mul_f32_e32 v24, v8, v24
	v_mul_f32_e32 v25, v9, v25
	v_mul_f32_e32 v18, v10, v18
	v_mul_f32_e32 v19, v11, v19
	v_mul_f32_e32 v20, v12, v20
	v_mul_f32_e32 v21, v13, v21
	v_mul_f32_e32 v22, v14, v22
	v_mul_f32_e32 v23, v15, v23
	v_mul_f32_e32 v24, v16, v24
	v_mul_f32_e32 v25, v17, v25
	v_cvt_pk_bf16_f32 v26, v18, v19
	v_cvt_pk_bf16_f32 v27, v20, v21
	v_cvt_pk_bf16_f32 v28, v22, v23
	v_cvt_pk_bf16_f32 v29, v24, v25
	global_store_dwordx4 v[162:163], v[26:29], off sc1
	v_lshl_add_u64 v[162:163], v[162:163], 0, v[30:31]
	v_lshlrev_b32_e32 v190, 16, v88
	v_and_b32_e32 v191, 0xffff0000, v88
	v_lshlrev_b32_e32 v192, 16, v89
	v_and_b32_e32 v193, 0xffff0000, v89
	v_lshlrev_b32_e32 v194, 16, v90
	v_and_b32_e32 v195, 0xffff0000, v90
	v_lshlrev_b32_e32 v196, 16, v91
	v_and_b32_e32 v197, 0xffff0000, v91
	v_lshlrev_b32_e32 v198, 16, v92
	v_and_b32_e32 v199, 0xffff0000, v92
	v_lshlrev_b32_e32 v200, 16, v93
	v_and_b32_e32 v201, 0xffff0000, v93
	v_lshlrev_b32_e32 v202, 16, v94
	v_and_b32_e32 v203, 0xffff0000, v94
	v_lshlrev_b32_e32 v204, 16, v95
	v_and_b32_e32 v205, 0xffff0000, v95
	v_pk_fma_f32 v[2:3], v[104:105], v[206:207], v[174:175]
	v_pk_fma_f32 v[4:5], v[106:107], v[208:209], v[176:177]
	v_pk_fma_f32 v[6:7], v[108:109], v[210:211], v[178:179]
	v_pk_fma_f32 v[8:9], v[110:111], v[212:213], v[180:181]
	v_pk_fma_f32 v[10:11], v[112:113], v[214:215], v[182:183]
	v_pk_fma_f32 v[12:13], v[114:115], v[216:217], v[184:185]
	v_pk_fma_f32 v[14:15], v[116:117], v[218:219], v[186:187]
	v_pk_fma_f32 v[16:17], v[118:119], v[220:221], v[188:189]
	v_pk_fma_f32 v[2:3], v[120:121], v[222:223], v[2:3]
	v_pk_fma_f32 v[4:5], v[122:123], v[224:225], v[4:5]
	v_pk_fma_f32 v[6:7], v[124:125], v[226:227], v[6:7]
	v_pk_fma_f32 v[8:9], v[126:127], v[228:229], v[8:9]
	v_pk_fma_f32 v[10:11], v[128:129], v[230:231], v[10:11]
	v_pk_fma_f32 v[12:13], v[130:131], v[232:233], v[12:13]
	v_pk_fma_f32 v[14:15], v[132:133], v[234:235], v[14:15]
	v_pk_fma_f32 v[16:17], v[134:135], v[236:237], v[16:17]
	v_pk_fma_f32 v[2:3], v[136:137], v[190:191], v[2:3]
	v_pk_fma_f32 v[4:5], v[138:139], v[192:193], v[4:5]
	v_pk_fma_f32 v[6:7], v[140:141], v[194:195], v[6:7]
	v_pk_fma_f32 v[8:9], v[142:143], v[196:197], v[8:9]
	v_pk_fma_f32 v[10:11], v[144:145], v[198:199], v[10:11]
	v_pk_fma_f32 v[12:13], v[146:147], v[200:201], v[12:13]
	v_pk_fma_f32 v[14:15], v[148:149], v[202:203], v[14:15]
	v_pk_fma_f32 v[16:17], v[150:151], v[204:205], v[16:17]
	v_mul_f32_e32 v18, 0xbfb8aa3b, v2
	v_mul_f32_e32 v19, 0xbfb8aa3b, v3
	v_mul_f32_e32 v20, 0xbfb8aa3b, v4
	v_mul_f32_e32 v21, 0xbfb8aa3b, v5
	v_mul_f32_e32 v22, 0xbfb8aa3b, v6
	v_mul_f32_e32 v23, 0xbfb8aa3b, v7
	v_mul_f32_e32 v24, 0xbfb8aa3b, v8
	v_mul_f32_e32 v25, 0xbfb8aa3b, v9
	v_exp_f32_e32 v18, v18
	v_exp_f32_e32 v19, v19
	v_exp_f32_e32 v20, v20
	v_exp_f32_e32 v21, v21
	v_exp_f32_e32 v22, v22
	v_exp_f32_e32 v23, v23
	v_exp_f32_e32 v24, v24
	v_exp_f32_e32 v25, v25
	v_add_f32_e32 v18, 1.0, v18
	v_add_f32_e32 v19, 1.0, v19
	v_add_f32_e32 v20, 1.0, v20
	v_add_f32_e32 v21, 1.0, v21
	v_add_f32_e32 v22, 1.0, v22
	v_add_f32_e32 v23, 1.0, v23
	v_add_f32_e32 v24, 1.0, v24
	v_add_f32_e32 v25, 1.0, v25
	v_rcp_f32_e32 v18, v18
	v_rcp_f32_e32 v19, v19
	v_rcp_f32_e32 v20, v20
	v_rcp_f32_e32 v21, v21
	v_rcp_f32_e32 v22, v22
	v_rcp_f32_e32 v23, v23
	v_rcp_f32_e32 v24, v24
	v_rcp_f32_e32 v25, v25
	v_mul_f32_e32 v18, v2, v18
	v_mul_f32_e32 v19, v3, v19
	v_mul_f32_e32 v20, v4, v20
	v_mul_f32_e32 v21, v5, v21
	v_mul_f32_e32 v22, v6, v22
	v_mul_f32_e32 v23, v7, v23
	v_mul_f32_e32 v24, v8, v24
	v_mul_f32_e32 v25, v9, v25
	v_mul_f32_e32 v18, v10, v18
	v_mul_f32_e32 v19, v11, v19
	v_mul_f32_e32 v20, v12, v20
	v_mul_f32_e32 v21, v13, v21
	v_mul_f32_e32 v22, v14, v22
	v_mul_f32_e32 v23, v15, v23
	v_mul_f32_e32 v24, v16, v24
	v_mul_f32_e32 v25, v17, v25
	v_cvt_pk_bf16_f32 v26, v18, v19
	v_cvt_pk_bf16_f32 v27, v20, v21
	v_cvt_pk_bf16_f32 v28, v22, v23
	v_cvt_pk_bf16_f32 v29, v24, v25
	global_store_dwordx4 v[162:163], v[26:29], off sc1
	v_lshl_add_u64 v[162:163], v[162:163], 0, v[30:31]
	v_lshlrev_b32_e32 v206, 16, v96
	v_and_b32_e32 v207, 0xffff0000, v96
	v_lshlrev_b32_e32 v208, 16, v97
	v_and_b32_e32 v209, 0xffff0000, v97
	v_lshlrev_b32_e32 v210, 16, v98
	v_and_b32_e32 v211, 0xffff0000, v98
	v_lshlrev_b32_e32 v212, 16, v99
	v_and_b32_e32 v213, 0xffff0000, v99
	v_lshlrev_b32_e32 v214, 16, v100
	v_and_b32_e32 v215, 0xffff0000, v100
	v_lshlrev_b32_e32 v216, 16, v101
	v_and_b32_e32 v217, 0xffff0000, v101
	v_lshlrev_b32_e32 v218, 16, v102
	v_and_b32_e32 v219, 0xffff0000, v102
	v_lshlrev_b32_e32 v220, 16, v103
	v_and_b32_e32 v221, 0xffff0000, v103
	v_pk_fma_f32 v[2:3], v[104:105], v[222:223], v[174:175]
	v_pk_fma_f32 v[4:5], v[106:107], v[224:225], v[176:177]
	v_pk_fma_f32 v[6:7], v[108:109], v[226:227], v[178:179]
	v_pk_fma_f32 v[8:9], v[110:111], v[228:229], v[180:181]
	v_pk_fma_f32 v[10:11], v[112:113], v[230:231], v[182:183]
	v_pk_fma_f32 v[12:13], v[114:115], v[232:233], v[184:185]
	v_pk_fma_f32 v[14:15], v[116:117], v[234:235], v[186:187]
	v_pk_fma_f32 v[16:17], v[118:119], v[236:237], v[188:189]
	v_pk_fma_f32 v[2:3], v[120:121], v[190:191], v[2:3]
	v_pk_fma_f32 v[4:5], v[122:123], v[192:193], v[4:5]
	v_pk_fma_f32 v[6:7], v[124:125], v[194:195], v[6:7]
	v_pk_fma_f32 v[8:9], v[126:127], v[196:197], v[8:9]
	v_pk_fma_f32 v[10:11], v[128:129], v[198:199], v[10:11]
	v_pk_fma_f32 v[12:13], v[130:131], v[200:201], v[12:13]
	v_pk_fma_f32 v[14:15], v[132:133], v[202:203], v[14:15]
	v_pk_fma_f32 v[16:17], v[134:135], v[204:205], v[16:17]
	v_pk_fma_f32 v[2:3], v[136:137], v[206:207], v[2:3]
	v_pk_fma_f32 v[4:5], v[138:139], v[208:209], v[4:5]
	v_pk_fma_f32 v[6:7], v[140:141], v[210:211], v[6:7]
	v_pk_fma_f32 v[8:9], v[142:143], v[212:213], v[8:9]
	v_pk_fma_f32 v[10:11], v[144:145], v[214:215], v[10:11]
	v_pk_fma_f32 v[12:13], v[146:147], v[216:217], v[12:13]
	v_pk_fma_f32 v[14:15], v[148:149], v[218:219], v[14:15]
	v_pk_fma_f32 v[16:17], v[150:151], v[220:221], v[16:17]
	v_mul_f32_e32 v18, 0xbfb8aa3b, v2
	v_mul_f32_e32 v19, 0xbfb8aa3b, v3
	v_mul_f32_e32 v20, 0xbfb8aa3b, v4
	v_mul_f32_e32 v21, 0xbfb8aa3b, v5
	v_mul_f32_e32 v22, 0xbfb8aa3b, v6
	v_mul_f32_e32 v23, 0xbfb8aa3b, v7
	v_mul_f32_e32 v24, 0xbfb8aa3b, v8
	v_mul_f32_e32 v25, 0xbfb8aa3b, v9
	v_exp_f32_e32 v18, v18
	v_exp_f32_e32 v19, v19
	v_exp_f32_e32 v20, v20
	v_exp_f32_e32 v21, v21
	v_exp_f32_e32 v22, v22
	v_exp_f32_e32 v23, v23
	v_exp_f32_e32 v24, v24
	v_exp_f32_e32 v25, v25
	v_add_f32_e32 v18, 1.0, v18
	v_add_f32_e32 v19, 1.0, v19
	v_add_f32_e32 v20, 1.0, v20
	v_add_f32_e32 v21, 1.0, v21
	v_add_f32_e32 v22, 1.0, v22
	v_add_f32_e32 v23, 1.0, v23
	v_add_f32_e32 v24, 1.0, v24
	v_add_f32_e32 v25, 1.0, v25
	v_rcp_f32_e32 v18, v18
	v_rcp_f32_e32 v19, v19
	v_rcp_f32_e32 v20, v20
	v_rcp_f32_e32 v21, v21
	v_rcp_f32_e32 v22, v22
	v_rcp_f32_e32 v23, v23
	v_rcp_f32_e32 v24, v24
	v_rcp_f32_e32 v25, v25
	v_mul_f32_e32 v18, v2, v18
	v_mul_f32_e32 v19, v3, v19
	v_mul_f32_e32 v20, v4, v20
	v_mul_f32_e32 v21, v5, v21
	v_mul_f32_e32 v22, v6, v22
	v_mul_f32_e32 v23, v7, v23
	v_mul_f32_e32 v24, v8, v24
	v_mul_f32_e32 v25, v9, v25
	v_mul_f32_e32 v18, v10, v18
	v_mul_f32_e32 v19, v11, v19
	v_mul_f32_e32 v20, v12, v20
	v_mul_f32_e32 v21, v13, v21
	v_mul_f32_e32 v22, v14, v22
	v_mul_f32_e32 v23, v15, v23
	v_mul_f32_e32 v24, v16, v24
	v_mul_f32_e32 v25, v17, v25
	v_cvt_pk_bf16_f32 v26, v18, v19
	v_cvt_pk_bf16_f32 v27, v20, v21
	v_cvt_pk_bf16_f32 v28, v22, v23
	v_cvt_pk_bf16_f32 v29, v24, v25
	global_store_dwordx4 v[162:163], v[26:29], off sc1
	v_lshl_add_u64 v[162:163], v[162:163], 0, v[30:31]
	global_load_dwordx4 v[68:71], v[158:159], off nt
	global_load_dwordx4 v[72:75], v[160:161], off nt
	v_lshl_add_u64 v[158:159], v[158:159], 0, v[164:165]
	v_lshl_add_u64 v[160:161], v[160:161], 0, v[164:165]
	global_load_dwordx4 v[76:79], v[158:159], off nt
	global_load_dwordx4 v[80:83], v[160:161], off nt
	v_lshl_add_u64 v[158:159], v[158:159], 0, v[164:165]
	v_lshl_add_u64 v[160:161], v[160:161], 0, v[164:165]
	global_load_dwordx4 v[88:91], v[158:159], off nt
	global_load_dwordx4 v[92:95], v[160:161], off nt
	v_lshl_add_u64 v[158:159], v[158:159], 0, v[164:165]
	v_lshl_add_u64 v[160:161], v[160:161], 0, v[164:165]
	global_load_dwordx4 v[96:99], v[158:159], off nt
	global_load_dwordx4 v[100:103], v[160:161], off nt
	v_lshl_add_u64 v[158:159], v[158:159], 0, v[164:165]
	v_lshl_add_u64 v[160:161], v[160:161], 0, v[164:165]
	s_waitcnt vmcnt(12)
	v_lshlrev_b32_e32 v222, 16, v36
	v_and_b32_e32 v223, 0xffff0000, v36
	v_lshlrev_b32_e32 v224, 16, v37
	v_and_b32_e32 v225, 0xffff0000, v37
	v_lshlrev_b32_e32 v226, 16, v38
	v_and_b32_e32 v227, 0xffff0000, v38
	v_lshlrev_b32_e32 v228, 16, v39
	v_and_b32_e32 v229, 0xffff0000, v39
	v_lshlrev_b32_e32 v230, 16, v40
	v_and_b32_e32 v231, 0xffff0000, v40
	v_lshlrev_b32_e32 v232, 16, v41
	v_and_b32_e32 v233, 0xffff0000, v41
	v_lshlrev_b32_e32 v234, 16, v42
	v_and_b32_e32 v235, 0xffff0000, v42
	v_lshlrev_b32_e32 v236, 16, v43
	v_and_b32_e32 v237, 0xffff0000, v43
	v_pk_fma_f32 v[2:3], v[104:105], v[190:191], v[174:175]
	v_pk_fma_f32 v[4:5], v[106:107], v[192:193], v[176:177]
	v_pk_fma_f32 v[6:7], v[108:109], v[194:195], v[178:179]
	v_pk_fma_f32 v[8:9], v[110:111], v[196:197], v[180:181]
	v_pk_fma_f32 v[10:11], v[112:113], v[198:199], v[182:183]
	v_pk_fma_f32 v[12:13], v[114:115], v[200:201], v[184:185]
	v_pk_fma_f32 v[14:15], v[116:117], v[202:203], v[186:187]
	v_pk_fma_f32 v[16:17], v[118:119], v[204:205], v[188:189]
	v_pk_fma_f32 v[2:3], v[120:121], v[206:207], v[2:3]
	v_pk_fma_f32 v[4:5], v[122:123], v[208:209], v[4:5]
	v_pk_fma_f32 v[6:7], v[124:125], v[210:211], v[6:7]
	v_pk_fma_f32 v[8:9], v[126:127], v[212:213], v[8:9]
	v_pk_fma_f32 v[10:11], v[128:129], v[214:215], v[10:11]
	v_pk_fma_f32 v[12:13], v[130:131], v[216:217], v[12:13]
	v_pk_fma_f32 v[14:15], v[132:133], v[218:219], v[14:15]
	v_pk_fma_f32 v[16:17], v[134:135], v[220:221], v[16:17]
	v_pk_fma_f32 v[2:3], v[136:137], v[222:223], v[2:3]
	v_pk_fma_f32 v[4:5], v[138:139], v[224:225], v[4:5]
	v_pk_fma_f32 v[6:7], v[140:141], v[226:227], v[6:7]
	v_pk_fma_f32 v[8:9], v[142:143], v[228:229], v[8:9]
	v_pk_fma_f32 v[10:11], v[144:145], v[230:231], v[10:11]
	v_pk_fma_f32 v[12:13], v[146:147], v[232:233], v[12:13]
	v_pk_fma_f32 v[14:15], v[148:149], v[234:235], v[14:15]
	v_pk_fma_f32 v[16:17], v[150:151], v[236:237], v[16:17]
	v_mul_f32_e32 v18, 0xbfb8aa3b, v2
	v_mul_f32_e32 v19, 0xbfb8aa3b, v3
	v_mul_f32_e32 v20, 0xbfb8aa3b, v4
	v_mul_f32_e32 v21, 0xbfb8aa3b, v5
	v_mul_f32_e32 v22, 0xbfb8aa3b, v6
	v_mul_f32_e32 v23, 0xbfb8aa3b, v7
	v_mul_f32_e32 v24, 0xbfb8aa3b, v8
	v_mul_f32_e32 v25, 0xbfb8aa3b, v9
	v_exp_f32_e32 v18, v18
	v_exp_f32_e32 v19, v19
	v_exp_f32_e32 v20, v20
	v_exp_f32_e32 v21, v21
	v_exp_f32_e32 v22, v22
	v_exp_f32_e32 v23, v23
	v_exp_f32_e32 v24, v24
	v_exp_f32_e32 v25, v25
	v_add_f32_e32 v18, 1.0, v18
	v_add_f32_e32 v19, 1.0, v19
	v_add_f32_e32 v20, 1.0, v20
	v_add_f32_e32 v21, 1.0, v21
	v_add_f32_e32 v22, 1.0, v22
	v_add_f32_e32 v23, 1.0, v23
	v_add_f32_e32 v24, 1.0, v24
	v_add_f32_e32 v25, 1.0, v25
	v_rcp_f32_e32 v18, v18
	v_rcp_f32_e32 v19, v19
	v_rcp_f32_e32 v20, v20
	v_rcp_f32_e32 v21, v21
	v_rcp_f32_e32 v22, v22
	v_rcp_f32_e32 v23, v23
	v_rcp_f32_e32 v24, v24
	v_rcp_f32_e32 v25, v25
	v_mul_f32_e32 v18, v2, v18
	v_mul_f32_e32 v19, v3, v19
	v_mul_f32_e32 v20, v4, v20
	v_mul_f32_e32 v21, v5, v21
	v_mul_f32_e32 v22, v6, v22
	v_mul_f32_e32 v23, v7, v23
	v_mul_f32_e32 v24, v8, v24
	v_mul_f32_e32 v25, v9, v25
	v_mul_f32_e32 v18, v10, v18
	v_mul_f32_e32 v19, v11, v19
	v_mul_f32_e32 v20, v12, v20
	v_mul_f32_e32 v21, v13, v21
	v_mul_f32_e32 v22, v14, v22
	v_mul_f32_e32 v23, v15, v23
	v_mul_f32_e32 v24, v16, v24
	v_mul_f32_e32 v25, v17, v25
	v_cvt_pk_bf16_f32 v26, v18, v19
	v_cvt_pk_bf16_f32 v27, v20, v21
	v_cvt_pk_bf16_f32 v28, v22, v23
	v_cvt_pk_bf16_f32 v29, v24, v25
	global_store_dwordx4 v[162:163], v[26:29], off sc1
	v_lshl_add_u64 v[162:163], v[162:163], 0, v[30:31]
	v_lshlrev_b32_e32 v190, 16, v44
	v_and_b32_e32 v191, 0xffff0000, v44
	v_lshlrev_b32_e32 v192, 16, v45
	v_and_b32_e32 v193, 0xffff0000, v45
	v_lshlrev_b32_e32 v194, 16, v46
	v_and_b32_e32 v195, 0xffff0000, v46
	v_lshlrev_b32_e32 v196, 16, v47
	v_and_b32_e32 v197, 0xffff0000, v47
	v_lshlrev_b32_e32 v198, 16, v48
	v_and_b32_e32 v199, 0xffff0000, v48
	v_lshlrev_b32_e32 v200, 16, v49
	v_and_b32_e32 v201, 0xffff0000, v49
	v_lshlrev_b32_e32 v202, 16, v50
	v_and_b32_e32 v203, 0xffff0000, v50
	v_lshlrev_b32_e32 v204, 16, v51
	v_and_b32_e32 v205, 0xffff0000, v51
	v_pk_fma_f32 v[2:3], v[104:105], v[206:207], v[174:175]
	v_pk_fma_f32 v[4:5], v[106:107], v[208:209], v[176:177]
	v_pk_fma_f32 v[6:7], v[108:109], v[210:211], v[178:179]
	v_pk_fma_f32 v[8:9], v[110:111], v[212:213], v[180:181]
	v_pk_fma_f32 v[10:11], v[112:113], v[214:215], v[182:183]
	v_pk_fma_f32 v[12:13], v[114:115], v[216:217], v[184:185]
	v_pk_fma_f32 v[14:15], v[116:117], v[218:219], v[186:187]
	v_pk_fma_f32 v[16:17], v[118:119], v[220:221], v[188:189]
	v_pk_fma_f32 v[2:3], v[120:121], v[222:223], v[2:3]
	v_pk_fma_f32 v[4:5], v[122:123], v[224:225], v[4:5]
	v_pk_fma_f32 v[6:7], v[124:125], v[226:227], v[6:7]
	v_pk_fma_f32 v[8:9], v[126:127], v[228:229], v[8:9]
	v_pk_fma_f32 v[10:11], v[128:129], v[230:231], v[10:11]
	v_pk_fma_f32 v[12:13], v[130:131], v[232:233], v[12:13]
	v_pk_fma_f32 v[14:15], v[132:133], v[234:235], v[14:15]
	v_pk_fma_f32 v[16:17], v[134:135], v[236:237], v[16:17]
	v_pk_fma_f32 v[2:3], v[136:137], v[190:191], v[2:3]
	v_pk_fma_f32 v[4:5], v[138:139], v[192:193], v[4:5]
	v_pk_fma_f32 v[6:7], v[140:141], v[194:195], v[6:7]
	v_pk_fma_f32 v[8:9], v[142:143], v[196:197], v[8:9]
	v_pk_fma_f32 v[10:11], v[144:145], v[198:199], v[10:11]
	v_pk_fma_f32 v[12:13], v[146:147], v[200:201], v[12:13]
	v_pk_fma_f32 v[14:15], v[148:149], v[202:203], v[14:15]
	v_pk_fma_f32 v[16:17], v[150:151], v[204:205], v[16:17]
	v_mul_f32_e32 v18, 0xbfb8aa3b, v2
	v_mul_f32_e32 v19, 0xbfb8aa3b, v3
	v_mul_f32_e32 v20, 0xbfb8aa3b, v4
	v_mul_f32_e32 v21, 0xbfb8aa3b, v5
	v_mul_f32_e32 v22, 0xbfb8aa3b, v6
	v_mul_f32_e32 v23, 0xbfb8aa3b, v7
	v_mul_f32_e32 v24, 0xbfb8aa3b, v8
	v_mul_f32_e32 v25, 0xbfb8aa3b, v9
	v_exp_f32_e32 v18, v18
	v_exp_f32_e32 v19, v19
	v_exp_f32_e32 v20, v20
	v_exp_f32_e32 v21, v21
	v_exp_f32_e32 v22, v22
	v_exp_f32_e32 v23, v23
	v_exp_f32_e32 v24, v24
	v_exp_f32_e32 v25, v25
	v_add_f32_e32 v18, 1.0, v18
	v_add_f32_e32 v19, 1.0, v19
	v_add_f32_e32 v20, 1.0, v20
	v_add_f32_e32 v21, 1.0, v21
	v_add_f32_e32 v22, 1.0, v22
	v_add_f32_e32 v23, 1.0, v23
	v_add_f32_e32 v24, 1.0, v24
	v_add_f32_e32 v25, 1.0, v25
	v_rcp_f32_e32 v18, v18
	v_rcp_f32_e32 v19, v19
	v_rcp_f32_e32 v20, v20
	v_rcp_f32_e32 v21, v21
	v_rcp_f32_e32 v22, v22
	v_rcp_f32_e32 v23, v23
	v_rcp_f32_e32 v24, v24
	v_rcp_f32_e32 v25, v25
	v_mul_f32_e32 v18, v2, v18
	v_mul_f32_e32 v19, v3, v19
	v_mul_f32_e32 v20, v4, v20
	v_mul_f32_e32 v21, v5, v21
	v_mul_f32_e32 v22, v6, v22
	v_mul_f32_e32 v23, v7, v23
	v_mul_f32_e32 v24, v8, v24
	v_mul_f32_e32 v25, v9, v25
	v_mul_f32_e32 v18, v10, v18
	v_mul_f32_e32 v19, v11, v19
	v_mul_f32_e32 v20, v12, v20
	v_mul_f32_e32 v21, v13, v21
	v_mul_f32_e32 v22, v14, v22
	v_mul_f32_e32 v23, v15, v23
	v_mul_f32_e32 v24, v16, v24
	v_mul_f32_e32 v25, v17, v25
	v_cvt_pk_bf16_f32 v26, v18, v19
	v_cvt_pk_bf16_f32 v27, v20, v21
	v_cvt_pk_bf16_f32 v28, v22, v23
	v_cvt_pk_bf16_f32 v29, v24, v25
	global_store_dwordx4 v[162:163], v[26:29], off sc1
	v_lshl_add_u64 v[162:163], v[162:163], 0, v[30:31]
	v_lshlrev_b32_e32 v206, 16, v52
	v_and_b32_e32 v207, 0xffff0000, v52
	v_lshlrev_b32_e32 v208, 16, v53
	v_and_b32_e32 v209, 0xffff0000, v53
	v_lshlrev_b32_e32 v210, 16, v54
	v_and_b32_e32 v211, 0xffff0000, v54
	v_lshlrev_b32_e32 v212, 16, v55
	v_and_b32_e32 v213, 0xffff0000, v55
	v_lshlrev_b32_e32 v214, 16, v56
	v_and_b32_e32 v215, 0xffff0000, v56
	v_lshlrev_b32_e32 v216, 16, v57
	v_and_b32_e32 v217, 0xffff0000, v57
	v_lshlrev_b32_e32 v218, 16, v58
	v_and_b32_e32 v219, 0xffff0000, v58
	v_lshlrev_b32_e32 v220, 16, v59
	v_and_b32_e32 v221, 0xffff0000, v59
	v_pk_fma_f32 v[2:3], v[104:105], v[222:223], v[174:175]
	v_pk_fma_f32 v[4:5], v[106:107], v[224:225], v[176:177]
	v_pk_fma_f32 v[6:7], v[108:109], v[226:227], v[178:179]
	v_pk_fma_f32 v[8:9], v[110:111], v[228:229], v[180:181]
	v_pk_fma_f32 v[10:11], v[112:113], v[230:231], v[182:183]
	v_pk_fma_f32 v[12:13], v[114:115], v[232:233], v[184:185]
	v_pk_fma_f32 v[14:15], v[116:117], v[234:235], v[186:187]
	v_pk_fma_f32 v[16:17], v[118:119], v[236:237], v[188:189]
	v_pk_fma_f32 v[2:3], v[120:121], v[190:191], v[2:3]
	v_pk_fma_f32 v[4:5], v[122:123], v[192:193], v[4:5]
	v_pk_fma_f32 v[6:7], v[124:125], v[194:195], v[6:7]
	v_pk_fma_f32 v[8:9], v[126:127], v[196:197], v[8:9]
	v_pk_fma_f32 v[10:11], v[128:129], v[198:199], v[10:11]
	v_pk_fma_f32 v[12:13], v[130:131], v[200:201], v[12:13]
	v_pk_fma_f32 v[14:15], v[132:133], v[202:203], v[14:15]
	v_pk_fma_f32 v[16:17], v[134:135], v[204:205], v[16:17]
	v_pk_fma_f32 v[2:3], v[136:137], v[206:207], v[2:3]
	v_pk_fma_f32 v[4:5], v[138:139], v[208:209], v[4:5]
	v_pk_fma_f32 v[6:7], v[140:141], v[210:211], v[6:7]
	v_pk_fma_f32 v[8:9], v[142:143], v[212:213], v[8:9]
	v_pk_fma_f32 v[10:11], v[144:145], v[214:215], v[10:11]
	v_pk_fma_f32 v[12:13], v[146:147], v[216:217], v[12:13]
	v_pk_fma_f32 v[14:15], v[148:149], v[218:219], v[14:15]
	v_pk_fma_f32 v[16:17], v[150:151], v[220:221], v[16:17]
	v_mul_f32_e32 v18, 0xbfb8aa3b, v2
	v_mul_f32_e32 v19, 0xbfb8aa3b, v3
	v_mul_f32_e32 v20, 0xbfb8aa3b, v4
	v_mul_f32_e32 v21, 0xbfb8aa3b, v5
	v_mul_f32_e32 v22, 0xbfb8aa3b, v6
	v_mul_f32_e32 v23, 0xbfb8aa3b, v7
	v_mul_f32_e32 v24, 0xbfb8aa3b, v8
	v_mul_f32_e32 v25, 0xbfb8aa3b, v9
	v_exp_f32_e32 v18, v18
	v_exp_f32_e32 v19, v19
	v_exp_f32_e32 v20, v20
	v_exp_f32_e32 v21, v21
	v_exp_f32_e32 v22, v22
	v_exp_f32_e32 v23, v23
	v_exp_f32_e32 v24, v24
	v_exp_f32_e32 v25, v25
	v_add_f32_e32 v18, 1.0, v18
	v_add_f32_e32 v19, 1.0, v19
	v_add_f32_e32 v20, 1.0, v20
	v_add_f32_e32 v21, 1.0, v21
	v_add_f32_e32 v22, 1.0, v22
	v_add_f32_e32 v23, 1.0, v23
	v_add_f32_e32 v24, 1.0, v24
	v_add_f32_e32 v25, 1.0, v25
	v_rcp_f32_e32 v18, v18
	v_rcp_f32_e32 v19, v19
	v_rcp_f32_e32 v20, v20
	v_rcp_f32_e32 v21, v21
	v_rcp_f32_e32 v22, v22
	v_rcp_f32_e32 v23, v23
	v_rcp_f32_e32 v24, v24
	v_rcp_f32_e32 v25, v25
	v_mul_f32_e32 v18, v2, v18
	v_mul_f32_e32 v19, v3, v19
	v_mul_f32_e32 v20, v4, v20
	v_mul_f32_e32 v21, v5, v21
	v_mul_f32_e32 v22, v6, v22
	v_mul_f32_e32 v23, v7, v23
	v_mul_f32_e32 v24, v8, v24
	v_mul_f32_e32 v25, v9, v25
	v_mul_f32_e32 v18, v10, v18
	v_mul_f32_e32 v19, v11, v19
	v_mul_f32_e32 v20, v12, v20
	v_mul_f32_e32 v21, v13, v21
	v_mul_f32_e32 v22, v14, v22
	v_mul_f32_e32 v23, v15, v23
	v_mul_f32_e32 v24, v16, v24
	v_mul_f32_e32 v25, v17, v25
	v_cvt_pk_bf16_f32 v26, v18, v19
	v_cvt_pk_bf16_f32 v27, v20, v21
	v_cvt_pk_bf16_f32 v28, v22, v23
	v_cvt_pk_bf16_f32 v29, v24, v25
	global_store_dwordx4 v[162:163], v[26:29], off sc1
	v_lshl_add_u64 v[162:163], v[162:163], 0, v[30:31]
	v_lshlrev_b32_e32 v222, 16, v60
	v_and_b32_e32 v223, 0xffff0000, v60
	v_lshlrev_b32_e32 v224, 16, v61
	v_and_b32_e32 v225, 0xffff0000, v61
	v_lshlrev_b32_e32 v226, 16, v62
	v_and_b32_e32 v227, 0xffff0000, v62
	v_lshlrev_b32_e32 v228, 16, v63
	v_and_b32_e32 v229, 0xffff0000, v63
	v_lshlrev_b32_e32 v230, 16, v64
	v_and_b32_e32 v231, 0xffff0000, v64
	v_lshlrev_b32_e32 v232, 16, v65
	v_and_b32_e32 v233, 0xffff0000, v65
	v_lshlrev_b32_e32 v234, 16, v66
	v_and_b32_e32 v235, 0xffff0000, v66
	v_lshlrev_b32_e32 v236, 16, v67
	v_and_b32_e32 v237, 0xffff0000, v67
	v_pk_fma_f32 v[2:3], v[104:105], v[190:191], v[174:175]
	v_pk_fma_f32 v[4:5], v[106:107], v[192:193], v[176:177]
	v_pk_fma_f32 v[6:7], v[108:109], v[194:195], v[178:179]
	v_pk_fma_f32 v[8:9], v[110:111], v[196:197], v[180:181]
	v_pk_fma_f32 v[10:11], v[112:113], v[198:199], v[182:183]
	v_pk_fma_f32 v[12:13], v[114:115], v[200:201], v[184:185]
	v_pk_fma_f32 v[14:15], v[116:117], v[202:203], v[186:187]
	v_pk_fma_f32 v[16:17], v[118:119], v[204:205], v[188:189]
	v_pk_fma_f32 v[2:3], v[120:121], v[206:207], v[2:3]
	v_pk_fma_f32 v[4:5], v[122:123], v[208:209], v[4:5]
	v_pk_fma_f32 v[6:7], v[124:125], v[210:211], v[6:7]
	v_pk_fma_f32 v[8:9], v[126:127], v[212:213], v[8:9]
	v_pk_fma_f32 v[10:11], v[128:129], v[214:215], v[10:11]
	v_pk_fma_f32 v[12:13], v[130:131], v[216:217], v[12:13]
	v_pk_fma_f32 v[14:15], v[132:133], v[218:219], v[14:15]
	v_pk_fma_f32 v[16:17], v[134:135], v[220:221], v[16:17]
	v_pk_fma_f32 v[2:3], v[136:137], v[222:223], v[2:3]
	v_pk_fma_f32 v[4:5], v[138:139], v[224:225], v[4:5]
	v_pk_fma_f32 v[6:7], v[140:141], v[226:227], v[6:7]
	v_pk_fma_f32 v[8:9], v[142:143], v[228:229], v[8:9]
	v_pk_fma_f32 v[10:11], v[144:145], v[230:231], v[10:11]
	v_pk_fma_f32 v[12:13], v[146:147], v[232:233], v[12:13]
	v_pk_fma_f32 v[14:15], v[148:149], v[234:235], v[14:15]
	v_pk_fma_f32 v[16:17], v[150:151], v[236:237], v[16:17]
	v_mul_f32_e32 v18, 0xbfb8aa3b, v2
	v_mul_f32_e32 v19, 0xbfb8aa3b, v3
	v_mul_f32_e32 v20, 0xbfb8aa3b, v4
	v_mul_f32_e32 v21, 0xbfb8aa3b, v5
	v_mul_f32_e32 v22, 0xbfb8aa3b, v6
	v_mul_f32_e32 v23, 0xbfb8aa3b, v7
	v_mul_f32_e32 v24, 0xbfb8aa3b, v8
	v_mul_f32_e32 v25, 0xbfb8aa3b, v9
	v_exp_f32_e32 v18, v18
	v_exp_f32_e32 v19, v19
	v_exp_f32_e32 v20, v20
	v_exp_f32_e32 v21, v21
	v_exp_f32_e32 v22, v22
	v_exp_f32_e32 v23, v23
	v_exp_f32_e32 v24, v24
	v_exp_f32_e32 v25, v25
	v_add_f32_e32 v18, 1.0, v18
	v_add_f32_e32 v19, 1.0, v19
	v_add_f32_e32 v20, 1.0, v20
	v_add_f32_e32 v21, 1.0, v21
	v_add_f32_e32 v22, 1.0, v22
	v_add_f32_e32 v23, 1.0, v23
	v_add_f32_e32 v24, 1.0, v24
	v_add_f32_e32 v25, 1.0, v25
	v_rcp_f32_e32 v18, v18
	v_rcp_f32_e32 v19, v19
	v_rcp_f32_e32 v20, v20
	v_rcp_f32_e32 v21, v21
	v_rcp_f32_e32 v22, v22
	v_rcp_f32_e32 v23, v23
	v_rcp_f32_e32 v24, v24
	v_rcp_f32_e32 v25, v25
	v_mul_f32_e32 v18, v2, v18
	v_mul_f32_e32 v19, v3, v19
	v_mul_f32_e32 v20, v4, v20
	v_mul_f32_e32 v21, v5, v21
	v_mul_f32_e32 v22, v6, v22
	v_mul_f32_e32 v23, v7, v23
	v_mul_f32_e32 v24, v8, v24
	v_mul_f32_e32 v25, v9, v25
	v_mul_f32_e32 v18, v10, v18
	v_mul_f32_e32 v19, v11, v19
	v_mul_f32_e32 v20, v12, v20
	v_mul_f32_e32 v21, v13, v21
	v_mul_f32_e32 v22, v14, v22
	v_mul_f32_e32 v23, v15, v23
	v_mul_f32_e32 v24, v16, v24
	v_mul_f32_e32 v25, v17, v25
	v_cvt_pk_bf16_f32 v26, v18, v19
	v_cvt_pk_bf16_f32 v27, v20, v21
	v_cvt_pk_bf16_f32 v28, v22, v23
	v_cvt_pk_bf16_f32 v29, v24, v25
	global_store_dwordx4 v[162:163], v[26:29], off sc1
	v_lshl_add_u64 v[162:163], v[162:163], 0, v[30:31]
	s_waitcnt vmcnt(4)
	v_lshlrev_b32_e32 v190, 16, v68
	v_and_b32_e32 v191, 0xffff0000, v68
	v_lshlrev_b32_e32 v192, 16, v69
	v_and_b32_e32 v193, 0xffff0000, v69
	v_lshlrev_b32_e32 v194, 16, v70
	v_and_b32_e32 v195, 0xffff0000, v70
	v_lshlrev_b32_e32 v196, 16, v71
	v_and_b32_e32 v197, 0xffff0000, v71
	v_lshlrev_b32_e32 v198, 16, v72
	v_and_b32_e32 v199, 0xffff0000, v72
	v_lshlrev_b32_e32 v200, 16, v73
	v_and_b32_e32 v201, 0xffff0000, v73
	v_lshlrev_b32_e32 v202, 16, v74
	v_and_b32_e32 v203, 0xffff0000, v74
	v_lshlrev_b32_e32 v204, 16, v75
	v_and_b32_e32 v205, 0xffff0000, v75
	v_pk_fma_f32 v[2:3], v[104:105], v[206:207], v[174:175]
	v_pk_fma_f32 v[4:5], v[106:107], v[208:209], v[176:177]
	v_pk_fma_f32 v[6:7], v[108:109], v[210:211], v[178:179]
	v_pk_fma_f32 v[8:9], v[110:111], v[212:213], v[180:181]
	v_pk_fma_f32 v[10:11], v[112:113], v[214:215], v[182:183]
	v_pk_fma_f32 v[12:13], v[114:115], v[216:217], v[184:185]
	v_pk_fma_f32 v[14:15], v[116:117], v[218:219], v[186:187]
	v_pk_fma_f32 v[16:17], v[118:119], v[220:221], v[188:189]
	v_pk_fma_f32 v[2:3], v[120:121], v[222:223], v[2:3]
	v_pk_fma_f32 v[4:5], v[122:123], v[224:225], v[4:5]
	v_pk_fma_f32 v[6:7], v[124:125], v[226:227], v[6:7]
	v_pk_fma_f32 v[8:9], v[126:127], v[228:229], v[8:9]
	v_pk_fma_f32 v[10:11], v[128:129], v[230:231], v[10:11]
	v_pk_fma_f32 v[12:13], v[130:131], v[232:233], v[12:13]
	v_pk_fma_f32 v[14:15], v[132:133], v[234:235], v[14:15]
	v_pk_fma_f32 v[16:17], v[134:135], v[236:237], v[16:17]
	v_pk_fma_f32 v[2:3], v[136:137], v[190:191], v[2:3]
	v_pk_fma_f32 v[4:5], v[138:139], v[192:193], v[4:5]
	v_pk_fma_f32 v[6:7], v[140:141], v[194:195], v[6:7]
	v_pk_fma_f32 v[8:9], v[142:143], v[196:197], v[8:9]
	v_pk_fma_f32 v[10:11], v[144:145], v[198:199], v[10:11]
	v_pk_fma_f32 v[12:13], v[146:147], v[200:201], v[12:13]
	v_pk_fma_f32 v[14:15], v[148:149], v[202:203], v[14:15]
	v_pk_fma_f32 v[16:17], v[150:151], v[204:205], v[16:17]
	v_mul_f32_e32 v18, 0xbfb8aa3b, v2
	v_mul_f32_e32 v19, 0xbfb8aa3b, v3
	v_mul_f32_e32 v20, 0xbfb8aa3b, v4
	v_mul_f32_e32 v21, 0xbfb8aa3b, v5
	v_mul_f32_e32 v22, 0xbfb8aa3b, v6
	v_mul_f32_e32 v23, 0xbfb8aa3b, v7
	v_mul_f32_e32 v24, 0xbfb8aa3b, v8
	v_mul_f32_e32 v25, 0xbfb8aa3b, v9
	v_exp_f32_e32 v18, v18
	v_exp_f32_e32 v19, v19
	v_exp_f32_e32 v20, v20
	v_exp_f32_e32 v21, v21
	v_exp_f32_e32 v22, v22
	v_exp_f32_e32 v23, v23
	v_exp_f32_e32 v24, v24
	v_exp_f32_e32 v25, v25
	v_add_f32_e32 v18, 1.0, v18
	v_add_f32_e32 v19, 1.0, v19
	v_add_f32_e32 v20, 1.0, v20
	v_add_f32_e32 v21, 1.0, v21
	v_add_f32_e32 v22, 1.0, v22
	v_add_f32_e32 v23, 1.0, v23
	v_add_f32_e32 v24, 1.0, v24
	v_add_f32_e32 v25, 1.0, v25
	v_rcp_f32_e32 v18, v18
	v_rcp_f32_e32 v19, v19
	v_rcp_f32_e32 v20, v20
	v_rcp_f32_e32 v21, v21
	v_rcp_f32_e32 v22, v22
	v_rcp_f32_e32 v23, v23
	v_rcp_f32_e32 v24, v24
	v_rcp_f32_e32 v25, v25
	v_mul_f32_e32 v18, v2, v18
	v_mul_f32_e32 v19, v3, v19
	v_mul_f32_e32 v20, v4, v20
	v_mul_f32_e32 v21, v5, v21
	v_mul_f32_e32 v22, v6, v22
	v_mul_f32_e32 v23, v7, v23
	v_mul_f32_e32 v24, v8, v24
	v_mul_f32_e32 v25, v9, v25
	v_mul_f32_e32 v18, v10, v18
	v_mul_f32_e32 v19, v11, v19
	v_mul_f32_e32 v20, v12, v20
	v_mul_f32_e32 v21, v13, v21
	v_mul_f32_e32 v22, v14, v22
	v_mul_f32_e32 v23, v15, v23
	v_mul_f32_e32 v24, v16, v24
	v_mul_f32_e32 v25, v17, v25
	v_cvt_pk_bf16_f32 v26, v18, v19
	v_cvt_pk_bf16_f32 v27, v20, v21
	v_cvt_pk_bf16_f32 v28, v22, v23
	v_cvt_pk_bf16_f32 v29, v24, v25
	global_store_dwordx4 v[162:163], v[26:29], off sc1
	v_lshl_add_u64 v[162:163], v[162:163], 0, v[30:31]
	v_lshlrev_b32_e32 v206, 16, v76
	v_and_b32_e32 v207, 0xffff0000, v76
	v_lshlrev_b32_e32 v208, 16, v77
	v_and_b32_e32 v209, 0xffff0000, v77
	v_lshlrev_b32_e32 v210, 16, v78
	v_and_b32_e32 v211, 0xffff0000, v78
	v_lshlrev_b32_e32 v212, 16, v79
	v_and_b32_e32 v213, 0xffff0000, v79
	v_lshlrev_b32_e32 v214, 16, v80
	v_and_b32_e32 v215, 0xffff0000, v80
	v_lshlrev_b32_e32 v216, 16, v81
	v_and_b32_e32 v217, 0xffff0000, v81
	v_lshlrev_b32_e32 v218, 16, v82
	v_and_b32_e32 v219, 0xffff0000, v82
	v_lshlrev_b32_e32 v220, 16, v83
	v_and_b32_e32 v221, 0xffff0000, v83
	v_pk_fma_f32 v[2:3], v[104:105], v[222:223], v[174:175]
	v_pk_fma_f32 v[4:5], v[106:107], v[224:225], v[176:177]
	v_pk_fma_f32 v[6:7], v[108:109], v[226:227], v[178:179]
	v_pk_fma_f32 v[8:9], v[110:111], v[228:229], v[180:181]
	v_pk_fma_f32 v[10:11], v[112:113], v[230:231], v[182:183]
	v_pk_fma_f32 v[12:13], v[114:115], v[232:233], v[184:185]
	v_pk_fma_f32 v[14:15], v[116:117], v[234:235], v[186:187]
	v_pk_fma_f32 v[16:17], v[118:119], v[236:237], v[188:189]
	v_pk_fma_f32 v[2:3], v[120:121], v[190:191], v[2:3]
	v_pk_fma_f32 v[4:5], v[122:123], v[192:193], v[4:5]
	v_pk_fma_f32 v[6:7], v[124:125], v[194:195], v[6:7]
	v_pk_fma_f32 v[8:9], v[126:127], v[196:197], v[8:9]
	v_pk_fma_f32 v[10:11], v[128:129], v[198:199], v[10:11]
	v_pk_fma_f32 v[12:13], v[130:131], v[200:201], v[12:13]
	v_pk_fma_f32 v[14:15], v[132:133], v[202:203], v[14:15]
	v_pk_fma_f32 v[16:17], v[134:135], v[204:205], v[16:17]
	v_pk_fma_f32 v[2:3], v[136:137], v[206:207], v[2:3]
	v_pk_fma_f32 v[4:5], v[138:139], v[208:209], v[4:5]
	v_pk_fma_f32 v[6:7], v[140:141], v[210:211], v[6:7]
	v_pk_fma_f32 v[8:9], v[142:143], v[212:213], v[8:9]
	v_pk_fma_f32 v[10:11], v[144:145], v[214:215], v[10:11]
	v_pk_fma_f32 v[12:13], v[146:147], v[216:217], v[12:13]
	v_pk_fma_f32 v[14:15], v[148:149], v[218:219], v[14:15]
	v_pk_fma_f32 v[16:17], v[150:151], v[220:221], v[16:17]
	v_mul_f32_e32 v18, 0xbfb8aa3b, v2
	v_mul_f32_e32 v19, 0xbfb8aa3b, v3
	v_mul_f32_e32 v20, 0xbfb8aa3b, v4
	v_mul_f32_e32 v21, 0xbfb8aa3b, v5
	v_mul_f32_e32 v22, 0xbfb8aa3b, v6
	v_mul_f32_e32 v23, 0xbfb8aa3b, v7
	v_mul_f32_e32 v24, 0xbfb8aa3b, v8
	v_mul_f32_e32 v25, 0xbfb8aa3b, v9
	v_exp_f32_e32 v18, v18
	v_exp_f32_e32 v19, v19
	v_exp_f32_e32 v20, v20
	v_exp_f32_e32 v21, v21
	v_exp_f32_e32 v22, v22
	v_exp_f32_e32 v23, v23
	v_exp_f32_e32 v24, v24
	v_exp_f32_e32 v25, v25
	v_add_f32_e32 v18, 1.0, v18
	v_add_f32_e32 v19, 1.0, v19
	v_add_f32_e32 v20, 1.0, v20
	v_add_f32_e32 v21, 1.0, v21
	v_add_f32_e32 v22, 1.0, v22
	v_add_f32_e32 v23, 1.0, v23
	v_add_f32_e32 v24, 1.0, v24
	v_add_f32_e32 v25, 1.0, v25
	v_rcp_f32_e32 v18, v18
	v_rcp_f32_e32 v19, v19
	v_rcp_f32_e32 v20, v20
	v_rcp_f32_e32 v21, v21
	v_rcp_f32_e32 v22, v22
	v_rcp_f32_e32 v23, v23
	v_rcp_f32_e32 v24, v24
	v_rcp_f32_e32 v25, v25
	v_mul_f32_e32 v18, v2, v18
	v_mul_f32_e32 v19, v3, v19
	v_mul_f32_e32 v20, v4, v20
	v_mul_f32_e32 v21, v5, v21
	v_mul_f32_e32 v22, v6, v22
	v_mul_f32_e32 v23, v7, v23
	v_mul_f32_e32 v24, v8, v24
	v_mul_f32_e32 v25, v9, v25
	v_mul_f32_e32 v18, v10, v18
	v_mul_f32_e32 v19, v11, v19
	v_mul_f32_e32 v20, v12, v20
	v_mul_f32_e32 v21, v13, v21
	v_mul_f32_e32 v22, v14, v22
	v_mul_f32_e32 v23, v15, v23
	v_mul_f32_e32 v24, v16, v24
	v_mul_f32_e32 v25, v17, v25
	v_cvt_pk_bf16_f32 v26, v18, v19
	v_cvt_pk_bf16_f32 v27, v20, v21
	v_cvt_pk_bf16_f32 v28, v22, v23
	v_cvt_pk_bf16_f32 v29, v24, v25
	global_store_dwordx4 v[162:163], v[26:29], off sc1
	v_lshl_add_u64 v[162:163], v[162:163], 0, v[30:31]
	v_lshlrev_b32_e32 v222, 16, v88
	v_and_b32_e32 v223, 0xffff0000, v88
	v_lshlrev_b32_e32 v224, 16, v89
	v_and_b32_e32 v225, 0xffff0000, v89
	v_lshlrev_b32_e32 v226, 16, v90
	v_and_b32_e32 v227, 0xffff0000, v90
	v_lshlrev_b32_e32 v228, 16, v91
	v_and_b32_e32 v229, 0xffff0000, v91
	v_lshlrev_b32_e32 v230, 16, v92
	v_and_b32_e32 v231, 0xffff0000, v92
	v_lshlrev_b32_e32 v232, 16, v93
	v_and_b32_e32 v233, 0xffff0000, v93
	v_lshlrev_b32_e32 v234, 16, v94
	v_and_b32_e32 v235, 0xffff0000, v94
	v_lshlrev_b32_e32 v236, 16, v95
	v_and_b32_e32 v237, 0xffff0000, v95
	v_pk_fma_f32 v[2:3], v[104:105], v[190:191], v[174:175]
	v_pk_fma_f32 v[4:5], v[106:107], v[192:193], v[176:177]
	v_pk_fma_f32 v[6:7], v[108:109], v[194:195], v[178:179]
	v_pk_fma_f32 v[8:9], v[110:111], v[196:197], v[180:181]
	v_pk_fma_f32 v[10:11], v[112:113], v[198:199], v[182:183]
	v_pk_fma_f32 v[12:13], v[114:115], v[200:201], v[184:185]
	v_pk_fma_f32 v[14:15], v[116:117], v[202:203], v[186:187]
	v_pk_fma_f32 v[16:17], v[118:119], v[204:205], v[188:189]
	v_pk_fma_f32 v[2:3], v[120:121], v[206:207], v[2:3]
	v_pk_fma_f32 v[4:5], v[122:123], v[208:209], v[4:5]
	v_pk_fma_f32 v[6:7], v[124:125], v[210:211], v[6:7]
	v_pk_fma_f32 v[8:9], v[126:127], v[212:213], v[8:9]
	v_pk_fma_f32 v[10:11], v[128:129], v[214:215], v[10:11]
	v_pk_fma_f32 v[12:13], v[130:131], v[216:217], v[12:13]
	v_pk_fma_f32 v[14:15], v[132:133], v[218:219], v[14:15]
	v_pk_fma_f32 v[16:17], v[134:135], v[220:221], v[16:17]
	v_pk_fma_f32 v[2:3], v[136:137], v[222:223], v[2:3]
	v_pk_fma_f32 v[4:5], v[138:139], v[224:225], v[4:5]
	v_pk_fma_f32 v[6:7], v[140:141], v[226:227], v[6:7]
	v_pk_fma_f32 v[8:9], v[142:143], v[228:229], v[8:9]
	v_pk_fma_f32 v[10:11], v[144:145], v[230:231], v[10:11]
	v_pk_fma_f32 v[12:13], v[146:147], v[232:233], v[12:13]
	v_pk_fma_f32 v[14:15], v[148:149], v[234:235], v[14:15]
	v_pk_fma_f32 v[16:17], v[150:151], v[236:237], v[16:17]
	v_mul_f32_e32 v18, 0xbfb8aa3b, v2
	v_mul_f32_e32 v19, 0xbfb8aa3b, v3
	v_mul_f32_e32 v20, 0xbfb8aa3b, v4
	v_mul_f32_e32 v21, 0xbfb8aa3b, v5
	v_mul_f32_e32 v22, 0xbfb8aa3b, v6
	v_mul_f32_e32 v23, 0xbfb8aa3b, v7
	v_mul_f32_e32 v24, 0xbfb8aa3b, v8
	v_mul_f32_e32 v25, 0xbfb8aa3b, v9
	v_exp_f32_e32 v18, v18
	v_exp_f32_e32 v19, v19
	v_exp_f32_e32 v20, v20
	v_exp_f32_e32 v21, v21
	v_exp_f32_e32 v22, v22
	v_exp_f32_e32 v23, v23
	v_exp_f32_e32 v24, v24
	v_exp_f32_e32 v25, v25
	v_add_f32_e32 v18, 1.0, v18
	v_add_f32_e32 v19, 1.0, v19
	v_add_f32_e32 v20, 1.0, v20
	v_add_f32_e32 v21, 1.0, v21
	v_add_f32_e32 v22, 1.0, v22
	v_add_f32_e32 v23, 1.0, v23
	v_add_f32_e32 v24, 1.0, v24
	v_add_f32_e32 v25, 1.0, v25
	v_rcp_f32_e32 v18, v18
	v_rcp_f32_e32 v19, v19
	v_rcp_f32_e32 v20, v20
	v_rcp_f32_e32 v21, v21
	v_rcp_f32_e32 v22, v22
	v_rcp_f32_e32 v23, v23
	v_rcp_f32_e32 v24, v24
	v_rcp_f32_e32 v25, v25
	v_mul_f32_e32 v18, v2, v18
	v_mul_f32_e32 v19, v3, v19
	v_mul_f32_e32 v20, v4, v20
	v_mul_f32_e32 v21, v5, v21
	v_mul_f32_e32 v22, v6, v22
	v_mul_f32_e32 v23, v7, v23
	v_mul_f32_e32 v24, v8, v24
	v_mul_f32_e32 v25, v9, v25
	v_mul_f32_e32 v18, v10, v18
	v_mul_f32_e32 v19, v11, v19
	v_mul_f32_e32 v20, v12, v20
	v_mul_f32_e32 v21, v13, v21
	v_mul_f32_e32 v22, v14, v22
	v_mul_f32_e32 v23, v15, v23
	v_mul_f32_e32 v24, v16, v24
	v_mul_f32_e32 v25, v17, v25
	v_cvt_pk_bf16_f32 v26, v18, v19
	v_cvt_pk_bf16_f32 v27, v20, v21
	v_cvt_pk_bf16_f32 v28, v22, v23
	v_cvt_pk_bf16_f32 v29, v24, v25
	global_store_dwordx4 v[162:163], v[26:29], off sc1
	v_lshl_add_u64 v[162:163], v[162:163], 0, v[30:31]
	v_lshlrev_b32_e32 v190, 16, v96
	v_and_b32_e32 v191, 0xffff0000, v96
	v_lshlrev_b32_e32 v192, 16, v97
	v_and_b32_e32 v193, 0xffff0000, v97
	v_lshlrev_b32_e32 v194, 16, v98
	v_and_b32_e32 v195, 0xffff0000, v98
	v_lshlrev_b32_e32 v196, 16, v99
	v_and_b32_e32 v197, 0xffff0000, v99
	v_lshlrev_b32_e32 v198, 16, v100
	v_and_b32_e32 v199, 0xffff0000, v100
	v_lshlrev_b32_e32 v200, 16, v101
	v_and_b32_e32 v201, 0xffff0000, v101
	v_lshlrev_b32_e32 v202, 16, v102
	v_and_b32_e32 v203, 0xffff0000, v102
	v_lshlrev_b32_e32 v204, 16, v103
	v_and_b32_e32 v205, 0xffff0000, v103
	v_pk_fma_f32 v[2:3], v[104:105], v[206:207], v[174:175]
	v_pk_fma_f32 v[4:5], v[106:107], v[208:209], v[176:177]
	v_pk_fma_f32 v[6:7], v[108:109], v[210:211], v[178:179]
	v_pk_fma_f32 v[8:9], v[110:111], v[212:213], v[180:181]
	v_pk_fma_f32 v[10:11], v[112:113], v[214:215], v[182:183]
	v_pk_fma_f32 v[12:13], v[114:115], v[216:217], v[184:185]
	v_pk_fma_f32 v[14:15], v[116:117], v[218:219], v[186:187]
	v_pk_fma_f32 v[16:17], v[118:119], v[220:221], v[188:189]
	v_pk_fma_f32 v[2:3], v[120:121], v[222:223], v[2:3]
	v_pk_fma_f32 v[4:5], v[122:123], v[224:225], v[4:5]
	v_pk_fma_f32 v[6:7], v[124:125], v[226:227], v[6:7]
	v_pk_fma_f32 v[8:9], v[126:127], v[228:229], v[8:9]
	v_pk_fma_f32 v[10:11], v[128:129], v[230:231], v[10:11]
	v_pk_fma_f32 v[12:13], v[130:131], v[232:233], v[12:13]
	v_pk_fma_f32 v[14:15], v[132:133], v[234:235], v[14:15]
	v_pk_fma_f32 v[16:17], v[134:135], v[236:237], v[16:17]
	v_pk_fma_f32 v[2:3], v[136:137], v[190:191], v[2:3]
	v_pk_fma_f32 v[4:5], v[138:139], v[192:193], v[4:5]
	v_pk_fma_f32 v[6:7], v[140:141], v[194:195], v[6:7]
	v_pk_fma_f32 v[8:9], v[142:143], v[196:197], v[8:9]
	v_pk_fma_f32 v[10:11], v[144:145], v[198:199], v[10:11]
	v_pk_fma_f32 v[12:13], v[146:147], v[200:201], v[12:13]
	v_pk_fma_f32 v[14:15], v[148:149], v[202:203], v[14:15]
	v_pk_fma_f32 v[16:17], v[150:151], v[204:205], v[16:17]
	v_mul_f32_e32 v18, 0xbfb8aa3b, v2
	v_mul_f32_e32 v19, 0xbfb8aa3b, v3
	v_mul_f32_e32 v20, 0xbfb8aa3b, v4
	v_mul_f32_e32 v21, 0xbfb8aa3b, v5
	v_mul_f32_e32 v22, 0xbfb8aa3b, v6
	v_mul_f32_e32 v23, 0xbfb8aa3b, v7
	v_mul_f32_e32 v24, 0xbfb8aa3b, v8
	v_mul_f32_e32 v25, 0xbfb8aa3b, v9
	v_exp_f32_e32 v18, v18
	v_exp_f32_e32 v19, v19
	v_exp_f32_e32 v20, v20
	v_exp_f32_e32 v21, v21
	v_exp_f32_e32 v22, v22
	v_exp_f32_e32 v23, v23
	v_exp_f32_e32 v24, v24
	v_exp_f32_e32 v25, v25
	v_add_f32_e32 v18, 1.0, v18
	v_add_f32_e32 v19, 1.0, v19
	v_add_f32_e32 v20, 1.0, v20
	v_add_f32_e32 v21, 1.0, v21
	v_add_f32_e32 v22, 1.0, v22
	v_add_f32_e32 v23, 1.0, v23
	v_add_f32_e32 v24, 1.0, v24
	v_add_f32_e32 v25, 1.0, v25
	v_rcp_f32_e32 v18, v18
	v_rcp_f32_e32 v19, v19
	v_rcp_f32_e32 v20, v20
	v_rcp_f32_e32 v21, v21
	v_rcp_f32_e32 v22, v22
	v_rcp_f32_e32 v23, v23
	v_rcp_f32_e32 v24, v24
	v_rcp_f32_e32 v25, v25
	v_mul_f32_e32 v18, v2, v18
	v_mul_f32_e32 v19, v3, v19
	v_mul_f32_e32 v20, v4, v20
	v_mul_f32_e32 v21, v5, v21
	v_mul_f32_e32 v22, v6, v22
	v_mul_f32_e32 v23, v7, v23
	v_mul_f32_e32 v24, v8, v24
	v_mul_f32_e32 v25, v9, v25
	v_mul_f32_e32 v18, v10, v18
	v_mul_f32_e32 v19, v11, v19
	v_mul_f32_e32 v20, v12, v20
	v_mul_f32_e32 v21, v13, v21
	v_mul_f32_e32 v22, v14, v22
	v_mul_f32_e32 v23, v15, v23
	v_mul_f32_e32 v24, v16, v24
	v_mul_f32_e32 v25, v17, v25
	v_cvt_pk_bf16_f32 v26, v18, v19
	v_cvt_pk_bf16_f32 v27, v20, v21
	v_cvt_pk_bf16_f32 v28, v22, v23
	v_cvt_pk_bf16_f32 v29, v24, v25
	global_store_dwordx4 v[162:163], v[26:29], off sc1
	v_lshl_add_u64 v[162:163], v[162:163], 0, v[30:31]
	s_branch .LBB0_2504
.Lconv_orig:
	v_readlane_b32 s36, v254, 50
	v_readlane_b32 s48, v254, 62
	v_readlane_b32 s49, v254, 63
	v_readlane_b32 s50, v255, 0
	v_readlane_b32 s51, v255, 1
	s_mov_b64 s[20:21], s[48:49]
	s_add_u32 s14, s20, 0xb000
	s_addc_u32 s15, s21, 0
	v_readlane_b32 s37, v254, 51
	v_readlane_b32 s38, v254, 52
	v_readlane_b32 s39, v254, 53
	v_readlane_b32 s40, v254, 54
	v_readlane_b32 s41, v254, 55
	v_readlane_b32 s42, v254, 56
	v_readlane_b32 s43, v254, 57
	v_readlane_b32 s44, v254, 58
	s_mov_b64 s[22:23], s[50:51]
	s_add_u32 s18, s20, 0x16000
	s_mov_b64 s[12:13], 0xb000
	s_mov_b64 s[16:17], 0x16000
	s_addc_u32 s19, s21, 0
	s_mov_b64 s[20:21], 0
	s_mov_b32 s3, 0xba2e8ba3
	s_mov_b32 s4, 0x2c000
	v_mov_b32_e32 v89, 0xffffd400
	s_mov_b64 s[22:23], 0x5800
	s_mov_b32 s5, 0x58000
	s_mov_b32 s30, 0xd322000
	s_mov_b32 s33, 0xd324000
	s_mov_b32 s36, 0x190e2000
	s_mov_b32 s37, 0xd327000
	s_mov_b32 s38, 0xd32a000
	s_mov_b32 s39, 0x190e4000
	s_mov_b32 s40, 0xd32d000
	s_mov_b32 s41, 0xd32f000
	s_mov_b32 s42, 0x190e7000
	s_mov_b32 s43, 0xd332000
	s_mov_b32 s44, 0xd335000
	s_mov_b64 s[24:25], 0x57fff
	v_mov_b32_e32 v88, v87
	v_mov_b64_e32 v[90:91], v[84:85]
	v_readlane_b32 s45, v254, 59
	v_readlane_b32 s46, v254, 60
	v_readlane_b32 s47, v254, 61
